# K-loop load segments reordered: LDS-DMA loads and their scalar set-up issued before the ds_read_b128 fragment reads
# speedup vs baseline: 1.0242x; 1.0042x over previous
; #define PG8_STAGE(bufoff, gbase, voff) do { _Pragma("unroll") for (int _i = 0; _i < 2; ++_i) \
;         __builtin_amdgcn_global_load_lds((const unsigned*)((const char*)(gbase) + (voff)[_i]), (LAS unsigned*)(lds + (bufoff) + ldsw + _i * 8192), 16, 0, 0); } while (0)
; #define PG8_LDA(dst, b, h) do { _Pragma("unroll") for (int m = 0; m < 4; ++m) _Pragma("unroll") for (int k = 0; k < 2; ++k) dst[m][k] = *(const LAS bf16x8*)(lds + PG8_SA(b, h) + aoff + m * 2048 + k * 1024); } while (0)
; #define PG8_LDB(dst, b, h) do { _Pragma("unroll") for (int n = 0; n < 2; ++n) _Pragma("unroll") for (int k = 0; k < 2; ++k) dst[n][k] = *(const LAS bf16x8*)(lds + PG8_SB(b, h) + boff + n * 2048 + k * 1024); } while (0)
; #define PG8_MMA(ai, bj, At, Bt) do { __builtin_amdgcn_s_setprio(1); _Pragma("unroll") for (int m = 0; m < 4; ++m) _Pragma("unroll") for (int n = 0; n < 2; ++n) _Pragma("unroll") for (int k = 0; k < 2; ++k) \
;         acc[ai][bj][m][n] = __builtin_amdgcn_mfma_f32_16x16x32_bf16(Bt[n][k], At[m][k], acc[ai][bj][m][n], 0, 0, 0); __builtin_amdgcn_s_setprio(0); } while (0)
; #define PG8_WAIT_V(n) asm volatile("s_waitcnt vmcnt(" #n ")" ::: "memory")
; template <class Epi, class Sched>
; __device__ __forceinline__ void gemm_phase(LAS unsigned char* lds, const Gemm g, const Sched& S, const Epi& E) {
;     ...
;         const char* nA = has_next ? (const char*)g.A + (size_t)nxt.pm * tstepA + (size_t)nxt.pn * g.a_pn_off * 2 : cA; const char* nB = has_next ? (const char*)g.Bt + (size_t)nxt.pn * tstepB : cB;
;         for (int t = 0; t < nt; t += 2) {
;             const bool last = (t == nt - 2);
;             const char* a1 = cA + (size_t)(t + 1) * kstep;
;             const char* a2 = last ? nA : cA + (size_t)(t + 2) * kstep; const char* b2 = last ? nB : cB + (size_t)(t + 2) * kstep;
;             const char* a3 = a2 + kstep; const char* b3 = b2 + kstep;
;             PG8_LDB(B0, 0, 0); PG8_LDB(B1, 0, 1); PG8_SCHED; PG8_LDA(At, 0, 0); PG8_STAGE(PG8_SA(1, 1), a1 + hstepA, voffA);
;             PG8_WAIT_V(8); PG8_WAIT_L(0); PG8_BAR; PG8_MMA(0, 0, At, B0); PG8_MMA(0, 1, At, B1); PG8_BAR; PG8_SCHED;
;             PG8_LDA(At, 0, 1); PG8_STAGE(PG8_SB(0, 0), b2, voffB); PG8_STAGE(PG8_SB(0, 1), b2 + hstepB, voffB); PG8_STAGE(PG8_SA(0, 0), a2, voffA);
;             PG8_WAIT_V(8); PG8_WAIT_L(0); PG8_BAR; PG8_MMA(1, 0, At, B0); PG8_MMA(1, 1, At, B1); PG8_BAR; PG8_SCHED;
.LBB0_231:
	s_ashr_i32 s83, s82, 31
	s_lshl_b64 s[36:37], s[82:83], 19
	s_add_u32 s84, s4, s36
	s_addc_u32 s85, s5, s37
	s_and_b64 s[36:37], s[70:71], exec
	s_cselect_b32 s43, s85, s19
	s_cselect_b32 s48, s84, s18
	s_ashr_i32 s81, s80, 31
	s_lshl_b64 s[36:37], s[80:81], 19
	v_readlane_b32 s12, v248, 5
	s_add_u32 s36, s12, s36
	v_readlane_b32 s12, v248, 6
	s_addc_u32 s37, s12, s37
	s_and_b64 s[86:87], s[70:71], exec
	s_cselect_b32 s49, s37, s21
	s_cselect_b32 s53, s36, s20
	s_add_u32 s18, s18, 0x40080
	s_addc_u32 s19, s19, 0
	s_add_u32 s54, s20, 0x100
	s_addc_u32 s81, s21, 0
	s_mov_b32 s83, -2
	s_add_u32 s20, s18, 0xfffc0080
	s_addc_u32 s21, s19, -1
	s_add_i32 s88, 0, 0x10000
	s_cmp_eq_u32 s83, 12
	s_cselect_b32 s21, s43, s21
	s_cselect_b32 s20, s48, s20
	s_cselect_b32 s87, s49, s81
	s_cselect_b32 s86, s53, s54
	s_add_i32 s90, 0, 0x14000
	s_add_u32 s100, s20, 0x80
	s_addc_u32 s101, s21, 0
	s_add_i32 m0, s9, 0xc000
	s_nop 0
	global_load_lds_dwordx4 v170, s[18:19]
	s_add_i32 m0, s9, 0xe000
	s_nop 0
	global_load_lds_dwordx4 v190, s[18:19]
	ds_read_b128 v[130:133], v246
	ds_read_b128 v[134:137], v246 offset:1024
	ds_read_b128 v[138:141], v246 offset:2048
	ds_read_b128 v[142:145], v246 offset:3072
	ds_read_b128 v[146:149], v246 offset:16384
	ds_read_b128 v[150:153], v246 offset:17408
	ds_read_b128 v[154:157], v246 offset:18432
	ds_read_b128 v[158:161], v246 offset:19456
	ds_read_b128 v[162:165], v222
	ds_read_b128 v[166:169], v222 offset:1024
	ds_read_b128 v[194:197], v222 offset:2048
	ds_read_b128 v[198:201], v222 offset:3072
	ds_read_b128 v[202:205], v222 offset:4096
	ds_read_b128 v[224:227], v222 offset:5120
	ds_read_b128 v[228:231], v222 offset:6144
	ds_read_b128 v[232:235], v222 offset:7168
	s_waitcnt vmcnt(8)
	s_waitcnt lgkmcnt(0)
	s_barrier
	s_waitcnt lgkmcnt(0)
	v_mfma_f32_16x16x32_bf16 v[126:129], v[130:133], v[162:165], 0
	v_mfma_f32_16x16x32_bf16 v[118:121], v[138:141], v[162:165], 0
	v_mfma_f32_16x16x32_bf16 v[110:113], v[130:133], v[194:197], 0
	v_mfma_f32_16x16x32_bf16 v[102:105], v[138:141], v[194:197], 0
	v_mfma_f32_16x16x32_bf16 v[94:97], v[130:133], v[202:205], 0
	v_mfma_f32_16x16x32_bf16 v[86:89], v[138:141], v[202:205], 0
	v_mfma_f32_16x16x32_bf16 v[78:81], v[130:133], v[228:231], 0
	v_mfma_f32_16x16x32_bf16 v[70:73], v[138:141], v[228:231], 0
	v_mfma_f32_16x16x32_bf16 v[126:129], v[134:137], v[166:169], v[126:129]
	v_mfma_f32_16x16x32_bf16 v[118:121], v[142:145], v[166:169], v[118:121]
	v_mfma_f32_16x16x32_bf16 v[110:113], v[134:137], v[198:201], v[110:113]
	v_mfma_f32_16x16x32_bf16 v[102:105], v[142:145], v[198:201], v[102:105]
	v_mfma_f32_16x16x32_bf16 v[94:97], v[134:137], v[224:227], v[94:97]
	v_mfma_f32_16x16x32_bf16 v[86:89], v[142:145], v[224:227], v[86:89]
	v_mfma_f32_16x16x32_bf16 v[78:81], v[134:137], v[232:235], v[78:81]
	v_mfma_f32_16x16x32_bf16 v[70:73], v[142:145], v[232:235], v[70:73]
	v_mfma_f32_16x16x32_bf16 v[122:125], v[146:149], v[162:165], 0
	v_mfma_f32_16x16x32_bf16 v[114:117], v[154:157], v[162:165], 0
	v_mfma_f32_16x16x32_bf16 v[106:109], v[146:149], v[194:197], 0
	v_mfma_f32_16x16x32_bf16 v[98:101], v[154:157], v[194:197], 0
	v_mfma_f32_16x16x32_bf16 v[90:93], v[146:149], v[202:205], 0
	v_mfma_f32_16x16x32_bf16 v[82:85], v[154:157], v[202:205], 0
	v_mfma_f32_16x16x32_bf16 v[74:77], v[146:149], v[228:231], 0
	v_mfma_f32_16x16x32_bf16 v[66:69], v[154:157], v[228:231], 0
	v_mfma_f32_16x16x32_bf16 v[122:125], v[150:153], v[166:169], v[122:125]
	v_mfma_f32_16x16x32_bf16 v[114:117], v[158:161], v[166:169], v[114:117]
	v_mfma_f32_16x16x32_bf16 v[106:109], v[150:153], v[198:201], v[106:109]
	v_mfma_f32_16x16x32_bf16 v[98:101], v[158:161], v[198:201], v[98:101]
	v_mfma_f32_16x16x32_bf16 v[90:93], v[150:153], v[224:227], v[90:93]
	v_mfma_f32_16x16x32_bf16 v[82:85], v[158:161], v[224:227], v[82:85]
	v_mfma_f32_16x16x32_bf16 v[74:77], v[150:153], v[232:235], v[74:77]
	v_mfma_f32_16x16x32_bf16 v[66:69], v[158:161], v[232:235], v[66:69]
	s_barrier
	s_add_i32 s88, s88, s8
	s_mov_b32 m0, s88
	s_nop 0
	global_load_lds_dwordx4 v172, s[86:87]
	s_add_i32 m0, s88, 0x2000
	s_add_u32 s88, s86, 0x40000
	s_addc_u32 s89, s87, 0
	s_add_i32 s90, s90, s8
	global_load_lds_dwordx4 v192, s[86:87]
	s_mov_b32 m0, s90
	s_nop 0
	global_load_lds_dwordx4 v172, s[88:89]
	s_add_i32 m0, s90, 0x2000
	s_nop 0
	global_load_lds_dwordx4 v192, s[88:89]
	s_mov_b32 m0, s9
	s_nop 0
	global_load_lds_dwordx4 v170, s[20:21]
	s_mov_b32 m0, s28
	s_nop 0
	global_load_lds_dwordx4 v190, s[20:21]
	ds_read_b128 v[162:165], v222 offset:16384
	ds_read_b128 v[166:169], v222 offset:17408
	ds_read_b128 v[194:197], v222 offset:18432
	ds_read_b128 v[198:201], v222 offset:19456
	ds_read_b128 v[202:205], v222 offset:20480
	ds_read_b128 v[224:227], v222 offset:21504
	ds_read_b128 v[228:231], v222 offset:22528
	ds_read_b128 v[232:235], v222 offset:23552
	s_waitcnt vmcnt(8)
	s_waitcnt lgkmcnt(0)
	s_barrier
; #define PG8_STAGE(bufoff, gbase, voff) do { _Pragma("unroll") for (int _i = 0; _i < 2; ++_i) \
;         __builtin_amdgcn_global_load_lds((const unsigned*)((const char*)(gbase) + (voff)[_i]), (LAS unsigned*)(lds + (bufoff) + ldsw + _i * 8192), 16, 0, 0); } while (0)
; #define PG8_LDA(dst, b, h) do { _Pragma("unroll") for (int m = 0; m < 4; ++m) _Pragma("unroll") for (int k = 0; k < 2; ++k) dst[m][k] = *(const LAS bf16x8*)(lds + PG8_SA(b, h) + aoff + m * 2048 + k * 1024); } while (0)
; #define PG8_LDB(dst, b, h) do { _Pragma("unroll") for (int n = 0; n < 2; ++n) _Pragma("unroll") for (int k = 0; k < 2; ++k) dst[n][k] = *(const LAS bf16x8*)(lds + PG8_SB(b, h) + boff + n * 2048 + k * 1024); } while (0)
; #define PG8_MMA(ai, bj, At, Bt) do { __builtin_amdgcn_s_setprio(1); _Pragma("unroll") for (int m = 0; m < 4; ++m) _Pragma("unroll") for (int n = 0; n < 2; ++n) _Pragma("unroll") for (int k = 0; k < 2; ++k) \
;         acc[ai][bj][m][n] = __builtin_amdgcn_mfma_f32_16x16x32_bf16(Bt[n][k], At[m][k], acc[ai][bj][m][n], 0, 0, 0); __builtin_amdgcn_s_setprio(0); } while (0)
; #define PG8_WAIT_V(n) asm volatile("s_waitcnt vmcnt(" #n ")" ::: "memory")
; #define PG8_WAIT_L(n) asm volatile("s_waitcnt lgkmcnt(" #n ")" ::: "memory")
; #define PG8_BAR __builtin_amdgcn_s_barrier()
; #define PG8_SCHED __builtin_amdgcn_sched_barrier(0)
; template <class Epi, class Sched>
; __device__ __forceinline__ void gemm_phase(LAS unsigned char* lds, const Gemm g, const Sched& S, const Epi& E) {
;     ...
;             PG8_WAIT_V(8); PG8_WAIT_L(0); PG8_BAR; PG8_MMA(1, 0, At, B0); PG8_MMA(1, 1, At, B1); PG8_BAR; PG8_SCHED;
;             PG8_LDB(B0, 1, 0); PG8_LDB(B1, 1, 1); PG8_SCHED; PG8_LDA(At, 1, 0); PG8_STAGE(PG8_SA(0, 1), a2 + hstepA, voffA);
;             PG8_WAIT_V(8); PG8_WAIT_L(0); PG8_BAR; PG8_MMA(0, 0, At, B0); PG8_MMA(0, 1, At, B1); PG8_BAR; PG8_SCHED;
	s_waitcnt lgkmcnt(0)
	v_mfma_f32_16x16x32_bf16 v[62:65], v[130:133], v[162:165], 0
	v_mfma_f32_16x16x32_bf16 v[54:57], v[138:141], v[162:165], 0
	v_mfma_f32_16x16x32_bf16 v[46:49], v[130:133], v[194:197], 0
	v_mfma_f32_16x16x32_bf16 v[38:41], v[138:141], v[194:197], 0
	v_mfma_f32_16x16x32_bf16 v[30:33], v[130:133], v[202:205], 0
	v_mfma_f32_16x16x32_bf16 v[22:25], v[138:141], v[202:205], 0
	v_mfma_f32_16x16x32_bf16 v[14:17], v[130:133], v[228:231], 0
	v_mfma_f32_16x16x32_bf16 v[6:9], v[138:141], v[228:231], 0
	v_mfma_f32_16x16x32_bf16 v[62:65], v[134:137], v[166:169], v[62:65]
	v_mfma_f32_16x16x32_bf16 v[54:57], v[142:145], v[166:169], v[54:57]
	v_mfma_f32_16x16x32_bf16 v[46:49], v[134:137], v[198:201], v[46:49]
	v_mfma_f32_16x16x32_bf16 v[38:41], v[142:145], v[198:201], v[38:41]
	v_mfma_f32_16x16x32_bf16 v[30:33], v[134:137], v[224:227], v[30:33]
	v_mfma_f32_16x16x32_bf16 v[22:25], v[142:145], v[224:227], v[22:25]
	v_mfma_f32_16x16x32_bf16 v[14:17], v[134:137], v[232:235], v[14:17]
	v_mfma_f32_16x16x32_bf16 v[6:9], v[142:145], v[232:235], v[6:9]
	v_mfma_f32_16x16x32_bf16 v[58:61], v[146:149], v[162:165], 0
	v_mfma_f32_16x16x32_bf16 v[50:53], v[154:157], v[162:165], 0
	v_mfma_f32_16x16x32_bf16 v[42:45], v[146:149], v[194:197], 0
	v_mfma_f32_16x16x32_bf16 v[34:37], v[154:157], v[194:197], 0
	v_mfma_f32_16x16x32_bf16 v[26:29], v[146:149], v[202:205], 0
	v_mfma_f32_16x16x32_bf16 v[18:21], v[154:157], v[202:205], 0
	v_mfma_f32_16x16x32_bf16 v[10:13], v[146:149], v[228:231], 0
	v_mfma_f32_16x16x32_bf16 v[2:5], v[154:157], v[228:231], 0
	v_mfma_f32_16x16x32_bf16 v[58:61], v[150:153], v[166:169], v[58:61]
	v_mfma_f32_16x16x32_bf16 v[50:53], v[158:161], v[166:169], v[50:53]
	v_mfma_f32_16x16x32_bf16 v[42:45], v[150:153], v[198:201], v[42:45]
	v_mfma_f32_16x16x32_bf16 v[34:37], v[158:161], v[198:201], v[34:37]
	v_mfma_f32_16x16x32_bf16 v[26:29], v[150:153], v[224:227], v[26:29]
	v_mfma_f32_16x16x32_bf16 v[18:21], v[158:161], v[224:227], v[18:21]
	v_mfma_f32_16x16x32_bf16 v[10:13], v[150:153], v[232:235], v[10:13]
	v_mfma_f32_16x16x32_bf16 v[2:5], v[158:161], v[232:235], v[2:5]
	s_barrier
	s_add_i32 s88, 0, 0x18000
	s_add_i32 s89, 0, 0x1c000
	s_add_u32 s20, s20, 0x40000
	s_addc_u32 s21, s21, 0
	s_mov_b32 m0, s29
	s_nop 0
	global_load_lds_dwordx4 v170, s[20:21]
	s_mov_b32 m0, s30
	s_nop 0
	global_load_lds_dwordx4 v190, s[20:21]
	ds_read_b128 v[130:133], v246 offset:32768
	ds_read_b128 v[134:137], v246 offset:33792
	ds_read_b128 v[138:141], v246 offset:34816
	ds_read_b128 v[142:145], v246 offset:35840
	ds_read_b128 v[146:149], v246 offset:49152
	ds_read_b128 v[150:153], v246 offset:50176
	ds_read_b128 v[154:157], v246 offset:51200
	ds_read_b128 v[158:161], v246 offset:52224
	ds_read_b128 v[162:165], v222 offset:32768
	ds_read_b128 v[166:169], v222 offset:33792
	ds_read_b128 v[194:197], v222 offset:34816
	ds_read_b128 v[198:201], v222 offset:35840
	ds_read_b128 v[202:205], v222 offset:36864
	ds_read_b128 v[224:227], v222 offset:37888
	ds_read_b128 v[228:231], v222 offset:38912
	ds_read_b128 v[232:235], v222 offset:39936
	s_waitcnt vmcnt(8)
	s_waitcnt lgkmcnt(0)
	s_barrier
	s_waitcnt lgkmcnt(0)
	v_mfma_f32_16x16x32_bf16 v[126:129], v[130:133], v[162:165], v[126:129]
	v_mfma_f32_16x16x32_bf16 v[118:121], v[138:141], v[162:165], v[118:121]
	v_mfma_f32_16x16x32_bf16 v[110:113], v[130:133], v[194:197], v[110:113]
	v_mfma_f32_16x16x32_bf16 v[102:105], v[138:141], v[194:197], v[102:105]
	v_mfma_f32_16x16x32_bf16 v[94:97], v[130:133], v[202:205], v[94:97]
	v_mfma_f32_16x16x32_bf16 v[86:89], v[138:141], v[202:205], v[86:89]
	v_mfma_f32_16x16x32_bf16 v[78:81], v[130:133], v[228:231], v[78:81]
	v_mfma_f32_16x16x32_bf16 v[70:73], v[138:141], v[228:231], v[70:73]
	v_mfma_f32_16x16x32_bf16 v[126:129], v[134:137], v[166:169], v[126:129]
	v_mfma_f32_16x16x32_bf16 v[118:121], v[142:145], v[166:169], v[118:121]
	v_mfma_f32_16x16x32_bf16 v[110:113], v[134:137], v[198:201], v[110:113]
	v_mfma_f32_16x16x32_bf16 v[102:105], v[142:145], v[198:201], v[102:105]
	v_mfma_f32_16x16x32_bf16 v[94:97], v[134:137], v[224:227], v[94:97]
	v_mfma_f32_16x16x32_bf16 v[86:89], v[142:145], v[224:227], v[86:89]
	v_mfma_f32_16x16x32_bf16 v[78:81], v[134:137], v[232:235], v[78:81]
	v_mfma_f32_16x16x32_bf16 v[70:73], v[142:145], v[232:235], v[70:73]
	v_mfma_f32_16x16x32_bf16 v[122:125], v[146:149], v[162:165], v[122:125]
	v_mfma_f32_16x16x32_bf16 v[114:117], v[154:157], v[162:165], v[114:117]
	v_mfma_f32_16x16x32_bf16 v[106:109], v[146:149], v[194:197], v[106:109]
	v_mfma_f32_16x16x32_bf16 v[98:101], v[154:157], v[194:197], v[98:101]
	v_mfma_f32_16x16x32_bf16 v[90:93], v[146:149], v[202:205], v[90:93]
	v_mfma_f32_16x16x32_bf16 v[82:85], v[154:157], v[202:205], v[82:85]
	v_mfma_f32_16x16x32_bf16 v[74:77], v[146:149], v[228:231], v[74:77]
	v_mfma_f32_16x16x32_bf16 v[66:69], v[154:157], v[228:231], v[66:69]
	v_mfma_f32_16x16x32_bf16 v[122:125], v[150:153], v[166:169], v[122:125]
	v_mfma_f32_16x16x32_bf16 v[114:117], v[158:161], v[166:169], v[114:117]
	v_mfma_f32_16x16x32_bf16 v[106:109], v[150:153], v[198:201], v[106:109]
	v_mfma_f32_16x16x32_bf16 v[98:101], v[158:161], v[198:201], v[98:101]
	v_mfma_f32_16x16x32_bf16 v[90:93], v[150:153], v[224:227], v[90:93]
	v_mfma_f32_16x16x32_bf16 v[82:85], v[158:161], v[224:227], v[82:85]
	v_mfma_f32_16x16x32_bf16 v[74:77], v[150:153], v[232:235], v[74:77]
	v_mfma_f32_16x16x32_bf16 v[66:69], v[158:161], v[232:235], v[66:69]
	s_barrier
; #define PG8_STAGE(bufoff, gbase, voff) do { _Pragma("unroll") for (int _i = 0; _i < 2; ++_i) \
;         __builtin_amdgcn_global_load_lds((const unsigned*)((const char*)(gbase) + (voff)[_i]), (LAS unsigned*)(lds + (bufoff) + ldsw + _i * 8192), 16, 0, 0); } while (0)
; #define PG8_LDA(dst, b, h) do { _Pragma("unroll") for (int m = 0; m < 4; ++m) _Pragma("unroll") for (int k = 0; k < 2; ++k) dst[m][k] = *(const LAS bf16x8*)(lds + PG8_SA(b, h) + aoff + m * 2048 + k * 1024); } while (0)
; #define PG8_LDB(dst, b, h) do { _Pragma("unroll") for (int n = 0; n < 2; ++n) _Pragma("unroll") for (int k = 0; k < 2; ++k) dst[n][k] = *(const LAS bf16x8*)(lds + PG8_SB(b, h) + boff + n * 2048 + k * 1024); } while (0)
; #define PG8_WAIT_V(n) asm volatile("s_waitcnt vmcnt(" #n ")" ::: "memory")
; #define PG8_WAIT_L(n) asm volatile("s_waitcnt lgkmcnt(" #n ")" ::: "memory")
; template <class Epi, class Sched>
; __device__ __forceinline__ void gemm_phase(LAS unsigned char* lds, const Gemm g, const Sched& S, const Epi& E) {
;     ...
;             const bool last = (t == nt - 2);
;             const char* a1 = cA + (size_t)(t + 1) * kstep;
;             const char* a2 = last ? nA : cA + (size_t)(t + 2) * kstep; const char* b2 = last ? nB : cB + (size_t)(t + 2) * kstep;
;             const char* a3 = a2 + kstep; const char* b3 = b2 + kstep;
;             PG8_LDB(B0, 0, 0); PG8_LDB(B1, 0, 1); PG8_SCHED; PG8_LDA(At, 0, 0); PG8_STAGE(PG8_SA(1, 1), a1 + hstepA, voffA);
;             PG8_WAIT_V(8); PG8_WAIT_L(0); PG8_BAR; PG8_MMA(0, 0, At, B0); PG8_MMA(0, 1, At, B1); PG8_BAR; PG8_SCHED;
;             PG8_LDA(At, 0, 1); PG8_STAGE(PG8_SB(0, 0), b2, voffB); PG8_STAGE(PG8_SB(0, 1), b2 + hstepB, voffB); PG8_STAGE(PG8_SA(0, 0), a2, voffA);
;             PG8_WAIT_V(8); PG8_WAIT_L(0); PG8_BAR; PG8_MMA(1, 0, At, B0); PG8_MMA(1, 1, At, B1); PG8_BAR; PG8_SCHED;
;             PG8_LDB(B0, 1, 0); PG8_LDB(B1, 1, 1); PG8_SCHED; PG8_LDA(At, 1, 0); PG8_STAGE(PG8_SA(0, 1), a2 + hstepA, voffA);
;             PG8_WAIT_V(8); PG8_WAIT_L(0); PG8_BAR; PG8_MMA(0, 0, At, B0); PG8_MMA(0, 1, At, B1); PG8_BAR; PG8_SCHED;
;             PG8_LDA(At, 1, 1); PG8_STAGE(PG8_SB(1, 0), b3, voffB); PG8_STAGE(PG8_SB(1, 1), b3 + hstepB, voffB); PG8_STAGE(PG8_SA(1, 0), a3, voffA);
;             PG8_WAIT_V(8); PG8_WAIT_L(0); PG8_BAR; PG8_MMA(1, 0, At, B0); PG8_MMA(1, 1, At, B1); PG8_BAR; PG8_SCHED;
	s_add_i32 s20, s8, 0x18000
	s_add_u32 s88, s86, 0x80
	s_addc_u32 s89, s87, 0
	s_mov_b32 m0, s20
	s_nop 0
	global_load_lds_dwordx4 v172, s[88:89]
	s_add_i32 m0, s20, 0x2000
	s_add_u32 s20, s86, 0x40080
	s_addc_u32 s21, s87, 0
	s_add_i32 s12, s8, 0x1c000
	global_load_lds_dwordx4 v192, s[88:89]
	s_mov_b32 m0, s12
	s_nop 0
	global_load_lds_dwordx4 v172, s[20:21]
	s_add_i32 m0, s12, 0x2000
	s_nop 0
	global_load_lds_dwordx4 v192, s[20:21]
	s_mov_b32 m0, s31
	s_nop 0
	global_load_lds_dwordx4 v170, s[100:101]
	s_mov_b32 m0, s34
	s_nop 0
	global_load_lds_dwordx4 v190, s[100:101]
	ds_read_b128 v[162:165], v222 offset:49152
	ds_read_b128 v[166:169], v222 offset:50176
	ds_read_b128 v[194:197], v222 offset:51200
	ds_read_b128 v[198:201], v222 offset:52224
	ds_read_b128 v[202:205], v222 offset:53248
	ds_read_b128 v[224:227], v222 offset:54272
	ds_read_b128 v[228:231], v222 offset:55296
	ds_read_b128 v[232:235], v222 offset:56320
	s_waitcnt vmcnt(8)
	s_waitcnt lgkmcnt(0)
	s_barrier
	s_waitcnt lgkmcnt(0)
	v_mfma_f32_16x16x32_bf16 v[62:65], v[130:133], v[162:165], v[62:65]
	v_mfma_f32_16x16x32_bf16 v[54:57], v[138:141], v[162:165], v[54:57]
	v_mfma_f32_16x16x32_bf16 v[46:49], v[130:133], v[194:197], v[46:49]
	v_mfma_f32_16x16x32_bf16 v[38:41], v[138:141], v[194:197], v[38:41]
	v_mfma_f32_16x16x32_bf16 v[30:33], v[130:133], v[202:205], v[30:33]
	v_mfma_f32_16x16x32_bf16 v[22:25], v[138:141], v[202:205], v[22:25]
	v_mfma_f32_16x16x32_bf16 v[14:17], v[130:133], v[228:231], v[14:17]
	v_mfma_f32_16x16x32_bf16 v[6:9], v[138:141], v[228:231], v[6:9]
	v_mfma_f32_16x16x32_bf16 v[62:65], v[134:137], v[166:169], v[62:65]
	v_mfma_f32_16x16x32_bf16 v[54:57], v[142:145], v[166:169], v[54:57]
	v_mfma_f32_16x16x32_bf16 v[46:49], v[134:137], v[198:201], v[46:49]
	v_mfma_f32_16x16x32_bf16 v[38:41], v[142:145], v[198:201], v[38:41]
	v_mfma_f32_16x16x32_bf16 v[30:33], v[134:137], v[224:227], v[30:33]
	v_mfma_f32_16x16x32_bf16 v[22:25], v[142:145], v[224:227], v[22:25]
	v_mfma_f32_16x16x32_bf16 v[14:17], v[134:137], v[232:235], v[14:17]
	v_mfma_f32_16x16x32_bf16 v[6:9], v[142:145], v[232:235], v[6:9]
	v_mfma_f32_16x16x32_bf16 v[58:61], v[146:149], v[162:165], v[58:61]
	v_mfma_f32_16x16x32_bf16 v[50:53], v[154:157], v[162:165], v[50:53]
	v_mfma_f32_16x16x32_bf16 v[42:45], v[146:149], v[194:197], v[42:45]
	v_mfma_f32_16x16x32_bf16 v[34:37], v[154:157], v[194:197], v[34:37]
	v_mfma_f32_16x16x32_bf16 v[26:29], v[146:149], v[202:205], v[26:29]
	v_mfma_f32_16x16x32_bf16 v[18:21], v[154:157], v[202:205], v[18:21]
	v_mfma_f32_16x16x32_bf16 v[10:13], v[146:149], v[228:231], v[10:13]
	v_mfma_f32_16x16x32_bf16 v[2:5], v[154:157], v[228:231], v[2:5]
	v_mfma_f32_16x16x32_bf16 v[58:61], v[150:153], v[166:169], v[58:61]
	v_mfma_f32_16x16x32_bf16 v[50:53], v[158:161], v[166:169], v[50:53]
	v_mfma_f32_16x16x32_bf16 v[42:45], v[150:153], v[198:201], v[42:45]
	v_mfma_f32_16x16x32_bf16 v[34:37], v[158:161], v[198:201], v[34:37]
	v_mfma_f32_16x16x32_bf16 v[26:29], v[150:153], v[224:227], v[26:29]
	v_mfma_f32_16x16x32_bf16 v[18:21], v[158:161], v[224:227], v[18:21]
	v_mfma_f32_16x16x32_bf16 v[10:13], v[150:153], v[232:235], v[10:13]
	v_mfma_f32_16x16x32_bf16 v[2:5], v[158:161], v[232:235], v[2:5]
	s_barrier
	s_add_i32 s83, s83, 2
	s_add_u32 s18, s18, 0x100
	s_addc_u32 s19, s19, 0
	s_add_u32 s54, s54, 0x100
	s_addc_u32 s81, s81, 0
	s_cmp_gt_u32 s83, 13
.LBB0_232:
	s_add_u32 s20, s18, 0xfffc0080
	s_addc_u32 s21, s19, -1
	s_add_i32 s88, 0, 0x10000
	s_cmp_eq_u32 s83, 12
	s_cselect_b32 s21, s43, s21
	s_cselect_b32 s20, s48, s20
	s_cselect_b32 s87, s49, s81
	s_cselect_b32 s86, s53, s54
	s_add_i32 s90, 0, 0x14000
	s_add_u32 s100, s20, 0x80
	s_addc_u32 s101, s21, 0
	s_add_i32 m0, s9, 0xc000
	s_nop 0
	global_load_lds_dwordx4 v170, s[18:19]
	s_add_i32 m0, s9, 0xe000
	s_nop 0
	global_load_lds_dwordx4 v190, s[18:19]
	ds_read_b128 v[130:133], v246
	ds_read_b128 v[134:137], v246 offset:1024
	ds_read_b128 v[138:141], v246 offset:2048
	ds_read_b128 v[142:145], v246 offset:3072
	ds_read_b128 v[146:149], v246 offset:16384
	ds_read_b128 v[150:153], v246 offset:17408
	ds_read_b128 v[154:157], v246 offset:18432
	ds_read_b128 v[158:161], v246 offset:19456
	ds_read_b128 v[162:165], v222
	ds_read_b128 v[166:169], v222 offset:1024
	ds_read_b128 v[194:197], v222 offset:2048
	ds_read_b128 v[198:201], v222 offset:3072
	ds_read_b128 v[202:205], v222 offset:4096
	ds_read_b128 v[224:227], v222 offset:5120
	ds_read_b128 v[228:231], v222 offset:6144
	ds_read_b128 v[232:235], v222 offset:7168
	s_waitcnt vmcnt(8)
	s_waitcnt lgkmcnt(0)
	s_barrier
; #define PG8_STAGE(bufoff, gbase, voff) do { _Pragma("unroll") for (int _i = 0; _i < 2; ++_i) \
;         __builtin_amdgcn_global_load_lds((const unsigned*)((const char*)(gbase) + (voff)[_i]), (LAS unsigned*)(lds + (bufoff) + ldsw + _i * 8192), 16, 0, 0); } while (0)
; #define PG8_LDA(dst, b, h) do { _Pragma("unroll") for (int m = 0; m < 4; ++m) _Pragma("unroll") for (int k = 0; k < 2; ++k) dst[m][k] = *(const LAS bf16x8*)(lds + PG8_SA(b, h) + aoff + m * 2048 + k * 1024); } while (0)
; #define PG8_MMA(ai, bj, At, Bt) do { __builtin_amdgcn_s_setprio(1); _Pragma("unroll") for (int m = 0; m < 4; ++m) _Pragma("unroll") for (int n = 0; n < 2; ++n) _Pragma("unroll") for (int k = 0; k < 2; ++k) \
;         acc[ai][bj][m][n] = __builtin_amdgcn_mfma_f32_16x16x32_bf16(Bt[n][k], At[m][k], acc[ai][bj][m][n], 0, 0, 0); __builtin_amdgcn_s_setprio(0); } while (0)
; #define PG8_WAIT_V(n) asm volatile("s_waitcnt vmcnt(" #n ")" ::: "memory")
; #define PG8_WAIT_L(n) asm volatile("s_waitcnt lgkmcnt(" #n ")" ::: "memory")
; #define PG8_BAR __builtin_amdgcn_s_barrier()
; #define PG8_SCHED __builtin_amdgcn_sched_barrier(0)
; template <class Epi, class Sched>
; __device__ __forceinline__ void gemm_phase(LAS unsigned char* lds, const Gemm g, const Sched& S, const Epi& E) {
;     ...
;             PG8_WAIT_V(8); PG8_WAIT_L(0); PG8_BAR; PG8_MMA(0, 0, At, B0); PG8_MMA(0, 1, At, B1); PG8_BAR; PG8_SCHED;
;             PG8_LDA(At, 0, 1); PG8_STAGE(PG8_SB(0, 0), b2, voffB); PG8_STAGE(PG8_SB(0, 1), b2 + hstepB, voffB); PG8_STAGE(PG8_SA(0, 0), a2, voffA);
;             PG8_WAIT_V(8); PG8_WAIT_L(0); PG8_BAR; PG8_MMA(1, 0, At, B0); PG8_MMA(1, 1, At, B1); PG8_BAR; PG8_SCHED;
	s_waitcnt lgkmcnt(0)
	v_mfma_f32_16x16x32_bf16 v[126:129], v[130:133], v[162:165], v[126:129]
	v_mfma_f32_16x16x32_bf16 v[118:121], v[138:141], v[162:165], v[118:121]
	v_mfma_f32_16x16x32_bf16 v[110:113], v[130:133], v[194:197], v[110:113]
	v_mfma_f32_16x16x32_bf16 v[102:105], v[138:141], v[194:197], v[102:105]
	v_mfma_f32_16x16x32_bf16 v[94:97], v[130:133], v[202:205], v[94:97]
	v_mfma_f32_16x16x32_bf16 v[86:89], v[138:141], v[202:205], v[86:89]
	v_mfma_f32_16x16x32_bf16 v[78:81], v[130:133], v[228:231], v[78:81]
	v_mfma_f32_16x16x32_bf16 v[70:73], v[138:141], v[228:231], v[70:73]
	v_mfma_f32_16x16x32_bf16 v[126:129], v[134:137], v[166:169], v[126:129]
	v_mfma_f32_16x16x32_bf16 v[118:121], v[142:145], v[166:169], v[118:121]
	v_mfma_f32_16x16x32_bf16 v[110:113], v[134:137], v[198:201], v[110:113]
	v_mfma_f32_16x16x32_bf16 v[102:105], v[142:145], v[198:201], v[102:105]
	v_mfma_f32_16x16x32_bf16 v[94:97], v[134:137], v[224:227], v[94:97]
	v_mfma_f32_16x16x32_bf16 v[86:89], v[142:145], v[224:227], v[86:89]
	v_mfma_f32_16x16x32_bf16 v[78:81], v[134:137], v[232:235], v[78:81]
	v_mfma_f32_16x16x32_bf16 v[70:73], v[142:145], v[232:235], v[70:73]
	v_mfma_f32_16x16x32_bf16 v[122:125], v[146:149], v[162:165], v[122:125]
	v_mfma_f32_16x16x32_bf16 v[114:117], v[154:157], v[162:165], v[114:117]
	v_mfma_f32_16x16x32_bf16 v[106:109], v[146:149], v[194:197], v[106:109]
	v_mfma_f32_16x16x32_bf16 v[98:101], v[154:157], v[194:197], v[98:101]
	v_mfma_f32_16x16x32_bf16 v[90:93], v[146:149], v[202:205], v[90:93]
	v_mfma_f32_16x16x32_bf16 v[82:85], v[154:157], v[202:205], v[82:85]
	v_mfma_f32_16x16x32_bf16 v[74:77], v[146:149], v[228:231], v[74:77]
	v_mfma_f32_16x16x32_bf16 v[66:69], v[154:157], v[228:231], v[66:69]
	v_mfma_f32_16x16x32_bf16 v[122:125], v[150:153], v[166:169], v[122:125]
	v_mfma_f32_16x16x32_bf16 v[114:117], v[158:161], v[166:169], v[114:117]
	v_mfma_f32_16x16x32_bf16 v[106:109], v[150:153], v[198:201], v[106:109]
	v_mfma_f32_16x16x32_bf16 v[98:101], v[158:161], v[198:201], v[98:101]
	v_mfma_f32_16x16x32_bf16 v[90:93], v[150:153], v[224:227], v[90:93]
	v_mfma_f32_16x16x32_bf16 v[82:85], v[158:161], v[224:227], v[82:85]
	v_mfma_f32_16x16x32_bf16 v[74:77], v[150:153], v[232:235], v[74:77]
	v_mfma_f32_16x16x32_bf16 v[66:69], v[158:161], v[232:235], v[66:69]
	s_barrier
	s_add_i32 s88, s88, s8
	s_mov_b32 m0, s88
	s_nop 0
	global_load_lds_dwordx4 v172, s[86:87]
	s_add_i32 m0, s88, 0x2000
	s_add_u32 s88, s86, 0x40000
	s_addc_u32 s89, s87, 0
	s_add_i32 s90, s90, s8
	global_load_lds_dwordx4 v192, s[86:87]
	s_mov_b32 m0, s90
	s_nop 0
	global_load_lds_dwordx4 v172, s[88:89]
	s_add_i32 m0, s90, 0x2000
	s_nop 0
	global_load_lds_dwordx4 v192, s[88:89]
	s_mov_b32 m0, s9
	s_nop 0
	global_load_lds_dwordx4 v170, s[20:21]
	s_mov_b32 m0, s28
	s_nop 0
	global_load_lds_dwordx4 v190, s[20:21]
	ds_read_b128 v[162:165], v222 offset:16384
	ds_read_b128 v[166:169], v222 offset:17408
	ds_read_b128 v[194:197], v222 offset:18432
	ds_read_b128 v[198:201], v222 offset:19456
	ds_read_b128 v[202:205], v222 offset:20480
	ds_read_b128 v[224:227], v222 offset:21504
	ds_read_b128 v[228:231], v222 offset:22528
	ds_read_b128 v[232:235], v222 offset:23552
	s_waitcnt vmcnt(8)
	s_waitcnt lgkmcnt(0)
	s_barrier
	s_waitcnt lgkmcnt(0)
	v_mfma_f32_16x16x32_bf16 v[62:65], v[130:133], v[162:165], v[62:65]
	v_mfma_f32_16x16x32_bf16 v[54:57], v[138:141], v[162:165], v[54:57]
	v_mfma_f32_16x16x32_bf16 v[46:49], v[130:133], v[194:197], v[46:49]
	v_mfma_f32_16x16x32_bf16 v[38:41], v[138:141], v[194:197], v[38:41]
	v_mfma_f32_16x16x32_bf16 v[30:33], v[130:133], v[202:205], v[30:33]
	v_mfma_f32_16x16x32_bf16 v[22:25], v[138:141], v[202:205], v[22:25]
	v_mfma_f32_16x16x32_bf16 v[14:17], v[130:133], v[228:231], v[14:17]
	v_mfma_f32_16x16x32_bf16 v[6:9], v[138:141], v[228:231], v[6:9]
	v_mfma_f32_16x16x32_bf16 v[62:65], v[134:137], v[166:169], v[62:65]
	v_mfma_f32_16x16x32_bf16 v[54:57], v[142:145], v[166:169], v[54:57]
	v_mfma_f32_16x16x32_bf16 v[46:49], v[134:137], v[198:201], v[46:49]
	v_mfma_f32_16x16x32_bf16 v[38:41], v[142:145], v[198:201], v[38:41]
	v_mfma_f32_16x16x32_bf16 v[30:33], v[134:137], v[224:227], v[30:33]
	v_mfma_f32_16x16x32_bf16 v[22:25], v[142:145], v[224:227], v[22:25]
	v_mfma_f32_16x16x32_bf16 v[14:17], v[134:137], v[232:235], v[14:17]
	v_mfma_f32_16x16x32_bf16 v[6:9], v[142:145], v[232:235], v[6:9]
	v_mfma_f32_16x16x32_bf16 v[58:61], v[146:149], v[162:165], v[58:61]
	v_mfma_f32_16x16x32_bf16 v[50:53], v[154:157], v[162:165], v[50:53]
	v_mfma_f32_16x16x32_bf16 v[42:45], v[146:149], v[194:197], v[42:45]
	v_mfma_f32_16x16x32_bf16 v[34:37], v[154:157], v[194:197], v[34:37]
	v_mfma_f32_16x16x32_bf16 v[26:29], v[146:149], v[202:205], v[26:29]
	v_mfma_f32_16x16x32_bf16 v[18:21], v[154:157], v[202:205], v[18:21]
	v_mfma_f32_16x16x32_bf16 v[10:13], v[146:149], v[228:231], v[10:13]
	v_mfma_f32_16x16x32_bf16 v[2:5], v[154:157], v[228:231], v[2:5]
	v_mfma_f32_16x16x32_bf16 v[58:61], v[150:153], v[166:169], v[58:61]
	v_mfma_f32_16x16x32_bf16 v[50:53], v[158:161], v[166:169], v[50:53]
	v_mfma_f32_16x16x32_bf16 v[42:45], v[150:153], v[198:201], v[42:45]
	v_mfma_f32_16x16x32_bf16 v[34:37], v[158:161], v[198:201], v[34:37]
	v_mfma_f32_16x16x32_bf16 v[26:29], v[150:153], v[224:227], v[26:29]
	v_mfma_f32_16x16x32_bf16 v[18:21], v[158:161], v[224:227], v[18:21]
	v_mfma_f32_16x16x32_bf16 v[10:13], v[150:153], v[232:235], v[10:13]
	v_mfma_f32_16x16x32_bf16 v[2:5], v[158:161], v[232:235], v[2:5]
	s_barrier
; #define PG8_STAGE(bufoff, gbase, voff) do { _Pragma("unroll") for (int _i = 0; _i < 2; ++_i) \
;         __builtin_amdgcn_global_load_lds((const unsigned*)((const char*)(gbase) + (voff)[_i]), (LAS unsigned*)(lds + (bufoff) + ldsw + _i * 8192), 16, 0, 0); } while (0)
; #define PG8_LDA(dst, b, h) do { _Pragma("unroll") for (int m = 0; m < 4; ++m) _Pragma("unroll") for (int k = 0; k < 2; ++k) dst[m][k] = *(const LAS bf16x8*)(lds + PG8_SA(b, h) + aoff + m * 2048 + k * 1024); } while (0)
; #define PG8_LDB(dst, b, h) do { _Pragma("unroll") for (int n = 0; n < 2; ++n) _Pragma("unroll") for (int k = 0; k < 2; ++k) dst[n][k] = *(const LAS bf16x8*)(lds + PG8_SB(b, h) + boff + n * 2048 + k * 1024); } while (0)
; #define PG8_MMA(ai, bj, At, Bt) do { __builtin_amdgcn_s_setprio(1); _Pragma("unroll") for (int m = 0; m < 4; ++m) _Pragma("unroll") for (int n = 0; n < 2; ++n) _Pragma("unroll") for (int k = 0; k < 2; ++k) \
;         acc[ai][bj][m][n] = __builtin_amdgcn_mfma_f32_16x16x32_bf16(Bt[n][k], At[m][k], acc[ai][bj][m][n], 0, 0, 0); __builtin_amdgcn_s_setprio(0); } while (0)
; #define PG8_WAIT_V(n) asm volatile("s_waitcnt vmcnt(" #n ")" ::: "memory")
; #define PG8_WAIT_L(n) asm volatile("s_waitcnt lgkmcnt(" #n ")" ::: "memory")
; #define PG8_BAR __builtin_amdgcn_s_barrier()
; #define PG8_SCHED __builtin_amdgcn_sched_barrier(0)
; template <class Epi, class Sched>
; __device__ __forceinline__ void gemm_phase(LAS unsigned char* lds, const Gemm g, const Sched& S, const Epi& E) {
;     ...
;             PG8_LDB(B0, 1, 0); PG8_LDB(B1, 1, 1); PG8_SCHED; PG8_LDA(At, 1, 0); PG8_STAGE(PG8_SA(0, 1), a2 + hstepA, voffA);
;             PG8_WAIT_V(8); PG8_WAIT_L(0); PG8_BAR; PG8_MMA(0, 0, At, B0); PG8_MMA(0, 1, At, B1); PG8_BAR; PG8_SCHED;
;             PG8_LDA(At, 1, 1); PG8_STAGE(PG8_SB(1, 0), b3, voffB); PG8_STAGE(PG8_SB(1, 1), b3 + hstepB, voffB); PG8_STAGE(PG8_SA(1, 0), a3, voffA);
;             PG8_WAIT_V(8); PG8_WAIT_L(0); PG8_BAR; PG8_MMA(1, 0, At, B0); PG8_MMA(1, 1, At, B1); PG8_BAR; PG8_SCHED;
;         }
;         if (wr == 0) PG8_BAR;
	s_add_i32 s88, 0, 0x18000
	s_add_i32 s89, 0, 0x1c000
	s_add_u32 s20, s20, 0x40000
	s_addc_u32 s21, s21, 0
	s_mov_b32 m0, s29
	s_nop 0
	global_load_lds_dwordx4 v170, s[20:21]
	s_mov_b32 m0, s30
	s_nop 0
	global_load_lds_dwordx4 v190, s[20:21]
	ds_read_b128 v[130:133], v246 offset:32768
	ds_read_b128 v[134:137], v246 offset:33792
	ds_read_b128 v[138:141], v246 offset:34816
	ds_read_b128 v[142:145], v246 offset:35840
	ds_read_b128 v[146:149], v246 offset:49152
	ds_read_b128 v[150:153], v246 offset:50176
	ds_read_b128 v[154:157], v246 offset:51200
	ds_read_b128 v[158:161], v246 offset:52224
	ds_read_b128 v[162:165], v222 offset:32768
	ds_read_b128 v[166:169], v222 offset:33792
	ds_read_b128 v[194:197], v222 offset:34816
	ds_read_b128 v[198:201], v222 offset:35840
	ds_read_b128 v[202:205], v222 offset:36864
	ds_read_b128 v[224:227], v222 offset:37888
	ds_read_b128 v[228:231], v222 offset:38912
	ds_read_b128 v[232:235], v222 offset:39936
	s_waitcnt vmcnt(8)
	s_waitcnt lgkmcnt(0)
	s_barrier
	s_waitcnt lgkmcnt(0)
	v_mfma_f32_16x16x32_bf16 v[126:129], v[130:133], v[162:165], v[126:129]
	v_mfma_f32_16x16x32_bf16 v[118:121], v[138:141], v[162:165], v[118:121]
	v_mfma_f32_16x16x32_bf16 v[110:113], v[130:133], v[194:197], v[110:113]
	v_mfma_f32_16x16x32_bf16 v[102:105], v[138:141], v[194:197], v[102:105]
	v_mfma_f32_16x16x32_bf16 v[94:97], v[130:133], v[202:205], v[94:97]
	v_mfma_f32_16x16x32_bf16 v[86:89], v[138:141], v[202:205], v[86:89]
	v_mfma_f32_16x16x32_bf16 v[78:81], v[130:133], v[228:231], v[78:81]
	v_mfma_f32_16x16x32_bf16 v[70:73], v[138:141], v[228:231], v[70:73]
	v_mfma_f32_16x16x32_bf16 v[126:129], v[134:137], v[166:169], v[126:129]
	v_mfma_f32_16x16x32_bf16 v[118:121], v[142:145], v[166:169], v[118:121]
	v_mfma_f32_16x16x32_bf16 v[110:113], v[134:137], v[198:201], v[110:113]
	v_mfma_f32_16x16x32_bf16 v[102:105], v[142:145], v[198:201], v[102:105]
	v_mfma_f32_16x16x32_bf16 v[94:97], v[134:137], v[224:227], v[94:97]
	v_mfma_f32_16x16x32_bf16 v[86:89], v[142:145], v[224:227], v[86:89]
	v_mfma_f32_16x16x32_bf16 v[78:81], v[134:137], v[232:235], v[78:81]
	v_mfma_f32_16x16x32_bf16 v[70:73], v[142:145], v[232:235], v[70:73]
	v_mfma_f32_16x16x32_bf16 v[122:125], v[146:149], v[162:165], v[122:125]
	v_mfma_f32_16x16x32_bf16 v[114:117], v[154:157], v[162:165], v[114:117]
	v_mfma_f32_16x16x32_bf16 v[106:109], v[146:149], v[194:197], v[106:109]
	v_mfma_f32_16x16x32_bf16 v[98:101], v[154:157], v[194:197], v[98:101]
	v_mfma_f32_16x16x32_bf16 v[90:93], v[146:149], v[202:205], v[90:93]
	v_mfma_f32_16x16x32_bf16 v[82:85], v[154:157], v[202:205], v[82:85]
	v_mfma_f32_16x16x32_bf16 v[74:77], v[146:149], v[228:231], v[74:77]
	v_mfma_f32_16x16x32_bf16 v[66:69], v[154:157], v[228:231], v[66:69]
	v_mfma_f32_16x16x32_bf16 v[122:125], v[150:153], v[166:169], v[122:125]
	v_mfma_f32_16x16x32_bf16 v[114:117], v[158:161], v[166:169], v[114:117]
	v_mfma_f32_16x16x32_bf16 v[106:109], v[150:153], v[198:201], v[106:109]
	v_mfma_f32_16x16x32_bf16 v[98:101], v[158:161], v[198:201], v[98:101]
	v_mfma_f32_16x16x32_bf16 v[90:93], v[150:153], v[224:227], v[90:93]
	v_mfma_f32_16x16x32_bf16 v[82:85], v[158:161], v[224:227], v[82:85]
	v_mfma_f32_16x16x32_bf16 v[74:77], v[150:153], v[232:235], v[74:77]
	v_mfma_f32_16x16x32_bf16 v[66:69], v[158:161], v[232:235], v[66:69]
	s_barrier
	s_add_i32 s20, s8, 0x18000
	s_add_u32 s88, s86, 0x80
	s_addc_u32 s89, s87, 0
	s_mov_b32 m0, s20
	s_nop 0
	global_load_lds_dwordx4 v172, s[88:89]
	s_add_i32 m0, s20, 0x2000
	s_add_u32 s20, s86, 0x40080
	s_addc_u32 s21, s87, 0
	s_add_i32 s12, s8, 0x1c000
	global_load_lds_dwordx4 v192, s[88:89]
	s_mov_b32 m0, s12
	s_nop 0
	global_load_lds_dwordx4 v172, s[20:21]
	s_add_i32 m0, s12, 0x2000
	s_nop 0
	global_load_lds_dwordx4 v192, s[20:21]
	s_mov_b32 m0, s31
	s_nop 0
	global_load_lds_dwordx4 v170, s[100:101]
	s_mov_b32 m0, s34
	s_nop 0
	global_load_lds_dwordx4 v190, s[100:101]
	ds_read_b128 v[162:165], v222 offset:49152
	ds_read_b128 v[166:169], v222 offset:50176
	ds_read_b128 v[194:197], v222 offset:51200
	ds_read_b128 v[198:201], v222 offset:52224
	ds_read_b128 v[202:205], v222 offset:53248
	ds_read_b128 v[224:227], v222 offset:54272
	ds_read_b128 v[228:231], v222 offset:55296
	ds_read_b128 v[232:235], v222 offset:56320
	s_waitcnt vmcnt(8)
	s_waitcnt lgkmcnt(0)
	s_barrier
	s_waitcnt lgkmcnt(0)
	v_mfma_f32_16x16x32_bf16 v[62:65], v[130:133], v[162:165], v[62:65]
	v_mfma_f32_16x16x32_bf16 v[54:57], v[138:141], v[162:165], v[54:57]
	v_mfma_f32_16x16x32_bf16 v[46:49], v[130:133], v[194:197], v[46:49]
	v_mfma_f32_16x16x32_bf16 v[38:41], v[138:141], v[194:197], v[38:41]
	v_mfma_f32_16x16x32_bf16 v[30:33], v[130:133], v[202:205], v[30:33]
	v_mfma_f32_16x16x32_bf16 v[22:25], v[138:141], v[202:205], v[22:25]
	v_mfma_f32_16x16x32_bf16 v[14:17], v[130:133], v[228:231], v[14:17]
	v_mfma_f32_16x16x32_bf16 v[6:9], v[138:141], v[228:231], v[6:9]
	v_mfma_f32_16x16x32_bf16 v[62:65], v[134:137], v[166:169], v[62:65]
	v_mfma_f32_16x16x32_bf16 v[54:57], v[142:145], v[166:169], v[54:57]
	v_mfma_f32_16x16x32_bf16 v[46:49], v[134:137], v[198:201], v[46:49]
	v_mfma_f32_16x16x32_bf16 v[38:41], v[142:145], v[198:201], v[38:41]
	v_mfma_f32_16x16x32_bf16 v[30:33], v[134:137], v[224:227], v[30:33]
	v_mfma_f32_16x16x32_bf16 v[22:25], v[142:145], v[224:227], v[22:25]
	v_mfma_f32_16x16x32_bf16 v[14:17], v[134:137], v[232:235], v[14:17]
	v_mfma_f32_16x16x32_bf16 v[6:9], v[142:145], v[232:235], v[6:9]
	v_mfma_f32_16x16x32_bf16 v[58:61], v[146:149], v[162:165], v[58:61]
	v_mfma_f32_16x16x32_bf16 v[50:53], v[154:157], v[162:165], v[50:53]
	v_mfma_f32_16x16x32_bf16 v[42:45], v[146:149], v[194:197], v[42:45]
	v_mfma_f32_16x16x32_bf16 v[34:37], v[154:157], v[194:197], v[34:37]
	v_mfma_f32_16x16x32_bf16 v[26:29], v[146:149], v[202:205], v[26:29]
	v_mfma_f32_16x16x32_bf16 v[18:21], v[154:157], v[202:205], v[18:21]
	v_mfma_f32_16x16x32_bf16 v[10:13], v[146:149], v[228:231], v[10:13]
	v_mfma_f32_16x16x32_bf16 v[2:5], v[154:157], v[228:231], v[2:5]
	v_mfma_f32_16x16x32_bf16 v[58:61], v[150:153], v[166:169], v[58:61]
	v_mfma_f32_16x16x32_bf16 v[50:53], v[158:161], v[166:169], v[50:53]
	v_mfma_f32_16x16x32_bf16 v[42:45], v[150:153], v[198:201], v[42:45]
	v_mfma_f32_16x16x32_bf16 v[34:37], v[158:161], v[198:201], v[34:37]
	v_mfma_f32_16x16x32_bf16 v[26:29], v[150:153], v[224:227], v[26:29]
	v_mfma_f32_16x16x32_bf16 v[18:21], v[158:161], v[224:227], v[18:21]
	v_mfma_f32_16x16x32_bf16 v[10:13], v[150:153], v[232:235], v[10:13]
	v_mfma_f32_16x16x32_bf16 v[2:5], v[158:161], v[232:235], v[2:5]
	s_barrier
	s_add_i32 s83, s83, 2
	s_add_u32 s18, s18, 0x100
	s_addc_u32 s19, s19, 0
	s_add_u32 s54, s54, 0x100
	s_addc_u32 s81, s81, 0
	s_cmp_gt_u32 s83, 13
	s_cbranch_scc0 .LBB0_232
	s_and_b64 vcc, exec, s[72:73]
	s_cbranch_vccz .LBB0_235
	s_barrier

; #define PG8_STAGE(bufoff, gbase, voff) do { _Pragma("unroll") for (int _i = 0; _i < 2; ++_i) \
;         __builtin_amdgcn_global_load_lds((const unsigned*)((const char*)(gbase) + (voff)[_i]), (LAS unsigned*)(lds + (bufoff) + ldsw + _i * 8192), 16, 0, 0); } while (0)
; #define PG8_LDA(dst, b, h) do { _Pragma("unroll") for (int m = 0; m < 4; ++m) _Pragma("unroll") for (int k = 0; k < 2; ++k) dst[m][k] = *(const LAS bf16x8*)(lds + PG8_SA(b, h) + aoff + m * 2048 + k * 1024); } while (0)
; #define PG8_LDB(dst, b, h) do { _Pragma("unroll") for (int n = 0; n < 2; ++n) _Pragma("unroll") for (int k = 0; k < 2; ++k) dst[n][k] = *(const LAS bf16x8*)(lds + PG8_SB(b, h) + boff + n * 2048 + k * 1024); } while (0)
; #define PG8_MMA(ai, bj, At, Bt) do { __builtin_amdgcn_s_setprio(1); _Pragma("unroll") for (int m = 0; m < 4; ++m) _Pragma("unroll") for (int n = 0; n < 2; ++n) _Pragma("unroll") for (int k = 0; k < 2; ++k) \
;         acc[ai][bj][m][n] = __builtin_amdgcn_mfma_f32_16x16x32_bf16(Bt[n][k], At[m][k], acc[ai][bj][m][n], 0, 0, 0); __builtin_amdgcn_s_setprio(0); } while (0)
; #define PG8_WAIT_V(n) asm volatile("s_waitcnt vmcnt(" #n ")" ::: "memory")
; template <class Epi, class Sched>
; __device__ __forceinline__ void gemm_phase(LAS unsigned char* lds, const Gemm g, const Sched& S, const Epi& E) {
;     ...
;         const char* nA = has_next ? (const char*)g.A + (size_t)nxt.pm * tstepA + (size_t)nxt.pn * g.a_pn_off * 2 : cA; const char* nB = has_next ? (const char*)g.Bt + (size_t)nxt.pn * tstepB : cB;
;         for (int t = 0; t < nt; t += 2) {
;             const bool last = (t == nt - 2);
;             const char* a1 = cA + (size_t)(t + 1) * kstep;
;             const char* a2 = last ? nA : cA + (size_t)(t + 2) * kstep; const char* b2 = last ? nB : cB + (size_t)(t + 2) * kstep;
;             const char* a3 = a2 + kstep; const char* b3 = b2 + kstep;
;             PG8_LDB(B0, 0, 0); PG8_LDB(B1, 0, 1); PG8_SCHED; PG8_LDA(At, 0, 0); PG8_STAGE(PG8_SA(1, 1), a1 + hstepA, voffA);
;             PG8_WAIT_V(8); PG8_WAIT_L(0); PG8_BAR; PG8_MMA(0, 0, At, B0); PG8_MMA(0, 1, At, B1); PG8_BAR; PG8_SCHED;
;             PG8_LDA(At, 0, 1); PG8_STAGE(PG8_SB(0, 0), b2, voffB); PG8_STAGE(PG8_SB(0, 1), b2 + hstepB, voffB); PG8_STAGE(PG8_SA(0, 0), a2, voffA);
;             PG8_WAIT_V(8); PG8_WAIT_L(0); PG8_BAR; PG8_MMA(1, 0, At, B0); PG8_MMA(1, 1, At, B1); PG8_BAR; PG8_SCHED;
.LBB0_348:
	s_ashr_i32 s71, s70, 31
	s_lshl_b64 s[48:49], s[70:71], 19
	s_add_u32 s72, s4, s48
	s_addc_u32 s73, s5, s49
	s_and_b64 s[48:49], s[66:67], exec
	s_cselect_b32 s48, s73, s19
	s_cselect_b32 s49, s72, s18
	s_ashr_i32 s69, s68, 31
	s_lshl_b64 s[74:75], s[68:69], 19
	v_readlane_b32 s12, v248, 13
	s_add_u32 s74, s12, s74
	v_readlane_b32 s12, v248, 14
	s_addc_u32 s75, s12, s75
	s_and_b64 s[76:77], s[66:67], exec
	s_cselect_b32 s53, s75, s21
	s_cselect_b32 s54, s74, s20
	s_add_u32 s18, s18, 0x40080
	s_addc_u32 s19, s19, 0
	s_add_u32 s69, s20, 0x100
	s_addc_u32 s71, s21, 0
	s_mov_b32 s78, -2
	s_waitcnt vmcnt(0)
	v_add_u32_e32 v255, 0x10000, v139
	s_add_u32 s20, s18, 0xfffc0080
	s_addc_u32 s21, s19, -1
	s_add_i32 s79, 0, 0x10000
	s_cmp_eq_u32 s78, 12
	s_cselect_b32 s21, s48, s21
	s_cselect_b32 s20, s49, s20
	s_cselect_b32 s77, s53, s71
	s_cselect_b32 s76, s54, s69
	s_add_u32 s100, s20, 0x80
	s_addc_u32 s101, s21, 0
	s_add_i32 s82, 0, 0x14000
	s_add_i32 m0, s9, 0xc000
	s_nop 0
	global_load_lds_dwordx4 v130, s[18:19]
	s_add_i32 m0, s9, 0xe000
	s_nop 0
	global_load_lds_dwordx4 v134, s[18:19]
	ds_read_b128 v[150:153], v255
	ds_read_b128 v[154:157], v255 offset:1024
	ds_read_b128 v[158:161], v255 offset:2048
	ds_read_b128 v[162:165], v255 offset:3072
	ds_read_b128 v[166:169], v255 offset:16384
	ds_read_b128 v[170:173], v255 offset:17408
	ds_read_b128 v[190:193], v255 offset:18432
	ds_read_b128 v[194:197], v255 offset:19456
	ds_read_b128 v[198:201], v148
	ds_read_b128 v[202:205], v148 offset:1024
	ds_read_b128 v[206:209], v148 offset:2048
	ds_read_b128 v[218:221], v148 offset:3072
	ds_read_b128 v[222:225], v148 offset:4096
	ds_read_b128 v[226:229], v148 offset:5120
	ds_read_b128 v[230:233], v148 offset:6144
	ds_read_b128 v[234:237], v148 offset:7168
	s_waitcnt vmcnt(8)
	s_waitcnt lgkmcnt(0)
	s_barrier
	s_waitcnt lgkmcnt(0)
	v_mfma_f32_16x16x32_bf16 v[126:129], v[150:153], v[198:201], 0
	v_mfma_f32_16x16x32_bf16 v[122:125], v[158:161], v[198:201], 0
	v_mfma_f32_16x16x32_bf16 v[110:113], v[150:153], v[206:209], 0
	v_mfma_f32_16x16x32_bf16 v[106:109], v[158:161], v[206:209], 0
	v_mfma_f32_16x16x32_bf16 v[94:97], v[150:153], v[222:225], 0
	v_mfma_f32_16x16x32_bf16 v[90:93], v[158:161], v[222:225], 0
	v_mfma_f32_16x16x32_bf16 v[82:85], v[150:153], v[230:233], 0
	v_mfma_f32_16x16x32_bf16 v[74:77], v[158:161], v[230:233], 0
	v_mfma_f32_16x16x32_bf16 v[126:129], v[154:157], v[202:205], v[126:129]
	v_mfma_f32_16x16x32_bf16 v[122:125], v[162:165], v[202:205], v[122:125]
	v_mfma_f32_16x16x32_bf16 v[110:113], v[154:157], v[218:221], v[110:113]
	v_mfma_f32_16x16x32_bf16 v[106:109], v[162:165], v[218:221], v[106:109]
	v_mfma_f32_16x16x32_bf16 v[94:97], v[154:157], v[226:229], v[94:97]
	v_mfma_f32_16x16x32_bf16 v[90:93], v[162:165], v[226:229], v[90:93]
	v_mfma_f32_16x16x32_bf16 v[82:85], v[154:157], v[234:237], v[82:85]
	v_mfma_f32_16x16x32_bf16 v[74:77], v[162:165], v[234:237], v[74:77]
	v_mfma_f32_16x16x32_bf16 v[118:121], v[166:169], v[198:201], 0
	v_mfma_f32_16x16x32_bf16 v[114:117], v[190:193], v[198:201], 0
	v_mfma_f32_16x16x32_bf16 v[102:105], v[166:169], v[206:209], 0
	v_mfma_f32_16x16x32_bf16 v[98:101], v[190:193], v[206:209], 0
	v_mfma_f32_16x16x32_bf16 v[86:89], v[166:169], v[222:225], 0
	v_mfma_f32_16x16x32_bf16 v[78:81], v[190:193], v[222:225], 0
	v_mfma_f32_16x16x32_bf16 v[70:73], v[166:169], v[230:233], 0
	v_mfma_f32_16x16x32_bf16 v[66:69], v[190:193], v[230:233], 0
	v_mfma_f32_16x16x32_bf16 v[118:121], v[170:173], v[202:205], v[118:121]
	v_mfma_f32_16x16x32_bf16 v[114:117], v[194:197], v[202:205], v[114:117]
	v_mfma_f32_16x16x32_bf16 v[102:105], v[170:173], v[218:221], v[102:105]
	v_mfma_f32_16x16x32_bf16 v[98:101], v[194:197], v[218:221], v[98:101]
	v_mfma_f32_16x16x32_bf16 v[86:89], v[170:173], v[226:229], v[86:89]
	v_mfma_f32_16x16x32_bf16 v[78:81], v[194:197], v[226:229], v[78:81]
	v_mfma_f32_16x16x32_bf16 v[70:73], v[170:173], v[234:237], v[70:73]
	v_mfma_f32_16x16x32_bf16 v[66:69], v[194:197], v[234:237], v[66:69]
	s_barrier
	s_add_i32 s79, s79, s8
	s_mov_b32 m0, s79
	s_nop 0
	global_load_lds_dwordx4 v132, s[76:77]
	s_add_i32 m0, s79, 0x2000
	s_add_u32 s80, s76, 0x40000
	s_addc_u32 s81, s77, 0
	s_add_i32 s79, s82, s8
	global_load_lds_dwordx4 v136, s[76:77]
	s_mov_b32 m0, s79
	s_nop 0
	global_load_lds_dwordx4 v132, s[80:81]
	s_add_i32 m0, s79, 0x2000
	s_nop 0
	global_load_lds_dwordx4 v136, s[80:81]
	s_mov_b32 m0, s9
	s_nop 0
	global_load_lds_dwordx4 v130, s[20:21]
	s_mov_b32 m0, s28
	s_nop 0
	global_load_lds_dwordx4 v134, s[20:21]
	ds_read_b128 v[198:201], v148 offset:16384
	ds_read_b128 v[202:205], v148 offset:17408
	ds_read_b128 v[206:209], v148 offset:18432
	ds_read_b128 v[218:221], v148 offset:19456
	ds_read_b128 v[222:225], v148 offset:20480
	ds_read_b128 v[226:229], v148 offset:21504
	ds_read_b128 v[230:233], v148 offset:22528
	ds_read_b128 v[234:237], v148 offset:23552
	s_waitcnt vmcnt(8)
	s_waitcnt lgkmcnt(0)
	s_barrier
; #define PG8_STAGE(bufoff, gbase, voff) do { _Pragma("unroll") for (int _i = 0; _i < 2; ++_i) \
;         __builtin_amdgcn_global_load_lds((const unsigned*)((const char*)(gbase) + (voff)[_i]), (LAS unsigned*)(lds + (bufoff) + ldsw + _i * 8192), 16, 0, 0); } while (0)
; #define PG8_LDA(dst, b, h) do { _Pragma("unroll") for (int m = 0; m < 4; ++m) _Pragma("unroll") for (int k = 0; k < 2; ++k) dst[m][k] = *(const LAS bf16x8*)(lds + PG8_SA(b, h) + aoff + m * 2048 + k * 1024); } while (0)
; #define PG8_LDB(dst, b, h) do { _Pragma("unroll") for (int n = 0; n < 2; ++n) _Pragma("unroll") for (int k = 0; k < 2; ++k) dst[n][k] = *(const LAS bf16x8*)(lds + PG8_SB(b, h) + boff + n * 2048 + k * 1024); } while (0)
; #define PG8_MMA(ai, bj, At, Bt) do { __builtin_amdgcn_s_setprio(1); _Pragma("unroll") for (int m = 0; m < 4; ++m) _Pragma("unroll") for (int n = 0; n < 2; ++n) _Pragma("unroll") for (int k = 0; k < 2; ++k) \
;         acc[ai][bj][m][n] = __builtin_amdgcn_mfma_f32_16x16x32_bf16(Bt[n][k], At[m][k], acc[ai][bj][m][n], 0, 0, 0); __builtin_amdgcn_s_setprio(0); } while (0)
; #define PG8_WAIT_V(n) asm volatile("s_waitcnt vmcnt(" #n ")" ::: "memory")
; #define PG8_WAIT_L(n) asm volatile("s_waitcnt lgkmcnt(" #n ")" ::: "memory")
; #define PG8_BAR __builtin_amdgcn_s_barrier()
; #define PG8_SCHED __builtin_amdgcn_sched_barrier(0)
; template <class Epi, class Sched>
; __device__ __forceinline__ void gemm_phase(LAS unsigned char* lds, const Gemm g, const Sched& S, const Epi& E) {
;     ...
;             PG8_WAIT_V(8); PG8_WAIT_L(0); PG8_BAR; PG8_MMA(1, 0, At, B0); PG8_MMA(1, 1, At, B1); PG8_BAR; PG8_SCHED;
;             PG8_LDB(B0, 1, 0); PG8_LDB(B1, 1, 1); PG8_SCHED; PG8_LDA(At, 1, 0); PG8_STAGE(PG8_SA(0, 1), a2 + hstepA, voffA);
;             PG8_WAIT_V(8); PG8_WAIT_L(0); PG8_BAR; PG8_MMA(0, 0, At, B0); PG8_MMA(0, 1, At, B1); PG8_BAR; PG8_SCHED;
	s_waitcnt lgkmcnt(0)
	v_mfma_f32_16x16x32_bf16 v[62:65], v[150:153], v[198:201], 0
	v_mfma_f32_16x16x32_bf16 v[58:61], v[158:161], v[198:201], 0
	v_mfma_f32_16x16x32_bf16 v[50:53], v[150:153], v[206:209], 0
	v_mfma_f32_16x16x32_bf16 v[42:45], v[158:161], v[206:209], 0
	v_mfma_f32_16x16x32_bf16 v[30:33], v[150:153], v[222:225], 0
	v_mfma_f32_16x16x32_bf16 v[26:29], v[158:161], v[222:225], 0
	v_mfma_f32_16x16x32_bf16 v[18:21], v[150:153], v[230:233], 0
	v_mfma_f32_16x16x32_bf16 v[10:13], v[158:161], v[230:233], 0
	v_mfma_f32_16x16x32_bf16 v[62:65], v[154:157], v[202:205], v[62:65]
	v_mfma_f32_16x16x32_bf16 v[58:61], v[162:165], v[202:205], v[58:61]
	v_mfma_f32_16x16x32_bf16 v[50:53], v[154:157], v[218:221], v[50:53]
	v_mfma_f32_16x16x32_bf16 v[42:45], v[162:165], v[218:221], v[42:45]
	v_mfma_f32_16x16x32_bf16 v[30:33], v[154:157], v[226:229], v[30:33]
	v_mfma_f32_16x16x32_bf16 v[26:29], v[162:165], v[226:229], v[26:29]
	v_mfma_f32_16x16x32_bf16 v[18:21], v[154:157], v[234:237], v[18:21]
	v_mfma_f32_16x16x32_bf16 v[10:13], v[162:165], v[234:237], v[10:13]
	v_mfma_f32_16x16x32_bf16 v[54:57], v[166:169], v[198:201], 0
	v_mfma_f32_16x16x32_bf16 v[46:49], v[190:193], v[198:201], 0
	v_mfma_f32_16x16x32_bf16 v[38:41], v[166:169], v[206:209], 0
	v_mfma_f32_16x16x32_bf16 v[34:37], v[190:193], v[206:209], 0
	v_mfma_f32_16x16x32_bf16 v[22:25], v[166:169], v[222:225], 0
	v_mfma_f32_16x16x32_bf16 v[14:17], v[190:193], v[222:225], 0
	v_mfma_f32_16x16x32_bf16 v[6:9], v[166:169], v[230:233], 0
	v_mfma_f32_16x16x32_bf16 v[2:5], v[190:193], v[230:233], 0
	v_mfma_f32_16x16x32_bf16 v[54:57], v[170:173], v[202:205], v[54:57]
	v_mfma_f32_16x16x32_bf16 v[46:49], v[194:197], v[202:205], v[46:49]
	v_mfma_f32_16x16x32_bf16 v[38:41], v[170:173], v[218:221], v[38:41]
	v_mfma_f32_16x16x32_bf16 v[34:37], v[194:197], v[218:221], v[34:37]
	v_mfma_f32_16x16x32_bf16 v[22:25], v[170:173], v[226:229], v[22:25]
	v_mfma_f32_16x16x32_bf16 v[14:17], v[194:197], v[226:229], v[14:17]
	v_mfma_f32_16x16x32_bf16 v[6:9], v[170:173], v[234:237], v[6:9]
	v_mfma_f32_16x16x32_bf16 v[2:5], v[194:197], v[234:237], v[2:5]
	s_barrier
	s_add_i32 s79, 0, 0x18000
	s_add_i32 s80, 0, 0x1c000
	s_add_u32 s20, s20, 0x40000
	s_addc_u32 s21, s21, 0
	s_mov_b32 m0, s29
	s_nop 0
	global_load_lds_dwordx4 v130, s[20:21]
	s_mov_b32 m0, s30
	s_nop 0
	global_load_lds_dwordx4 v134, s[20:21]
	ds_read_b128 v[150:153], v255 offset:32768
	ds_read_b128 v[154:157], v255 offset:33792
	ds_read_b128 v[158:161], v255 offset:34816
	ds_read_b128 v[162:165], v255 offset:35840
	ds_read_b128 v[166:169], v255 offset:49152
	ds_read_b128 v[170:173], v255 offset:50176
	ds_read_b128 v[190:193], v255 offset:51200
	ds_read_b128 v[194:197], v255 offset:52224
	ds_read_b128 v[198:201], v148 offset:32768
	ds_read_b128 v[202:205], v148 offset:33792
	ds_read_b128 v[206:209], v148 offset:34816
	ds_read_b128 v[218:221], v148 offset:35840
	ds_read_b128 v[222:225], v148 offset:36864
	ds_read_b128 v[226:229], v148 offset:37888
	ds_read_b128 v[230:233], v148 offset:38912
	ds_read_b128 v[234:237], v148 offset:39936
	s_waitcnt vmcnt(8)
	s_waitcnt lgkmcnt(0)
	s_barrier
	s_waitcnt lgkmcnt(0)
	v_mfma_f32_16x16x32_bf16 v[126:129], v[150:153], v[198:201], v[126:129]
	v_mfma_f32_16x16x32_bf16 v[122:125], v[158:161], v[198:201], v[122:125]
	v_mfma_f32_16x16x32_bf16 v[110:113], v[150:153], v[206:209], v[110:113]
	v_mfma_f32_16x16x32_bf16 v[106:109], v[158:161], v[206:209], v[106:109]
	v_mfma_f32_16x16x32_bf16 v[94:97], v[150:153], v[222:225], v[94:97]
	v_mfma_f32_16x16x32_bf16 v[90:93], v[158:161], v[222:225], v[90:93]
	v_mfma_f32_16x16x32_bf16 v[82:85], v[150:153], v[230:233], v[82:85]
	v_mfma_f32_16x16x32_bf16 v[74:77], v[158:161], v[230:233], v[74:77]
	v_mfma_f32_16x16x32_bf16 v[126:129], v[154:157], v[202:205], v[126:129]
	v_mfma_f32_16x16x32_bf16 v[122:125], v[162:165], v[202:205], v[122:125]
	v_mfma_f32_16x16x32_bf16 v[110:113], v[154:157], v[218:221], v[110:113]
	v_mfma_f32_16x16x32_bf16 v[106:109], v[162:165], v[218:221], v[106:109]
	v_mfma_f32_16x16x32_bf16 v[94:97], v[154:157], v[226:229], v[94:97]
	v_mfma_f32_16x16x32_bf16 v[90:93], v[162:165], v[226:229], v[90:93]
	v_mfma_f32_16x16x32_bf16 v[82:85], v[154:157], v[234:237], v[82:85]
	v_mfma_f32_16x16x32_bf16 v[74:77], v[162:165], v[234:237], v[74:77]
	v_mfma_f32_16x16x32_bf16 v[118:121], v[166:169], v[198:201], v[118:121]
	v_mfma_f32_16x16x32_bf16 v[114:117], v[190:193], v[198:201], v[114:117]
	v_mfma_f32_16x16x32_bf16 v[102:105], v[166:169], v[206:209], v[102:105]
	v_mfma_f32_16x16x32_bf16 v[98:101], v[190:193], v[206:209], v[98:101]
	v_mfma_f32_16x16x32_bf16 v[86:89], v[166:169], v[222:225], v[86:89]
	v_mfma_f32_16x16x32_bf16 v[78:81], v[190:193], v[222:225], v[78:81]
	v_mfma_f32_16x16x32_bf16 v[70:73], v[166:169], v[230:233], v[70:73]
	v_mfma_f32_16x16x32_bf16 v[66:69], v[190:193], v[230:233], v[66:69]
	v_mfma_f32_16x16x32_bf16 v[118:121], v[170:173], v[202:205], v[118:121]
	v_mfma_f32_16x16x32_bf16 v[114:117], v[194:197], v[202:205], v[114:117]
	v_mfma_f32_16x16x32_bf16 v[102:105], v[170:173], v[218:221], v[102:105]
	v_mfma_f32_16x16x32_bf16 v[98:101], v[194:197], v[218:221], v[98:101]
	v_mfma_f32_16x16x32_bf16 v[86:89], v[170:173], v[226:229], v[86:89]
	v_mfma_f32_16x16x32_bf16 v[78:81], v[194:197], v[226:229], v[78:81]
	v_mfma_f32_16x16x32_bf16 v[70:73], v[170:173], v[234:237], v[70:73]
	v_mfma_f32_16x16x32_bf16 v[66:69], v[194:197], v[234:237], v[66:69]
	s_barrier
; #define PG8_STAGE(bufoff, gbase, voff) do { _Pragma("unroll") for (int _i = 0; _i < 2; ++_i) \
;         __builtin_amdgcn_global_load_lds((const unsigned*)((const char*)(gbase) + (voff)[_i]), (LAS unsigned*)(lds + (bufoff) + ldsw + _i * 8192), 16, 0, 0); } while (0)
; #define PG8_LDA(dst, b, h) do { _Pragma("unroll") for (int m = 0; m < 4; ++m) _Pragma("unroll") for (int k = 0; k < 2; ++k) dst[m][k] = *(const LAS bf16x8*)(lds + PG8_SA(b, h) + aoff + m * 2048 + k * 1024); } while (0)
; #define PG8_LDB(dst, b, h) do { _Pragma("unroll") for (int n = 0; n < 2; ++n) _Pragma("unroll") for (int k = 0; k < 2; ++k) dst[n][k] = *(const LAS bf16x8*)(lds + PG8_SB(b, h) + boff + n * 2048 + k * 1024); } while (0)
; #define PG8_WAIT_V(n) asm volatile("s_waitcnt vmcnt(" #n ")" ::: "memory")
; #define PG8_WAIT_L(n) asm volatile("s_waitcnt lgkmcnt(" #n ")" ::: "memory")
; template <class Epi, class Sched>
; __device__ __forceinline__ void gemm_phase(LAS unsigned char* lds, const Gemm g, const Sched& S, const Epi& E) {
;     ...
;             const bool last = (t == nt - 2);
;             const char* a1 = cA + (size_t)(t + 1) * kstep;
;             const char* a2 = last ? nA : cA + (size_t)(t + 2) * kstep; const char* b2 = last ? nB : cB + (size_t)(t + 2) * kstep;
;             const char* a3 = a2 + kstep; const char* b3 = b2 + kstep;
;             PG8_LDB(B0, 0, 0); PG8_LDB(B1, 0, 1); PG8_SCHED; PG8_LDA(At, 0, 0); PG8_STAGE(PG8_SA(1, 1), a1 + hstepA, voffA);
;             PG8_WAIT_V(8); PG8_WAIT_L(0); PG8_BAR; PG8_MMA(0, 0, At, B0); PG8_MMA(0, 1, At, B1); PG8_BAR; PG8_SCHED;
;             PG8_LDA(At, 0, 1); PG8_STAGE(PG8_SB(0, 0), b2, voffB); PG8_STAGE(PG8_SB(0, 1), b2 + hstepB, voffB); PG8_STAGE(PG8_SA(0, 0), a2, voffA);
;             PG8_WAIT_V(8); PG8_WAIT_L(0); PG8_BAR; PG8_MMA(1, 0, At, B0); PG8_MMA(1, 1, At, B1); PG8_BAR; PG8_SCHED;
;             PG8_LDB(B0, 1, 0); PG8_LDB(B1, 1, 1); PG8_SCHED; PG8_LDA(At, 1, 0); PG8_STAGE(PG8_SA(0, 1), a2 + hstepA, voffA);
;             PG8_WAIT_V(8); PG8_WAIT_L(0); PG8_BAR; PG8_MMA(0, 0, At, B0); PG8_MMA(0, 1, At, B1); PG8_BAR; PG8_SCHED;
;             PG8_LDA(At, 1, 1); PG8_STAGE(PG8_SB(1, 0), b3, voffB); PG8_STAGE(PG8_SB(1, 1), b3 + hstepB, voffB); PG8_STAGE(PG8_SA(1, 0), a3, voffA);
;             PG8_WAIT_V(8); PG8_WAIT_L(0); PG8_BAR; PG8_MMA(1, 0, At, B0); PG8_MMA(1, 1, At, B1); PG8_BAR; PG8_SCHED;
	s_add_i32 s20, s8, 0x18000
	s_add_u32 s80, s76, 0x80
	s_addc_u32 s81, s77, 0
	s_mov_b32 m0, s20
	s_nop 0
	global_load_lds_dwordx4 v132, s[80:81]
	s_add_i32 m0, s20, 0x2000
	s_add_u32 s20, s76, 0x40080
	s_addc_u32 s21, s77, 0
	s_add_i32 s12, s8, 0x1c000
	global_load_lds_dwordx4 v136, s[80:81]
	s_mov_b32 m0, s12
	s_nop 0
	global_load_lds_dwordx4 v132, s[20:21]
	s_add_i32 m0, s12, 0x2000
	s_nop 0
	global_load_lds_dwordx4 v136, s[20:21]
	s_mov_b32 m0, s31
	s_nop 0
	global_load_lds_dwordx4 v130, s[100:101]
	s_mov_b32 m0, s34
	s_nop 0
	global_load_lds_dwordx4 v134, s[100:101]
	ds_read_b128 v[198:201], v148 offset:49152
	ds_read_b128 v[202:205], v148 offset:50176
	ds_read_b128 v[206:209], v148 offset:51200
	ds_read_b128 v[218:221], v148 offset:52224
	ds_read_b128 v[222:225], v148 offset:53248
	ds_read_b128 v[226:229], v148 offset:54272
	ds_read_b128 v[230:233], v148 offset:55296
	ds_read_b128 v[234:237], v148 offset:56320
	s_waitcnt vmcnt(8)
	s_waitcnt lgkmcnt(0)
	s_barrier
	s_waitcnt lgkmcnt(0)
	v_mfma_f32_16x16x32_bf16 v[62:65], v[150:153], v[198:201], v[62:65]
	v_mfma_f32_16x16x32_bf16 v[58:61], v[158:161], v[198:201], v[58:61]
	v_mfma_f32_16x16x32_bf16 v[50:53], v[150:153], v[206:209], v[50:53]
	v_mfma_f32_16x16x32_bf16 v[42:45], v[158:161], v[206:209], v[42:45]
	v_mfma_f32_16x16x32_bf16 v[30:33], v[150:153], v[222:225], v[30:33]
	v_mfma_f32_16x16x32_bf16 v[26:29], v[158:161], v[222:225], v[26:29]
	v_mfma_f32_16x16x32_bf16 v[18:21], v[150:153], v[230:233], v[18:21]
	v_mfma_f32_16x16x32_bf16 v[10:13], v[158:161], v[230:233], v[10:13]
	v_mfma_f32_16x16x32_bf16 v[62:65], v[154:157], v[202:205], v[62:65]
	v_mfma_f32_16x16x32_bf16 v[58:61], v[162:165], v[202:205], v[58:61]
	v_mfma_f32_16x16x32_bf16 v[50:53], v[154:157], v[218:221], v[50:53]
	v_mfma_f32_16x16x32_bf16 v[42:45], v[162:165], v[218:221], v[42:45]
	v_mfma_f32_16x16x32_bf16 v[30:33], v[154:157], v[226:229], v[30:33]
	v_mfma_f32_16x16x32_bf16 v[26:29], v[162:165], v[226:229], v[26:29]
	v_mfma_f32_16x16x32_bf16 v[18:21], v[154:157], v[234:237], v[18:21]
	v_mfma_f32_16x16x32_bf16 v[10:13], v[162:165], v[234:237], v[10:13]
	v_mfma_f32_16x16x32_bf16 v[54:57], v[166:169], v[198:201], v[54:57]
	v_mfma_f32_16x16x32_bf16 v[46:49], v[190:193], v[198:201], v[46:49]
	v_mfma_f32_16x16x32_bf16 v[38:41], v[166:169], v[206:209], v[38:41]
	v_mfma_f32_16x16x32_bf16 v[34:37], v[190:193], v[206:209], v[34:37]
	v_mfma_f32_16x16x32_bf16 v[22:25], v[166:169], v[222:225], v[22:25]
	v_mfma_f32_16x16x32_bf16 v[14:17], v[190:193], v[222:225], v[14:17]
	v_mfma_f32_16x16x32_bf16 v[6:9], v[166:169], v[230:233], v[6:9]
	v_mfma_f32_16x16x32_bf16 v[2:5], v[190:193], v[230:233], v[2:5]
	v_mfma_f32_16x16x32_bf16 v[54:57], v[170:173], v[202:205], v[54:57]
	v_mfma_f32_16x16x32_bf16 v[46:49], v[194:197], v[202:205], v[46:49]
	v_mfma_f32_16x16x32_bf16 v[38:41], v[170:173], v[218:221], v[38:41]
	v_mfma_f32_16x16x32_bf16 v[34:37], v[194:197], v[218:221], v[34:37]
	v_mfma_f32_16x16x32_bf16 v[22:25], v[170:173], v[226:229], v[22:25]
	v_mfma_f32_16x16x32_bf16 v[14:17], v[194:197], v[226:229], v[14:17]
	v_mfma_f32_16x16x32_bf16 v[6:9], v[170:173], v[234:237], v[6:9]
	v_mfma_f32_16x16x32_bf16 v[2:5], v[194:197], v[234:237], v[2:5]
	s_barrier
	s_add_i32 s78, s78, 2
	s_add_u32 s18, s18, 0x100
	s_addc_u32 s19, s19, 0
	s_add_u32 s69, s69, 0x100
	s_addc_u32 s71, s71, 0
	s_cmp_gt_u32 s78, 13
.LBB0_349:
	s_add_u32 s20, s18, 0xfffc0080
	s_addc_u32 s21, s19, -1
	s_add_i32 s79, 0, 0x10000
	s_cmp_eq_u32 s78, 12
	s_cselect_b32 s21, s48, s21
	s_cselect_b32 s20, s49, s20
	s_cselect_b32 s77, s53, s71
	s_cselect_b32 s76, s54, s69
	s_add_u32 s100, s20, 0x80
	s_addc_u32 s101, s21, 0
	s_add_i32 s82, 0, 0x14000
	s_add_i32 m0, s9, 0xc000
	s_nop 0
	global_load_lds_dwordx4 v130, s[18:19]
	s_add_i32 m0, s9, 0xe000
	s_nop 0
	global_load_lds_dwordx4 v134, s[18:19]
	ds_read_b128 v[150:153], v255
	ds_read_b128 v[154:157], v255 offset:1024
	ds_read_b128 v[158:161], v255 offset:2048
	ds_read_b128 v[162:165], v255 offset:3072
	ds_read_b128 v[166:169], v255 offset:16384
	ds_read_b128 v[170:173], v255 offset:17408
	ds_read_b128 v[190:193], v255 offset:18432
	ds_read_b128 v[194:197], v255 offset:19456
	ds_read_b128 v[198:201], v148
	ds_read_b128 v[202:205], v148 offset:1024
	ds_read_b128 v[206:209], v148 offset:2048
	ds_read_b128 v[218:221], v148 offset:3072
	ds_read_b128 v[222:225], v148 offset:4096
	ds_read_b128 v[226:229], v148 offset:5120
	ds_read_b128 v[230:233], v148 offset:6144
	ds_read_b128 v[234:237], v148 offset:7168
	s_waitcnt vmcnt(8)
	s_waitcnt lgkmcnt(0)
	s_barrier
; #define PG8_STAGE(bufoff, gbase, voff) do { _Pragma("unroll") for (int _i = 0; _i < 2; ++_i) \
;         __builtin_amdgcn_global_load_lds((const unsigned*)((const char*)(gbase) + (voff)[_i]), (LAS unsigned*)(lds + (bufoff) + ldsw + _i * 8192), 16, 0, 0); } while (0)
; #define PG8_LDA(dst, b, h) do { _Pragma("unroll") for (int m = 0; m < 4; ++m) _Pragma("unroll") for (int k = 0; k < 2; ++k) dst[m][k] = *(const LAS bf16x8*)(lds + PG8_SA(b, h) + aoff + m * 2048 + k * 1024); } while (0)
; #define PG8_MMA(ai, bj, At, Bt) do { __builtin_amdgcn_s_setprio(1); _Pragma("unroll") for (int m = 0; m < 4; ++m) _Pragma("unroll") for (int n = 0; n < 2; ++n) _Pragma("unroll") for (int k = 0; k < 2; ++k) \
;         acc[ai][bj][m][n] = __builtin_amdgcn_mfma_f32_16x16x32_bf16(Bt[n][k], At[m][k], acc[ai][bj][m][n], 0, 0, 0); __builtin_amdgcn_s_setprio(0); } while (0)
; #define PG8_WAIT_V(n) asm volatile("s_waitcnt vmcnt(" #n ")" ::: "memory")
; #define PG8_WAIT_L(n) asm volatile("s_waitcnt lgkmcnt(" #n ")" ::: "memory")
; #define PG8_BAR __builtin_amdgcn_s_barrier()
; #define PG8_SCHED __builtin_amdgcn_sched_barrier(0)
; template <class Epi, class Sched>
; __device__ __forceinline__ void gemm_phase(LAS unsigned char* lds, const Gemm g, const Sched& S, const Epi& E) {
;     ...
;             PG8_WAIT_V(8); PG8_WAIT_L(0); PG8_BAR; PG8_MMA(0, 0, At, B0); PG8_MMA(0, 1, At, B1); PG8_BAR; PG8_SCHED;
;             PG8_LDA(At, 0, 1); PG8_STAGE(PG8_SB(0, 0), b2, voffB); PG8_STAGE(PG8_SB(0, 1), b2 + hstepB, voffB); PG8_STAGE(PG8_SA(0, 0), a2, voffA);
;             PG8_WAIT_V(8); PG8_WAIT_L(0); PG8_BAR; PG8_MMA(1, 0, At, B0); PG8_MMA(1, 1, At, B1); PG8_BAR; PG8_SCHED;
	s_waitcnt lgkmcnt(0)
	v_mfma_f32_16x16x32_bf16 v[126:129], v[150:153], v[198:201], v[126:129]
	v_mfma_f32_16x16x32_bf16 v[122:125], v[158:161], v[198:201], v[122:125]
	v_mfma_f32_16x16x32_bf16 v[110:113], v[150:153], v[206:209], v[110:113]
	v_mfma_f32_16x16x32_bf16 v[106:109], v[158:161], v[206:209], v[106:109]
	v_mfma_f32_16x16x32_bf16 v[94:97], v[150:153], v[222:225], v[94:97]
	v_mfma_f32_16x16x32_bf16 v[90:93], v[158:161], v[222:225], v[90:93]
	v_mfma_f32_16x16x32_bf16 v[82:85], v[150:153], v[230:233], v[82:85]
	v_mfma_f32_16x16x32_bf16 v[74:77], v[158:161], v[230:233], v[74:77]
	v_mfma_f32_16x16x32_bf16 v[126:129], v[154:157], v[202:205], v[126:129]
	v_mfma_f32_16x16x32_bf16 v[122:125], v[162:165], v[202:205], v[122:125]
	v_mfma_f32_16x16x32_bf16 v[110:113], v[154:157], v[218:221], v[110:113]
	v_mfma_f32_16x16x32_bf16 v[106:109], v[162:165], v[218:221], v[106:109]
	v_mfma_f32_16x16x32_bf16 v[94:97], v[154:157], v[226:229], v[94:97]
	v_mfma_f32_16x16x32_bf16 v[90:93], v[162:165], v[226:229], v[90:93]
	v_mfma_f32_16x16x32_bf16 v[82:85], v[154:157], v[234:237], v[82:85]
	v_mfma_f32_16x16x32_bf16 v[74:77], v[162:165], v[234:237], v[74:77]
	v_mfma_f32_16x16x32_bf16 v[118:121], v[166:169], v[198:201], v[118:121]
	v_mfma_f32_16x16x32_bf16 v[114:117], v[190:193], v[198:201], v[114:117]
	v_mfma_f32_16x16x32_bf16 v[102:105], v[166:169], v[206:209], v[102:105]
	v_mfma_f32_16x16x32_bf16 v[98:101], v[190:193], v[206:209], v[98:101]
	v_mfma_f32_16x16x32_bf16 v[86:89], v[166:169], v[222:225], v[86:89]
	v_mfma_f32_16x16x32_bf16 v[78:81], v[190:193], v[222:225], v[78:81]
	v_mfma_f32_16x16x32_bf16 v[70:73], v[166:169], v[230:233], v[70:73]
	v_mfma_f32_16x16x32_bf16 v[66:69], v[190:193], v[230:233], v[66:69]
	v_mfma_f32_16x16x32_bf16 v[118:121], v[170:173], v[202:205], v[118:121]
	v_mfma_f32_16x16x32_bf16 v[114:117], v[194:197], v[202:205], v[114:117]
	v_mfma_f32_16x16x32_bf16 v[102:105], v[170:173], v[218:221], v[102:105]
	v_mfma_f32_16x16x32_bf16 v[98:101], v[194:197], v[218:221], v[98:101]
	v_mfma_f32_16x16x32_bf16 v[86:89], v[170:173], v[226:229], v[86:89]
	v_mfma_f32_16x16x32_bf16 v[78:81], v[194:197], v[226:229], v[78:81]
	v_mfma_f32_16x16x32_bf16 v[70:73], v[170:173], v[234:237], v[70:73]
	v_mfma_f32_16x16x32_bf16 v[66:69], v[194:197], v[234:237], v[66:69]
	s_barrier
	s_add_i32 s79, s79, s8
	s_mov_b32 m0, s79
	s_nop 0
	global_load_lds_dwordx4 v132, s[76:77]
	s_add_i32 m0, s79, 0x2000
	s_add_u32 s80, s76, 0x40000
	s_addc_u32 s81, s77, 0
	s_add_i32 s79, s82, s8
	global_load_lds_dwordx4 v136, s[76:77]
	s_mov_b32 m0, s79
	s_nop 0
	global_load_lds_dwordx4 v132, s[80:81]
	s_add_i32 m0, s79, 0x2000
	s_nop 0
	global_load_lds_dwordx4 v136, s[80:81]
	s_mov_b32 m0, s9
	s_nop 0
	global_load_lds_dwordx4 v130, s[20:21]
	s_mov_b32 m0, s28
	s_nop 0
	global_load_lds_dwordx4 v134, s[20:21]
	ds_read_b128 v[198:201], v148 offset:16384
	ds_read_b128 v[202:205], v148 offset:17408
	ds_read_b128 v[206:209], v148 offset:18432
	ds_read_b128 v[218:221], v148 offset:19456
	ds_read_b128 v[222:225], v148 offset:20480
	ds_read_b128 v[226:229], v148 offset:21504
	ds_read_b128 v[230:233], v148 offset:22528
	ds_read_b128 v[234:237], v148 offset:23552
	s_waitcnt vmcnt(8)
	s_waitcnt lgkmcnt(0)
	s_barrier
	s_waitcnt lgkmcnt(0)
	v_mfma_f32_16x16x32_bf16 v[62:65], v[150:153], v[198:201], v[62:65]
	v_mfma_f32_16x16x32_bf16 v[58:61], v[158:161], v[198:201], v[58:61]
	v_mfma_f32_16x16x32_bf16 v[50:53], v[150:153], v[206:209], v[50:53]
	v_mfma_f32_16x16x32_bf16 v[42:45], v[158:161], v[206:209], v[42:45]
	v_mfma_f32_16x16x32_bf16 v[30:33], v[150:153], v[222:225], v[30:33]
	v_mfma_f32_16x16x32_bf16 v[26:29], v[158:161], v[222:225], v[26:29]
	v_mfma_f32_16x16x32_bf16 v[18:21], v[150:153], v[230:233], v[18:21]
	v_mfma_f32_16x16x32_bf16 v[10:13], v[158:161], v[230:233], v[10:13]
	v_mfma_f32_16x16x32_bf16 v[62:65], v[154:157], v[202:205], v[62:65]
	v_mfma_f32_16x16x32_bf16 v[58:61], v[162:165], v[202:205], v[58:61]
	v_mfma_f32_16x16x32_bf16 v[50:53], v[154:157], v[218:221], v[50:53]
	v_mfma_f32_16x16x32_bf16 v[42:45], v[162:165], v[218:221], v[42:45]
	v_mfma_f32_16x16x32_bf16 v[30:33], v[154:157], v[226:229], v[30:33]
	v_mfma_f32_16x16x32_bf16 v[26:29], v[162:165], v[226:229], v[26:29]
	v_mfma_f32_16x16x32_bf16 v[18:21], v[154:157], v[234:237], v[18:21]
	v_mfma_f32_16x16x32_bf16 v[10:13], v[162:165], v[234:237], v[10:13]
	v_mfma_f32_16x16x32_bf16 v[54:57], v[166:169], v[198:201], v[54:57]
	v_mfma_f32_16x16x32_bf16 v[46:49], v[190:193], v[198:201], v[46:49]
	v_mfma_f32_16x16x32_bf16 v[38:41], v[166:169], v[206:209], v[38:41]
	v_mfma_f32_16x16x32_bf16 v[34:37], v[190:193], v[206:209], v[34:37]
	v_mfma_f32_16x16x32_bf16 v[22:25], v[166:169], v[222:225], v[22:25]
	v_mfma_f32_16x16x32_bf16 v[14:17], v[190:193], v[222:225], v[14:17]
	v_mfma_f32_16x16x32_bf16 v[6:9], v[166:169], v[230:233], v[6:9]
	v_mfma_f32_16x16x32_bf16 v[2:5], v[190:193], v[230:233], v[2:5]
	v_mfma_f32_16x16x32_bf16 v[54:57], v[170:173], v[202:205], v[54:57]
	v_mfma_f32_16x16x32_bf16 v[46:49], v[194:197], v[202:205], v[46:49]
	v_mfma_f32_16x16x32_bf16 v[38:41], v[170:173], v[218:221], v[38:41]
	v_mfma_f32_16x16x32_bf16 v[34:37], v[194:197], v[218:221], v[34:37]
	v_mfma_f32_16x16x32_bf16 v[22:25], v[170:173], v[226:229], v[22:25]
	v_mfma_f32_16x16x32_bf16 v[14:17], v[194:197], v[226:229], v[14:17]
	v_mfma_f32_16x16x32_bf16 v[6:9], v[170:173], v[234:237], v[6:9]
	v_mfma_f32_16x16x32_bf16 v[2:5], v[194:197], v[234:237], v[2:5]
	s_barrier
; #define PG8_STAGE(bufoff, gbase, voff) do { _Pragma("unroll") for (int _i = 0; _i < 2; ++_i) \
;         __builtin_amdgcn_global_load_lds((const unsigned*)((const char*)(gbase) + (voff)[_i]), (LAS unsigned*)(lds + (bufoff) + ldsw + _i * 8192), 16, 0, 0); } while (0)
; #define PG8_LDA(dst, b, h) do { _Pragma("unroll") for (int m = 0; m < 4; ++m) _Pragma("unroll") for (int k = 0; k < 2; ++k) dst[m][k] = *(const LAS bf16x8*)(lds + PG8_SA(b, h) + aoff + m * 2048 + k * 1024); } while (0)
; #define PG8_LDB(dst, b, h) do { _Pragma("unroll") for (int n = 0; n < 2; ++n) _Pragma("unroll") for (int k = 0; k < 2; ++k) dst[n][k] = *(const LAS bf16x8*)(lds + PG8_SB(b, h) + boff + n * 2048 + k * 1024); } while (0)
; #define PG8_MMA(ai, bj, At, Bt) do { __builtin_amdgcn_s_setprio(1); _Pragma("unroll") for (int m = 0; m < 4; ++m) _Pragma("unroll") for (int n = 0; n < 2; ++n) _Pragma("unroll") for (int k = 0; k < 2; ++k) \
;         acc[ai][bj][m][n] = __builtin_amdgcn_mfma_f32_16x16x32_bf16(Bt[n][k], At[m][k], acc[ai][bj][m][n], 0, 0, 0); __builtin_amdgcn_s_setprio(0); } while (0)
; #define PG8_WAIT_V(n) asm volatile("s_waitcnt vmcnt(" #n ")" ::: "memory")
; #define PG8_WAIT_L(n) asm volatile("s_waitcnt lgkmcnt(" #n ")" ::: "memory")
; #define PG8_BAR __builtin_amdgcn_s_barrier()
; #define PG8_SCHED __builtin_amdgcn_sched_barrier(0)
; template <class Epi, class Sched>
; __device__ __forceinline__ void gemm_phase(LAS unsigned char* lds, const Gemm g, const Sched& S, const Epi& E) {
;     ...
;             PG8_LDB(B0, 1, 0); PG8_LDB(B1, 1, 1); PG8_SCHED; PG8_LDA(At, 1, 0); PG8_STAGE(PG8_SA(0, 1), a2 + hstepA, voffA);
;             PG8_WAIT_V(8); PG8_WAIT_L(0); PG8_BAR; PG8_MMA(0, 0, At, B0); PG8_MMA(0, 1, At, B1); PG8_BAR; PG8_SCHED;
;             PG8_LDA(At, 1, 1); PG8_STAGE(PG8_SB(1, 0), b3, voffB); PG8_STAGE(PG8_SB(1, 1), b3 + hstepB, voffB); PG8_STAGE(PG8_SA(1, 0), a3, voffA);
;             PG8_WAIT_V(8); PG8_WAIT_L(0); PG8_BAR; PG8_MMA(1, 0, At, B0); PG8_MMA(1, 1, At, B1); PG8_BAR; PG8_SCHED;
;         }
;         if (wr == 0) PG8_BAR;
	s_add_i32 s79, 0, 0x18000
	s_add_i32 s80, 0, 0x1c000
	s_add_u32 s20, s20, 0x40000
	s_addc_u32 s21, s21, 0
	s_mov_b32 m0, s29
	s_nop 0
	global_load_lds_dwordx4 v130, s[20:21]
	s_mov_b32 m0, s30
	s_nop 0
	global_load_lds_dwordx4 v134, s[20:21]
	ds_read_b128 v[150:153], v255 offset:32768
	ds_read_b128 v[154:157], v255 offset:33792
	ds_read_b128 v[158:161], v255 offset:34816
	ds_read_b128 v[162:165], v255 offset:35840
	ds_read_b128 v[166:169], v255 offset:49152
	ds_read_b128 v[170:173], v255 offset:50176
	ds_read_b128 v[190:193], v255 offset:51200
	ds_read_b128 v[194:197], v255 offset:52224
	ds_read_b128 v[198:201], v148 offset:32768
	ds_read_b128 v[202:205], v148 offset:33792
	ds_read_b128 v[206:209], v148 offset:34816
	ds_read_b128 v[218:221], v148 offset:35840
	ds_read_b128 v[222:225], v148 offset:36864
	ds_read_b128 v[226:229], v148 offset:37888
	ds_read_b128 v[230:233], v148 offset:38912
	ds_read_b128 v[234:237], v148 offset:39936
	s_waitcnt vmcnt(8)
	s_waitcnt lgkmcnt(0)
	s_barrier
	s_waitcnt lgkmcnt(0)
	v_mfma_f32_16x16x32_bf16 v[126:129], v[150:153], v[198:201], v[126:129]
	v_mfma_f32_16x16x32_bf16 v[122:125], v[158:161], v[198:201], v[122:125]
	v_mfma_f32_16x16x32_bf16 v[110:113], v[150:153], v[206:209], v[110:113]
	v_mfma_f32_16x16x32_bf16 v[106:109], v[158:161], v[206:209], v[106:109]
	v_mfma_f32_16x16x32_bf16 v[94:97], v[150:153], v[222:225], v[94:97]
	v_mfma_f32_16x16x32_bf16 v[90:93], v[158:161], v[222:225], v[90:93]
	v_mfma_f32_16x16x32_bf16 v[82:85], v[150:153], v[230:233], v[82:85]
	v_mfma_f32_16x16x32_bf16 v[74:77], v[158:161], v[230:233], v[74:77]
	v_mfma_f32_16x16x32_bf16 v[126:129], v[154:157], v[202:205], v[126:129]
	v_mfma_f32_16x16x32_bf16 v[122:125], v[162:165], v[202:205], v[122:125]
	v_mfma_f32_16x16x32_bf16 v[110:113], v[154:157], v[218:221], v[110:113]
	v_mfma_f32_16x16x32_bf16 v[106:109], v[162:165], v[218:221], v[106:109]
	v_mfma_f32_16x16x32_bf16 v[94:97], v[154:157], v[226:229], v[94:97]
	v_mfma_f32_16x16x32_bf16 v[90:93], v[162:165], v[226:229], v[90:93]
	v_mfma_f32_16x16x32_bf16 v[82:85], v[154:157], v[234:237], v[82:85]
	v_mfma_f32_16x16x32_bf16 v[74:77], v[162:165], v[234:237], v[74:77]
	v_mfma_f32_16x16x32_bf16 v[118:121], v[166:169], v[198:201], v[118:121]
	v_mfma_f32_16x16x32_bf16 v[114:117], v[190:193], v[198:201], v[114:117]
	v_mfma_f32_16x16x32_bf16 v[102:105], v[166:169], v[206:209], v[102:105]
	v_mfma_f32_16x16x32_bf16 v[98:101], v[190:193], v[206:209], v[98:101]
	v_mfma_f32_16x16x32_bf16 v[86:89], v[166:169], v[222:225], v[86:89]
	v_mfma_f32_16x16x32_bf16 v[78:81], v[190:193], v[222:225], v[78:81]
	v_mfma_f32_16x16x32_bf16 v[70:73], v[166:169], v[230:233], v[70:73]
	v_mfma_f32_16x16x32_bf16 v[66:69], v[190:193], v[230:233], v[66:69]
	v_mfma_f32_16x16x32_bf16 v[118:121], v[170:173], v[202:205], v[118:121]
	v_mfma_f32_16x16x32_bf16 v[114:117], v[194:197], v[202:205], v[114:117]
	v_mfma_f32_16x16x32_bf16 v[102:105], v[170:173], v[218:221], v[102:105]
	v_mfma_f32_16x16x32_bf16 v[98:101], v[194:197], v[218:221], v[98:101]
	v_mfma_f32_16x16x32_bf16 v[86:89], v[170:173], v[226:229], v[86:89]
	v_mfma_f32_16x16x32_bf16 v[78:81], v[194:197], v[226:229], v[78:81]
	v_mfma_f32_16x16x32_bf16 v[70:73], v[170:173], v[234:237], v[70:73]
	v_mfma_f32_16x16x32_bf16 v[66:69], v[194:197], v[234:237], v[66:69]
	s_barrier
	s_add_i32 s20, s8, 0x18000
	s_add_u32 s80, s76, 0x80
	s_addc_u32 s81, s77, 0
	s_mov_b32 m0, s20
	s_nop 0
	global_load_lds_dwordx4 v132, s[80:81]
	s_add_i32 m0, s20, 0x2000
	s_add_u32 s20, s76, 0x40080
	s_addc_u32 s21, s77, 0
	s_add_i32 s12, s8, 0x1c000
	global_load_lds_dwordx4 v136, s[80:81]
	s_mov_b32 m0, s12
	s_nop 0
	global_load_lds_dwordx4 v132, s[20:21]
	s_add_i32 m0, s12, 0x2000
	s_nop 0
	global_load_lds_dwordx4 v136, s[20:21]
	s_mov_b32 m0, s31
	s_nop 0
	global_load_lds_dwordx4 v130, s[100:101]
	s_mov_b32 m0, s34
	s_nop 0
	global_load_lds_dwordx4 v134, s[100:101]
	ds_read_b128 v[198:201], v148 offset:49152
	ds_read_b128 v[202:205], v148 offset:50176
	ds_read_b128 v[206:209], v148 offset:51200
	ds_read_b128 v[218:221], v148 offset:52224
	ds_read_b128 v[222:225], v148 offset:53248
	ds_read_b128 v[226:229], v148 offset:54272
	ds_read_b128 v[230:233], v148 offset:55296
	ds_read_b128 v[234:237], v148 offset:56320
	s_waitcnt vmcnt(8)
	s_waitcnt lgkmcnt(0)
	s_barrier
	s_waitcnt lgkmcnt(0)
	v_mfma_f32_16x16x32_bf16 v[62:65], v[150:153], v[198:201], v[62:65]
	v_mfma_f32_16x16x32_bf16 v[58:61], v[158:161], v[198:201], v[58:61]
	v_mfma_f32_16x16x32_bf16 v[50:53], v[150:153], v[206:209], v[50:53]
	v_mfma_f32_16x16x32_bf16 v[42:45], v[158:161], v[206:209], v[42:45]
	v_mfma_f32_16x16x32_bf16 v[30:33], v[150:153], v[222:225], v[30:33]
	v_mfma_f32_16x16x32_bf16 v[26:29], v[158:161], v[222:225], v[26:29]
	v_mfma_f32_16x16x32_bf16 v[18:21], v[150:153], v[230:233], v[18:21]
	v_mfma_f32_16x16x32_bf16 v[10:13], v[158:161], v[230:233], v[10:13]
	v_mfma_f32_16x16x32_bf16 v[62:65], v[154:157], v[202:205], v[62:65]
	v_mfma_f32_16x16x32_bf16 v[58:61], v[162:165], v[202:205], v[58:61]
	v_mfma_f32_16x16x32_bf16 v[50:53], v[154:157], v[218:221], v[50:53]
	v_mfma_f32_16x16x32_bf16 v[42:45], v[162:165], v[218:221], v[42:45]
	v_mfma_f32_16x16x32_bf16 v[30:33], v[154:157], v[226:229], v[30:33]
	v_mfma_f32_16x16x32_bf16 v[26:29], v[162:165], v[226:229], v[26:29]
	v_mfma_f32_16x16x32_bf16 v[18:21], v[154:157], v[234:237], v[18:21]
	v_mfma_f32_16x16x32_bf16 v[10:13], v[162:165], v[234:237], v[10:13]
	v_mfma_f32_16x16x32_bf16 v[54:57], v[166:169], v[198:201], v[54:57]
	v_mfma_f32_16x16x32_bf16 v[46:49], v[190:193], v[198:201], v[46:49]
	v_mfma_f32_16x16x32_bf16 v[38:41], v[166:169], v[206:209], v[38:41]
	v_mfma_f32_16x16x32_bf16 v[34:37], v[190:193], v[206:209], v[34:37]
	v_mfma_f32_16x16x32_bf16 v[22:25], v[166:169], v[222:225], v[22:25]
	v_mfma_f32_16x16x32_bf16 v[14:17], v[190:193], v[222:225], v[14:17]
	v_mfma_f32_16x16x32_bf16 v[6:9], v[166:169], v[230:233], v[6:9]
	v_mfma_f32_16x16x32_bf16 v[2:5], v[190:193], v[230:233], v[2:5]
	v_mfma_f32_16x16x32_bf16 v[54:57], v[170:173], v[202:205], v[54:57]
	v_mfma_f32_16x16x32_bf16 v[46:49], v[194:197], v[202:205], v[46:49]
	v_mfma_f32_16x16x32_bf16 v[38:41], v[170:173], v[218:221], v[38:41]
	v_mfma_f32_16x16x32_bf16 v[34:37], v[194:197], v[218:221], v[34:37]
	v_mfma_f32_16x16x32_bf16 v[22:25], v[170:173], v[226:229], v[22:25]
	v_mfma_f32_16x16x32_bf16 v[14:17], v[194:197], v[226:229], v[14:17]
	v_mfma_f32_16x16x32_bf16 v[6:9], v[170:173], v[234:237], v[6:9]
	v_mfma_f32_16x16x32_bf16 v[2:5], v[194:197], v[234:237], v[2:5]
	s_barrier
	s_add_i32 s78, s78, 2
	s_add_u32 s18, s18, 0x100
	s_addc_u32 s19, s19, 0
	s_add_u32 s69, s69, 0x100
	s_addc_u32 s71, s71, 0
	s_cmp_gt_u32 s78, 13
	s_cbranch_scc0 .LBB0_349
	s_and_b64 vcc, exec, s[36:37]
	s_cbranch_vccz .LBB0_352
	s_barrier

; #define PG8_STAGE(bufoff, gbase, voff) do { _Pragma("unroll") for (int _i = 0; _i < 2; ++_i) \
;         __builtin_amdgcn_global_load_lds((const unsigned*)((const char*)(gbase) + (voff)[_i]), (LAS unsigned*)(lds + (bufoff) + ldsw + _i * 8192), 16, 0, 0); } while (0)
; #define PG8_LDA(dst, b, h) do { _Pragma("unroll") for (int m = 0; m < 4; ++m) _Pragma("unroll") for (int k = 0; k < 2; ++k) dst[m][k] = *(const LAS bf16x8*)(lds + PG8_SA(b, h) + aoff + m * 2048 + k * 1024); } while (0)
; #define PG8_LDB(dst, b, h) do { _Pragma("unroll") for (int n = 0; n < 2; ++n) _Pragma("unroll") for (int k = 0; k < 2; ++k) dst[n][k] = *(const LAS bf16x8*)(lds + PG8_SB(b, h) + boff + n * 2048 + k * 1024); } while (0)
; #define PG8_MMA(ai, bj, At, Bt) do { __builtin_amdgcn_s_setprio(1); _Pragma("unroll") for (int m = 0; m < 4; ++m) _Pragma("unroll") for (int n = 0; n < 2; ++n) _Pragma("unroll") for (int k = 0; k < 2; ++k) \
;         acc[ai][bj][m][n] = __builtin_amdgcn_mfma_f32_16x16x32_bf16(Bt[n][k], At[m][k], acc[ai][bj][m][n], 0, 0, 0); __builtin_amdgcn_s_setprio(0); } while (0)
; #define PG8_WAIT_V(n) asm volatile("s_waitcnt vmcnt(" #n ")" ::: "memory")
; template <class Epi, class Sched>
; __device__ __forceinline__ void gemm_phase(LAS unsigned char* lds, const Gemm g, const Sched& S, const Epi& E) {
;     ...
;         const char* nA = has_next ? (const char*)g.A + (size_t)nxt.pm * tstepA + (size_t)nxt.pn * g.a_pn_off * 2 : cA; const char* nB = has_next ? (const char*)g.Bt + (size_t)nxt.pn * tstepB : cB;
;         for (int t = 0; t < nt; t += 2) {
;             const bool last = (t == nt - 2);
;             const char* a1 = cA + (size_t)(t + 1) * kstep;
;             const char* a2 = last ? nA : cA + (size_t)(t + 2) * kstep; const char* b2 = last ? nB : cB + (size_t)(t + 2) * kstep;
;             const char* a3 = a2 + kstep; const char* b3 = b2 + kstep;
;             PG8_LDB(B0, 0, 0); PG8_LDB(B1, 0, 1); PG8_SCHED; PG8_LDA(At, 0, 0); PG8_STAGE(PG8_SA(1, 1), a1 + hstepA, voffA);
;             PG8_WAIT_V(8); PG8_WAIT_L(0); PG8_BAR; PG8_MMA(0, 0, At, B0); PG8_MMA(0, 1, At, B1); PG8_BAR; PG8_SCHED;
;             PG8_LDA(At, 0, 1); PG8_STAGE(PG8_SB(0, 0), b2, voffB); PG8_STAGE(PG8_SB(0, 1), b2 + hstepB, voffB); PG8_STAGE(PG8_SA(0, 0), a2, voffA);
;             PG8_WAIT_V(8); PG8_WAIT_L(0); PG8_BAR; PG8_MMA(1, 0, At, B0); PG8_MMA(1, 1, At, B1); PG8_BAR; PG8_SCHED;
.LBB0_377:
	s_ashr_i32 s71, s70, 31
	s_lshl_b64 s[48:49], s[70:71], 19
	v_readlane_b32 s12, v248, 21
	s_add_u32 s72, s12, s48
	v_readlane_b32 s12, v248, 22
	s_addc_u32 s73, s12, s49
	s_and_b64 s[48:49], s[66:67], exec
	s_cselect_b32 s43, s73, s19
	s_cselect_b32 s48, s72, s18
	s_ashr_i32 s69, s68, 31
	s_lshl_b64 s[74:75], s[68:69], 19
	s_add_u32 s74, s4, s74
	s_addc_u32 s75, s5, s75
	s_and_b64 s[76:77], s[66:67], exec
	s_cselect_b32 s49, s75, s21
	s_cselect_b32 s53, s74, s20
	s_add_u32 s18, s18, 0x40080
	s_addc_u32 s19, s19, 0
	s_add_u32 s69, s20, 0x100
	s_addc_u32 s71, s21, 0
	s_mov_b32 s78, -2
	v_add_u32_e32 v255, 0x10000, v158
	s_add_u32 s20, s18, 0xfffc0080
	s_addc_u32 s21, s19, -1
	s_add_i32 s79, 0, 0x10000
	s_cmp_eq_u32 s78, 12
	s_cselect_b32 s21, s43, s21
	s_cselect_b32 s20, s48, s20
	s_cselect_b32 s77, s49, s71
	s_cselect_b32 s76, s53, s69
	s_add_u32 s100, s20, 0x80
	s_addc_u32 s101, s21, 0
	s_add_i32 s82, 0, 0x14000
	s_add_i32 m0, s9, 0xc000
	s_nop 0
	global_load_lds_dwordx4 v146, s[18:19]
	s_add_i32 m0, s9, 0xe000
	s_nop 0
	global_load_lds_dwordx4 v150, s[18:19]
	ds_read_b128 v[130:133], v255
	ds_read_b128 v[134:137], v255 offset:1024
	ds_read_b128 v[138:141], v255 offset:2048
	ds_read_b128 v[142:145], v255 offset:3072
	ds_read_b128 v[162:165], v255 offset:16384
	ds_read_b128 v[166:169], v255 offset:17408
	ds_read_b128 v[170:173], v255 offset:18432
	ds_read_b128 v[190:193], v255 offset:19456
	ds_read_b128 v[194:197], v160
	ds_read_b128 v[198:201], v160 offset:1024
	ds_read_b128 v[202:205], v160 offset:2048
	ds_read_b128 v[206:209], v160 offset:3072
	ds_read_b128 v[218:221], v160 offset:4096
	ds_read_b128 v[222:225], v160 offset:5120
	ds_read_b128 v[226:229], v160 offset:6144
	ds_read_b128 v[230:233], v160 offset:7168
	s_waitcnt vmcnt(8)
	s_waitcnt lgkmcnt(0)
	s_barrier
	s_waitcnt lgkmcnt(0)
	v_mfma_f32_16x16x32_bf16 v[126:129], v[130:133], v[194:197], 0
	v_mfma_f32_16x16x32_bf16 v[122:125], v[138:141], v[194:197], 0
	v_mfma_f32_16x16x32_bf16 v[118:121], v[130:133], v[202:205], 0
	v_mfma_f32_16x16x32_bf16 v[110:113], v[138:141], v[202:205], 0
	v_mfma_f32_16x16x32_bf16 v[102:105], v[130:133], v[218:221], 0
	v_mfma_f32_16x16x32_bf16 v[94:97], v[138:141], v[218:221], 0
	v_mfma_f32_16x16x32_bf16 v[86:89], v[130:133], v[226:229], 0
	v_mfma_f32_16x16x32_bf16 v[78:81], v[138:141], v[226:229], 0
	v_mfma_f32_16x16x32_bf16 v[126:129], v[134:137], v[198:201], v[126:129]
	v_mfma_f32_16x16x32_bf16 v[122:125], v[142:145], v[198:201], v[122:125]
	v_mfma_f32_16x16x32_bf16 v[118:121], v[134:137], v[206:209], v[118:121]
	v_mfma_f32_16x16x32_bf16 v[110:113], v[142:145], v[206:209], v[110:113]
	v_mfma_f32_16x16x32_bf16 v[102:105], v[134:137], v[222:225], v[102:105]
	v_mfma_f32_16x16x32_bf16 v[94:97], v[142:145], v[222:225], v[94:97]
	v_mfma_f32_16x16x32_bf16 v[86:89], v[134:137], v[230:233], v[86:89]
	v_mfma_f32_16x16x32_bf16 v[78:81], v[142:145], v[230:233], v[78:81]
	v_mfma_f32_16x16x32_bf16 v[114:117], v[162:165], v[194:197], 0
	v_mfma_f32_16x16x32_bf16 v[106:109], v[170:173], v[194:197], 0
	v_mfma_f32_16x16x32_bf16 v[98:101], v[162:165], v[202:205], 0
	v_mfma_f32_16x16x32_bf16 v[90:93], v[170:173], v[202:205], 0
	v_mfma_f32_16x16x32_bf16 v[82:85], v[162:165], v[218:221], 0
	v_mfma_f32_16x16x32_bf16 v[74:77], v[170:173], v[218:221], 0
	v_mfma_f32_16x16x32_bf16 v[70:73], v[162:165], v[226:229], 0
	v_mfma_f32_16x16x32_bf16 v[66:69], v[170:173], v[226:229], 0
	v_mfma_f32_16x16x32_bf16 v[114:117], v[166:169], v[198:201], v[114:117]
	v_mfma_f32_16x16x32_bf16 v[106:109], v[190:193], v[198:201], v[106:109]
	v_mfma_f32_16x16x32_bf16 v[98:101], v[166:169], v[206:209], v[98:101]
	v_mfma_f32_16x16x32_bf16 v[90:93], v[190:193], v[206:209], v[90:93]
	v_mfma_f32_16x16x32_bf16 v[82:85], v[166:169], v[222:225], v[82:85]
	v_mfma_f32_16x16x32_bf16 v[74:77], v[190:193], v[222:225], v[74:77]
	v_mfma_f32_16x16x32_bf16 v[70:73], v[166:169], v[230:233], v[70:73]
	v_mfma_f32_16x16x32_bf16 v[66:69], v[190:193], v[230:233], v[66:69]
	s_barrier
	s_add_i32 s79, s79, s8
	s_mov_b32 m0, s79
	s_nop 0
	global_load_lds_dwordx4 v148, s[76:77]
	s_add_i32 m0, s79, 0x2000
	s_add_u32 s80, s76, 0x40000
	s_addc_u32 s81, s77, 0
	s_add_i32 s79, s82, s8
	global_load_lds_dwordx4 v152, s[76:77]
	s_mov_b32 m0, s79
	s_nop 0
	global_load_lds_dwordx4 v148, s[80:81]
	s_add_i32 m0, s79, 0x2000
	s_nop 0
	global_load_lds_dwordx4 v152, s[80:81]
	s_mov_b32 m0, s9
	s_nop 0
	global_load_lds_dwordx4 v146, s[20:21]
	s_mov_b32 m0, s28
	s_nop 0
	global_load_lds_dwordx4 v150, s[20:21]
	ds_read_b128 v[194:197], v160 offset:16384
	ds_read_b128 v[198:201], v160 offset:17408
	ds_read_b128 v[202:205], v160 offset:18432
	ds_read_b128 v[206:209], v160 offset:19456
	ds_read_b128 v[218:221], v160 offset:20480
	ds_read_b128 v[222:225], v160 offset:21504
	ds_read_b128 v[226:229], v160 offset:22528
	ds_read_b128 v[230:233], v160 offset:23552
	s_waitcnt vmcnt(8)
	s_waitcnt lgkmcnt(0)
	s_barrier
; #define PG8_STAGE(bufoff, gbase, voff) do { _Pragma("unroll") for (int _i = 0; _i < 2; ++_i) \
;         __builtin_amdgcn_global_load_lds((const unsigned*)((const char*)(gbase) + (voff)[_i]), (LAS unsigned*)(lds + (bufoff) + ldsw + _i * 8192), 16, 0, 0); } while (0)
; #define PG8_LDA(dst, b, h) do { _Pragma("unroll") for (int m = 0; m < 4; ++m) _Pragma("unroll") for (int k = 0; k < 2; ++k) dst[m][k] = *(const LAS bf16x8*)(lds + PG8_SA(b, h) + aoff + m * 2048 + k * 1024); } while (0)
; #define PG8_LDB(dst, b, h) do { _Pragma("unroll") for (int n = 0; n < 2; ++n) _Pragma("unroll") for (int k = 0; k < 2; ++k) dst[n][k] = *(const LAS bf16x8*)(lds + PG8_SB(b, h) + boff + n * 2048 + k * 1024); } while (0)
; #define PG8_MMA(ai, bj, At, Bt) do { __builtin_amdgcn_s_setprio(1); _Pragma("unroll") for (int m = 0; m < 4; ++m) _Pragma("unroll") for (int n = 0; n < 2; ++n) _Pragma("unroll") for (int k = 0; k < 2; ++k) \
;         acc[ai][bj][m][n] = __builtin_amdgcn_mfma_f32_16x16x32_bf16(Bt[n][k], At[m][k], acc[ai][bj][m][n], 0, 0, 0); __builtin_amdgcn_s_setprio(0); } while (0)
; #define PG8_WAIT_V(n) asm volatile("s_waitcnt vmcnt(" #n ")" ::: "memory")
; #define PG8_WAIT_L(n) asm volatile("s_waitcnt lgkmcnt(" #n ")" ::: "memory")
; #define PG8_BAR __builtin_amdgcn_s_barrier()
; #define PG8_SCHED __builtin_amdgcn_sched_barrier(0)
; template <class Epi, class Sched>
; __device__ __forceinline__ void gemm_phase(LAS unsigned char* lds, const Gemm g, const Sched& S, const Epi& E) {
;     ...
;             PG8_WAIT_V(8); PG8_WAIT_L(0); PG8_BAR; PG8_MMA(1, 0, At, B0); PG8_MMA(1, 1, At, B1); PG8_BAR; PG8_SCHED;
;             PG8_LDB(B0, 1, 0); PG8_LDB(B1, 1, 1); PG8_SCHED; PG8_LDA(At, 1, 0); PG8_STAGE(PG8_SA(0, 1), a2 + hstepA, voffA);
;             PG8_WAIT_V(8); PG8_WAIT_L(0); PG8_BAR; PG8_MMA(0, 0, At, B0); PG8_MMA(0, 1, At, B1); PG8_BAR; PG8_SCHED;
	s_waitcnt lgkmcnt(0)
	v_mfma_f32_16x16x32_bf16 v[62:65], v[130:133], v[194:197], 0
	v_mfma_f32_16x16x32_bf16 v[58:61], v[138:141], v[194:197], 0
	v_mfma_f32_16x16x32_bf16 v[54:57], v[130:133], v[202:205], 0
	v_mfma_f32_16x16x32_bf16 v[46:49], v[138:141], v[202:205], 0
	v_mfma_f32_16x16x32_bf16 v[38:41], v[130:133], v[218:221], 0
	v_mfma_f32_16x16x32_bf16 v[30:33], v[138:141], v[218:221], 0
	v_mfma_f32_16x16x32_bf16 v[22:25], v[130:133], v[226:229], 0
	v_mfma_f32_16x16x32_bf16 v[14:17], v[138:141], v[226:229], 0
	v_mfma_f32_16x16x32_bf16 v[62:65], v[134:137], v[198:201], v[62:65]
	v_mfma_f32_16x16x32_bf16 v[58:61], v[142:145], v[198:201], v[58:61]
	v_mfma_f32_16x16x32_bf16 v[54:57], v[134:137], v[206:209], v[54:57]
	v_mfma_f32_16x16x32_bf16 v[46:49], v[142:145], v[206:209], v[46:49]
	v_mfma_f32_16x16x32_bf16 v[38:41], v[134:137], v[222:225], v[38:41]
	v_mfma_f32_16x16x32_bf16 v[30:33], v[142:145], v[222:225], v[30:33]
	v_mfma_f32_16x16x32_bf16 v[22:25], v[134:137], v[230:233], v[22:25]
	v_mfma_f32_16x16x32_bf16 v[14:17], v[142:145], v[230:233], v[14:17]
	v_mfma_f32_16x16x32_bf16 v[50:53], v[162:165], v[194:197], 0
	v_mfma_f32_16x16x32_bf16 v[42:45], v[170:173], v[194:197], 0
	v_mfma_f32_16x16x32_bf16 v[34:37], v[162:165], v[202:205], 0
	v_mfma_f32_16x16x32_bf16 v[26:29], v[170:173], v[202:205], 0
	v_mfma_f32_16x16x32_bf16 v[18:21], v[162:165], v[218:221], 0
	v_mfma_f32_16x16x32_bf16 v[10:13], v[170:173], v[218:221], 0
	v_mfma_f32_16x16x32_bf16 v[6:9], v[162:165], v[226:229], 0
	v_mfma_f32_16x16x32_bf16 v[2:5], v[170:173], v[226:229], 0
	v_mfma_f32_16x16x32_bf16 v[50:53], v[166:169], v[198:201], v[50:53]
	v_mfma_f32_16x16x32_bf16 v[42:45], v[190:193], v[198:201], v[42:45]
	v_mfma_f32_16x16x32_bf16 v[34:37], v[166:169], v[206:209], v[34:37]
	v_mfma_f32_16x16x32_bf16 v[26:29], v[190:193], v[206:209], v[26:29]
	v_mfma_f32_16x16x32_bf16 v[18:21], v[166:169], v[222:225], v[18:21]
	v_mfma_f32_16x16x32_bf16 v[10:13], v[190:193], v[222:225], v[10:13]
	v_mfma_f32_16x16x32_bf16 v[6:9], v[166:169], v[230:233], v[6:9]
	v_mfma_f32_16x16x32_bf16 v[2:5], v[190:193], v[230:233], v[2:5]
	s_barrier
	s_add_i32 s79, 0, 0x18000
	s_add_i32 s80, 0, 0x1c000
	s_add_u32 s20, s20, 0x40000
	s_addc_u32 s21, s21, 0
	s_mov_b32 m0, s29
	s_nop 0
	global_load_lds_dwordx4 v146, s[20:21]
	s_mov_b32 m0, s30
	s_nop 0
	global_load_lds_dwordx4 v150, s[20:21]
	ds_read_b128 v[130:133], v255 offset:32768
	ds_read_b128 v[134:137], v255 offset:33792
	ds_read_b128 v[138:141], v255 offset:34816
	ds_read_b128 v[142:145], v255 offset:35840
	ds_read_b128 v[162:165], v255 offset:49152
	ds_read_b128 v[166:169], v255 offset:50176
	ds_read_b128 v[170:173], v255 offset:51200
	ds_read_b128 v[190:193], v255 offset:52224
	ds_read_b128 v[194:197], v160 offset:32768
	ds_read_b128 v[198:201], v160 offset:33792
	ds_read_b128 v[202:205], v160 offset:34816
	ds_read_b128 v[206:209], v160 offset:35840
	ds_read_b128 v[218:221], v160 offset:36864
	ds_read_b128 v[222:225], v160 offset:37888
	ds_read_b128 v[226:229], v160 offset:38912
	ds_read_b128 v[230:233], v160 offset:39936
	s_waitcnt vmcnt(8)
	s_waitcnt lgkmcnt(0)
	s_barrier
	s_waitcnt lgkmcnt(0)
	v_mfma_f32_16x16x32_bf16 v[126:129], v[130:133], v[194:197], v[126:129]
	v_mfma_f32_16x16x32_bf16 v[122:125], v[138:141], v[194:197], v[122:125]
	v_mfma_f32_16x16x32_bf16 v[118:121], v[130:133], v[202:205], v[118:121]
	v_mfma_f32_16x16x32_bf16 v[110:113], v[138:141], v[202:205], v[110:113]
	v_mfma_f32_16x16x32_bf16 v[102:105], v[130:133], v[218:221], v[102:105]
	v_mfma_f32_16x16x32_bf16 v[94:97], v[138:141], v[218:221], v[94:97]
	v_mfma_f32_16x16x32_bf16 v[86:89], v[130:133], v[226:229], v[86:89]
	v_mfma_f32_16x16x32_bf16 v[78:81], v[138:141], v[226:229], v[78:81]
	v_mfma_f32_16x16x32_bf16 v[126:129], v[134:137], v[198:201], v[126:129]
	v_mfma_f32_16x16x32_bf16 v[122:125], v[142:145], v[198:201], v[122:125]
	v_mfma_f32_16x16x32_bf16 v[118:121], v[134:137], v[206:209], v[118:121]
	v_mfma_f32_16x16x32_bf16 v[110:113], v[142:145], v[206:209], v[110:113]
	v_mfma_f32_16x16x32_bf16 v[102:105], v[134:137], v[222:225], v[102:105]
	v_mfma_f32_16x16x32_bf16 v[94:97], v[142:145], v[222:225], v[94:97]
	v_mfma_f32_16x16x32_bf16 v[86:89], v[134:137], v[230:233], v[86:89]
	v_mfma_f32_16x16x32_bf16 v[78:81], v[142:145], v[230:233], v[78:81]
	v_mfma_f32_16x16x32_bf16 v[114:117], v[162:165], v[194:197], v[114:117]
	v_mfma_f32_16x16x32_bf16 v[106:109], v[170:173], v[194:197], v[106:109]
	v_mfma_f32_16x16x32_bf16 v[98:101], v[162:165], v[202:205], v[98:101]
	v_mfma_f32_16x16x32_bf16 v[90:93], v[170:173], v[202:205], v[90:93]
	v_mfma_f32_16x16x32_bf16 v[82:85], v[162:165], v[218:221], v[82:85]
	v_mfma_f32_16x16x32_bf16 v[74:77], v[170:173], v[218:221], v[74:77]
	v_mfma_f32_16x16x32_bf16 v[70:73], v[162:165], v[226:229], v[70:73]
	v_mfma_f32_16x16x32_bf16 v[66:69], v[170:173], v[226:229], v[66:69]
	v_mfma_f32_16x16x32_bf16 v[114:117], v[166:169], v[198:201], v[114:117]
	v_mfma_f32_16x16x32_bf16 v[106:109], v[190:193], v[198:201], v[106:109]
	v_mfma_f32_16x16x32_bf16 v[98:101], v[166:169], v[206:209], v[98:101]
	v_mfma_f32_16x16x32_bf16 v[90:93], v[190:193], v[206:209], v[90:93]
	v_mfma_f32_16x16x32_bf16 v[82:85], v[166:169], v[222:225], v[82:85]
	v_mfma_f32_16x16x32_bf16 v[74:77], v[190:193], v[222:225], v[74:77]
	v_mfma_f32_16x16x32_bf16 v[70:73], v[166:169], v[230:233], v[70:73]
	v_mfma_f32_16x16x32_bf16 v[66:69], v[190:193], v[230:233], v[66:69]
	s_barrier
; #define PG8_STAGE(bufoff, gbase, voff) do { _Pragma("unroll") for (int _i = 0; _i < 2; ++_i) \
;         __builtin_amdgcn_global_load_lds((const unsigned*)((const char*)(gbase) + (voff)[_i]), (LAS unsigned*)(lds + (bufoff) + ldsw + _i * 8192), 16, 0, 0); } while (0)
; #define PG8_LDA(dst, b, h) do { _Pragma("unroll") for (int m = 0; m < 4; ++m) _Pragma("unroll") for (int k = 0; k < 2; ++k) dst[m][k] = *(const LAS bf16x8*)(lds + PG8_SA(b, h) + aoff + m * 2048 + k * 1024); } while (0)
; #define PG8_LDB(dst, b, h) do { _Pragma("unroll") for (int n = 0; n < 2; ++n) _Pragma("unroll") for (int k = 0; k < 2; ++k) dst[n][k] = *(const LAS bf16x8*)(lds + PG8_SB(b, h) + boff + n * 2048 + k * 1024); } while (0)
; #define PG8_WAIT_V(n) asm volatile("s_waitcnt vmcnt(" #n ")" ::: "memory")
; #define PG8_WAIT_L(n) asm volatile("s_waitcnt lgkmcnt(" #n ")" ::: "memory")
; template <class Epi, class Sched>
; __device__ __forceinline__ void gemm_phase(LAS unsigned char* lds, const Gemm g, const Sched& S, const Epi& E) {
;     ...
;             const bool last = (t == nt - 2);
;             const char* a1 = cA + (size_t)(t + 1) * kstep;
;             const char* a2 = last ? nA : cA + (size_t)(t + 2) * kstep; const char* b2 = last ? nB : cB + (size_t)(t + 2) * kstep;
;             const char* a3 = a2 + kstep; const char* b3 = b2 + kstep;
;             PG8_LDB(B0, 0, 0); PG8_LDB(B1, 0, 1); PG8_SCHED; PG8_LDA(At, 0, 0); PG8_STAGE(PG8_SA(1, 1), a1 + hstepA, voffA);
;             PG8_WAIT_V(8); PG8_WAIT_L(0); PG8_BAR; PG8_MMA(0, 0, At, B0); PG8_MMA(0, 1, At, B1); PG8_BAR; PG8_SCHED;
;             PG8_LDA(At, 0, 1); PG8_STAGE(PG8_SB(0, 0), b2, voffB); PG8_STAGE(PG8_SB(0, 1), b2 + hstepB, voffB); PG8_STAGE(PG8_SA(0, 0), a2, voffA);
;             PG8_WAIT_V(8); PG8_WAIT_L(0); PG8_BAR; PG8_MMA(1, 0, At, B0); PG8_MMA(1, 1, At, B1); PG8_BAR; PG8_SCHED;
;             PG8_LDB(B0, 1, 0); PG8_LDB(B1, 1, 1); PG8_SCHED; PG8_LDA(At, 1, 0); PG8_STAGE(PG8_SA(0, 1), a2 + hstepA, voffA);
;             PG8_WAIT_V(8); PG8_WAIT_L(0); PG8_BAR; PG8_MMA(0, 0, At, B0); PG8_MMA(0, 1, At, B1); PG8_BAR; PG8_SCHED;
;             PG8_LDA(At, 1, 1); PG8_STAGE(PG8_SB(1, 0), b3, voffB); PG8_STAGE(PG8_SB(1, 1), b3 + hstepB, voffB); PG8_STAGE(PG8_SA(1, 0), a3, voffA);
;             PG8_WAIT_V(8); PG8_WAIT_L(0); PG8_BAR; PG8_MMA(1, 0, At, B0); PG8_MMA(1, 1, At, B1); PG8_BAR; PG8_SCHED;
	s_add_i32 s20, s8, 0x18000
	s_add_u32 s80, s76, 0x80
	s_addc_u32 s81, s77, 0
	s_mov_b32 m0, s20
	s_nop 0
	global_load_lds_dwordx4 v148, s[80:81]
	s_add_i32 m0, s20, 0x2000
	s_add_u32 s20, s76, 0x40080
	s_addc_u32 s21, s77, 0
	s_add_i32 s12, s8, 0x1c000
	global_load_lds_dwordx4 v152, s[80:81]
	s_mov_b32 m0, s12
	s_nop 0
	global_load_lds_dwordx4 v148, s[20:21]
	s_add_i32 m0, s12, 0x2000
	s_nop 0
	global_load_lds_dwordx4 v152, s[20:21]
	s_mov_b32 m0, s31
	s_nop 0
	global_load_lds_dwordx4 v146, s[100:101]
	s_mov_b32 m0, s34
	s_nop 0
	global_load_lds_dwordx4 v150, s[100:101]
	ds_read_b128 v[194:197], v160 offset:49152
	ds_read_b128 v[198:201], v160 offset:50176
	ds_read_b128 v[202:205], v160 offset:51200
	ds_read_b128 v[206:209], v160 offset:52224
	ds_read_b128 v[218:221], v160 offset:53248
	ds_read_b128 v[222:225], v160 offset:54272
	ds_read_b128 v[226:229], v160 offset:55296
	ds_read_b128 v[230:233], v160 offset:56320
	s_waitcnt vmcnt(8)
	s_waitcnt lgkmcnt(0)
	s_barrier
	s_waitcnt lgkmcnt(0)
	v_mfma_f32_16x16x32_bf16 v[62:65], v[130:133], v[194:197], v[62:65]
	v_mfma_f32_16x16x32_bf16 v[58:61], v[138:141], v[194:197], v[58:61]
	v_mfma_f32_16x16x32_bf16 v[54:57], v[130:133], v[202:205], v[54:57]
	v_mfma_f32_16x16x32_bf16 v[46:49], v[138:141], v[202:205], v[46:49]
	v_mfma_f32_16x16x32_bf16 v[38:41], v[130:133], v[218:221], v[38:41]
	v_mfma_f32_16x16x32_bf16 v[30:33], v[138:141], v[218:221], v[30:33]
	v_mfma_f32_16x16x32_bf16 v[22:25], v[130:133], v[226:229], v[22:25]
	v_mfma_f32_16x16x32_bf16 v[14:17], v[138:141], v[226:229], v[14:17]
	v_mfma_f32_16x16x32_bf16 v[62:65], v[134:137], v[198:201], v[62:65]
	v_mfma_f32_16x16x32_bf16 v[58:61], v[142:145], v[198:201], v[58:61]
	v_mfma_f32_16x16x32_bf16 v[54:57], v[134:137], v[206:209], v[54:57]
	v_mfma_f32_16x16x32_bf16 v[46:49], v[142:145], v[206:209], v[46:49]
	v_mfma_f32_16x16x32_bf16 v[38:41], v[134:137], v[222:225], v[38:41]
	v_mfma_f32_16x16x32_bf16 v[30:33], v[142:145], v[222:225], v[30:33]
	v_mfma_f32_16x16x32_bf16 v[22:25], v[134:137], v[230:233], v[22:25]
	v_mfma_f32_16x16x32_bf16 v[14:17], v[142:145], v[230:233], v[14:17]
	v_mfma_f32_16x16x32_bf16 v[50:53], v[162:165], v[194:197], v[50:53]
	v_mfma_f32_16x16x32_bf16 v[42:45], v[170:173], v[194:197], v[42:45]
	v_mfma_f32_16x16x32_bf16 v[34:37], v[162:165], v[202:205], v[34:37]
	v_mfma_f32_16x16x32_bf16 v[26:29], v[170:173], v[202:205], v[26:29]
	v_mfma_f32_16x16x32_bf16 v[18:21], v[162:165], v[218:221], v[18:21]
	v_mfma_f32_16x16x32_bf16 v[10:13], v[170:173], v[218:221], v[10:13]
	v_mfma_f32_16x16x32_bf16 v[6:9], v[162:165], v[226:229], v[6:9]
	v_mfma_f32_16x16x32_bf16 v[2:5], v[170:173], v[226:229], v[2:5]
	v_mfma_f32_16x16x32_bf16 v[50:53], v[166:169], v[198:201], v[50:53]
	v_mfma_f32_16x16x32_bf16 v[42:45], v[190:193], v[198:201], v[42:45]
	v_mfma_f32_16x16x32_bf16 v[34:37], v[166:169], v[206:209], v[34:37]
	v_mfma_f32_16x16x32_bf16 v[26:29], v[190:193], v[206:209], v[26:29]
	v_mfma_f32_16x16x32_bf16 v[18:21], v[166:169], v[222:225], v[18:21]
	v_mfma_f32_16x16x32_bf16 v[10:13], v[190:193], v[222:225], v[10:13]
	v_mfma_f32_16x16x32_bf16 v[6:9], v[166:169], v[230:233], v[6:9]
	v_mfma_f32_16x16x32_bf16 v[2:5], v[190:193], v[230:233], v[2:5]
	s_barrier
	s_add_i32 s78, s78, 2
	s_add_u32 s18, s18, 0x100
	s_addc_u32 s19, s19, 0
	s_add_u32 s69, s69, 0x100
	s_addc_u32 s71, s71, 0
	s_cmp_gt_u32 s78, 13
.LBB0_378:
	s_add_u32 s20, s18, 0xfffc0080
	s_addc_u32 s21, s19, -1
	s_add_i32 s79, 0, 0x10000
	s_cmp_eq_u32 s78, 12
	s_cselect_b32 s21, s43, s21
	s_cselect_b32 s20, s48, s20
	s_cselect_b32 s77, s49, s71
	s_cselect_b32 s76, s53, s69
	s_add_u32 s100, s20, 0x80
	s_addc_u32 s101, s21, 0
	s_add_i32 s82, 0, 0x14000
	s_add_i32 m0, s9, 0xc000
	s_nop 0
	global_load_lds_dwordx4 v146, s[18:19]
	s_add_i32 m0, s9, 0xe000
	s_nop 0
	global_load_lds_dwordx4 v150, s[18:19]
	ds_read_b128 v[130:133], v255
	ds_read_b128 v[134:137], v255 offset:1024
	ds_read_b128 v[138:141], v255 offset:2048
	ds_read_b128 v[142:145], v255 offset:3072
	ds_read_b128 v[162:165], v255 offset:16384
	ds_read_b128 v[166:169], v255 offset:17408
	ds_read_b128 v[170:173], v255 offset:18432
	ds_read_b128 v[190:193], v255 offset:19456
	ds_read_b128 v[194:197], v160
	ds_read_b128 v[198:201], v160 offset:1024
	ds_read_b128 v[202:205], v160 offset:2048
	ds_read_b128 v[206:209], v160 offset:3072
	ds_read_b128 v[218:221], v160 offset:4096
	ds_read_b128 v[222:225], v160 offset:5120
	ds_read_b128 v[226:229], v160 offset:6144
	ds_read_b128 v[230:233], v160 offset:7168
	s_waitcnt vmcnt(8)
	s_waitcnt lgkmcnt(0)
	s_barrier
; #define PG8_STAGE(bufoff, gbase, voff) do { _Pragma("unroll") for (int _i = 0; _i < 2; ++_i) \
;         __builtin_amdgcn_global_load_lds((const unsigned*)((const char*)(gbase) + (voff)[_i]), (LAS unsigned*)(lds + (bufoff) + ldsw + _i * 8192), 16, 0, 0); } while (0)
; #define PG8_LDA(dst, b, h) do { _Pragma("unroll") for (int m = 0; m < 4; ++m) _Pragma("unroll") for (int k = 0; k < 2; ++k) dst[m][k] = *(const LAS bf16x8*)(lds + PG8_SA(b, h) + aoff + m * 2048 + k * 1024); } while (0)
; #define PG8_MMA(ai, bj, At, Bt) do { __builtin_amdgcn_s_setprio(1); _Pragma("unroll") for (int m = 0; m < 4; ++m) _Pragma("unroll") for (int n = 0; n < 2; ++n) _Pragma("unroll") for (int k = 0; k < 2; ++k) \
;         acc[ai][bj][m][n] = __builtin_amdgcn_mfma_f32_16x16x32_bf16(Bt[n][k], At[m][k], acc[ai][bj][m][n], 0, 0, 0); __builtin_amdgcn_s_setprio(0); } while (0)
; #define PG8_WAIT_V(n) asm volatile("s_waitcnt vmcnt(" #n ")" ::: "memory")
; #define PG8_WAIT_L(n) asm volatile("s_waitcnt lgkmcnt(" #n ")" ::: "memory")
; #define PG8_BAR __builtin_amdgcn_s_barrier()
; #define PG8_SCHED __builtin_amdgcn_sched_barrier(0)
; template <class Epi, class Sched>
; __device__ __forceinline__ void gemm_phase(LAS unsigned char* lds, const Gemm g, const Sched& S, const Epi& E) {
;     ...
;             PG8_WAIT_V(8); PG8_WAIT_L(0); PG8_BAR; PG8_MMA(0, 0, At, B0); PG8_MMA(0, 1, At, B1); PG8_BAR; PG8_SCHED;
;             PG8_LDA(At, 0, 1); PG8_STAGE(PG8_SB(0, 0), b2, voffB); PG8_STAGE(PG8_SB(0, 1), b2 + hstepB, voffB); PG8_STAGE(PG8_SA(0, 0), a2, voffA);
;             PG8_WAIT_V(8); PG8_WAIT_L(0); PG8_BAR; PG8_MMA(1, 0, At, B0); PG8_MMA(1, 1, At, B1); PG8_BAR; PG8_SCHED;
	s_waitcnt lgkmcnt(0)
	v_mfma_f32_16x16x32_bf16 v[126:129], v[130:133], v[194:197], v[126:129]
	v_mfma_f32_16x16x32_bf16 v[122:125], v[138:141], v[194:197], v[122:125]
	v_mfma_f32_16x16x32_bf16 v[118:121], v[130:133], v[202:205], v[118:121]
	v_mfma_f32_16x16x32_bf16 v[110:113], v[138:141], v[202:205], v[110:113]
	v_mfma_f32_16x16x32_bf16 v[102:105], v[130:133], v[218:221], v[102:105]
	v_mfma_f32_16x16x32_bf16 v[94:97], v[138:141], v[218:221], v[94:97]
	v_mfma_f32_16x16x32_bf16 v[86:89], v[130:133], v[226:229], v[86:89]
	v_mfma_f32_16x16x32_bf16 v[78:81], v[138:141], v[226:229], v[78:81]
	v_mfma_f32_16x16x32_bf16 v[126:129], v[134:137], v[198:201], v[126:129]
	v_mfma_f32_16x16x32_bf16 v[122:125], v[142:145], v[198:201], v[122:125]
	v_mfma_f32_16x16x32_bf16 v[118:121], v[134:137], v[206:209], v[118:121]
	v_mfma_f32_16x16x32_bf16 v[110:113], v[142:145], v[206:209], v[110:113]
	v_mfma_f32_16x16x32_bf16 v[102:105], v[134:137], v[222:225], v[102:105]
	v_mfma_f32_16x16x32_bf16 v[94:97], v[142:145], v[222:225], v[94:97]
	v_mfma_f32_16x16x32_bf16 v[86:89], v[134:137], v[230:233], v[86:89]
	v_mfma_f32_16x16x32_bf16 v[78:81], v[142:145], v[230:233], v[78:81]
	v_mfma_f32_16x16x32_bf16 v[114:117], v[162:165], v[194:197], v[114:117]
	v_mfma_f32_16x16x32_bf16 v[106:109], v[170:173], v[194:197], v[106:109]
	v_mfma_f32_16x16x32_bf16 v[98:101], v[162:165], v[202:205], v[98:101]
	v_mfma_f32_16x16x32_bf16 v[90:93], v[170:173], v[202:205], v[90:93]
	v_mfma_f32_16x16x32_bf16 v[82:85], v[162:165], v[218:221], v[82:85]
	v_mfma_f32_16x16x32_bf16 v[74:77], v[170:173], v[218:221], v[74:77]
	v_mfma_f32_16x16x32_bf16 v[70:73], v[162:165], v[226:229], v[70:73]
	v_mfma_f32_16x16x32_bf16 v[66:69], v[170:173], v[226:229], v[66:69]
	v_mfma_f32_16x16x32_bf16 v[114:117], v[166:169], v[198:201], v[114:117]
	v_mfma_f32_16x16x32_bf16 v[106:109], v[190:193], v[198:201], v[106:109]
	v_mfma_f32_16x16x32_bf16 v[98:101], v[166:169], v[206:209], v[98:101]
	v_mfma_f32_16x16x32_bf16 v[90:93], v[190:193], v[206:209], v[90:93]
	v_mfma_f32_16x16x32_bf16 v[82:85], v[166:169], v[222:225], v[82:85]
	v_mfma_f32_16x16x32_bf16 v[74:77], v[190:193], v[222:225], v[74:77]
	v_mfma_f32_16x16x32_bf16 v[70:73], v[166:169], v[230:233], v[70:73]
	v_mfma_f32_16x16x32_bf16 v[66:69], v[190:193], v[230:233], v[66:69]
	s_barrier
	s_add_i32 s79, s79, s8
	s_mov_b32 m0, s79
	s_nop 0
	global_load_lds_dwordx4 v148, s[76:77]
	s_add_i32 m0, s79, 0x2000
	s_add_u32 s80, s76, 0x40000
	s_addc_u32 s81, s77, 0
	s_add_i32 s79, s82, s8
	global_load_lds_dwordx4 v152, s[76:77]
	s_mov_b32 m0, s79
	s_nop 0
	global_load_lds_dwordx4 v148, s[80:81]
	s_add_i32 m0, s79, 0x2000
	s_nop 0
	global_load_lds_dwordx4 v152, s[80:81]
	s_mov_b32 m0, s9
	s_nop 0
	global_load_lds_dwordx4 v146, s[20:21]
	s_mov_b32 m0, s28
	s_nop 0
	global_load_lds_dwordx4 v150, s[20:21]
	ds_read_b128 v[194:197], v160 offset:16384
	ds_read_b128 v[198:201], v160 offset:17408
	ds_read_b128 v[202:205], v160 offset:18432
	ds_read_b128 v[206:209], v160 offset:19456
	ds_read_b128 v[218:221], v160 offset:20480
	ds_read_b128 v[222:225], v160 offset:21504
	ds_read_b128 v[226:229], v160 offset:22528
	ds_read_b128 v[230:233], v160 offset:23552
	s_waitcnt vmcnt(8)
	s_waitcnt lgkmcnt(0)
	s_barrier
	s_waitcnt lgkmcnt(0)
	v_mfma_f32_16x16x32_bf16 v[62:65], v[130:133], v[194:197], v[62:65]
	v_mfma_f32_16x16x32_bf16 v[58:61], v[138:141], v[194:197], v[58:61]
	v_mfma_f32_16x16x32_bf16 v[54:57], v[130:133], v[202:205], v[54:57]
	v_mfma_f32_16x16x32_bf16 v[46:49], v[138:141], v[202:205], v[46:49]
	v_mfma_f32_16x16x32_bf16 v[38:41], v[130:133], v[218:221], v[38:41]
	v_mfma_f32_16x16x32_bf16 v[30:33], v[138:141], v[218:221], v[30:33]
	v_mfma_f32_16x16x32_bf16 v[22:25], v[130:133], v[226:229], v[22:25]
	v_mfma_f32_16x16x32_bf16 v[14:17], v[138:141], v[226:229], v[14:17]
	v_mfma_f32_16x16x32_bf16 v[62:65], v[134:137], v[198:201], v[62:65]
	v_mfma_f32_16x16x32_bf16 v[58:61], v[142:145], v[198:201], v[58:61]
	v_mfma_f32_16x16x32_bf16 v[54:57], v[134:137], v[206:209], v[54:57]
	v_mfma_f32_16x16x32_bf16 v[46:49], v[142:145], v[206:209], v[46:49]
	v_mfma_f32_16x16x32_bf16 v[38:41], v[134:137], v[222:225], v[38:41]
	v_mfma_f32_16x16x32_bf16 v[30:33], v[142:145], v[222:225], v[30:33]
	v_mfma_f32_16x16x32_bf16 v[22:25], v[134:137], v[230:233], v[22:25]
	v_mfma_f32_16x16x32_bf16 v[14:17], v[142:145], v[230:233], v[14:17]
	v_mfma_f32_16x16x32_bf16 v[50:53], v[162:165], v[194:197], v[50:53]
	v_mfma_f32_16x16x32_bf16 v[42:45], v[170:173], v[194:197], v[42:45]
	v_mfma_f32_16x16x32_bf16 v[34:37], v[162:165], v[202:205], v[34:37]
	v_mfma_f32_16x16x32_bf16 v[26:29], v[170:173], v[202:205], v[26:29]
	v_mfma_f32_16x16x32_bf16 v[18:21], v[162:165], v[218:221], v[18:21]
	v_mfma_f32_16x16x32_bf16 v[10:13], v[170:173], v[218:221], v[10:13]
	v_mfma_f32_16x16x32_bf16 v[6:9], v[162:165], v[226:229], v[6:9]
	v_mfma_f32_16x16x32_bf16 v[2:5], v[170:173], v[226:229], v[2:5]
	v_mfma_f32_16x16x32_bf16 v[50:53], v[166:169], v[198:201], v[50:53]
	v_mfma_f32_16x16x32_bf16 v[42:45], v[190:193], v[198:201], v[42:45]
	v_mfma_f32_16x16x32_bf16 v[34:37], v[166:169], v[206:209], v[34:37]
	v_mfma_f32_16x16x32_bf16 v[26:29], v[190:193], v[206:209], v[26:29]
	v_mfma_f32_16x16x32_bf16 v[18:21], v[166:169], v[222:225], v[18:21]
	v_mfma_f32_16x16x32_bf16 v[10:13], v[190:193], v[222:225], v[10:13]
	v_mfma_f32_16x16x32_bf16 v[6:9], v[166:169], v[230:233], v[6:9]
	v_mfma_f32_16x16x32_bf16 v[2:5], v[190:193], v[230:233], v[2:5]
	s_barrier
; #define PG8_STAGE(bufoff, gbase, voff) do { _Pragma("unroll") for (int _i = 0; _i < 2; ++_i) \
;         __builtin_amdgcn_global_load_lds((const unsigned*)((const char*)(gbase) + (voff)[_i]), (LAS unsigned*)(lds + (bufoff) + ldsw + _i * 8192), 16, 0, 0); } while (0)
; #define PG8_LDA(dst, b, h) do { _Pragma("unroll") for (int m = 0; m < 4; ++m) _Pragma("unroll") for (int k = 0; k < 2; ++k) dst[m][k] = *(const LAS bf16x8*)(lds + PG8_SA(b, h) + aoff + m * 2048 + k * 1024); } while (0)
; #define PG8_LDB(dst, b, h) do { _Pragma("unroll") for (int n = 0; n < 2; ++n) _Pragma("unroll") for (int k = 0; k < 2; ++k) dst[n][k] = *(const LAS bf16x8*)(lds + PG8_SB(b, h) + boff + n * 2048 + k * 1024); } while (0)
; #define PG8_MMA(ai, bj, At, Bt) do { __builtin_amdgcn_s_setprio(1); _Pragma("unroll") for (int m = 0; m < 4; ++m) _Pragma("unroll") for (int n = 0; n < 2; ++n) _Pragma("unroll") for (int k = 0; k < 2; ++k) \
;         acc[ai][bj][m][n] = __builtin_amdgcn_mfma_f32_16x16x32_bf16(Bt[n][k], At[m][k], acc[ai][bj][m][n], 0, 0, 0); __builtin_amdgcn_s_setprio(0); } while (0)
; #define PG8_WAIT_V(n) asm volatile("s_waitcnt vmcnt(" #n ")" ::: "memory")
; #define PG8_WAIT_L(n) asm volatile("s_waitcnt lgkmcnt(" #n ")" ::: "memory")
; #define PG8_BAR __builtin_amdgcn_s_barrier()
; #define PG8_SCHED __builtin_amdgcn_sched_barrier(0)
; template <class Epi, class Sched>
; __device__ __forceinline__ void gemm_phase(LAS unsigned char* lds, const Gemm g, const Sched& S, const Epi& E) {
;     ...
;             PG8_LDB(B0, 1, 0); PG8_LDB(B1, 1, 1); PG8_SCHED; PG8_LDA(At, 1, 0); PG8_STAGE(PG8_SA(0, 1), a2 + hstepA, voffA);
;             PG8_WAIT_V(8); PG8_WAIT_L(0); PG8_BAR; PG8_MMA(0, 0, At, B0); PG8_MMA(0, 1, At, B1); PG8_BAR; PG8_SCHED;
;             PG8_LDA(At, 1, 1); PG8_STAGE(PG8_SB(1, 0), b3, voffB); PG8_STAGE(PG8_SB(1, 1), b3 + hstepB, voffB); PG8_STAGE(PG8_SA(1, 0), a3, voffA);
;             PG8_WAIT_V(8); PG8_WAIT_L(0); PG8_BAR; PG8_MMA(1, 0, At, B0); PG8_MMA(1, 1, At, B1); PG8_BAR; PG8_SCHED;
;         }
;         if (wr == 0) PG8_BAR;
	s_add_i32 s79, 0, 0x18000
	s_add_i32 s80, 0, 0x1c000
	s_add_u32 s20, s20, 0x40000
	s_addc_u32 s21, s21, 0
	s_mov_b32 m0, s29
	s_nop 0
	global_load_lds_dwordx4 v146, s[20:21]
	s_mov_b32 m0, s30
	s_nop 0
	global_load_lds_dwordx4 v150, s[20:21]
	ds_read_b128 v[130:133], v255 offset:32768
	ds_read_b128 v[134:137], v255 offset:33792
	ds_read_b128 v[138:141], v255 offset:34816
	ds_read_b128 v[142:145], v255 offset:35840
	ds_read_b128 v[162:165], v255 offset:49152
	ds_read_b128 v[166:169], v255 offset:50176
	ds_read_b128 v[170:173], v255 offset:51200
	ds_read_b128 v[190:193], v255 offset:52224
	ds_read_b128 v[194:197], v160 offset:32768
	ds_read_b128 v[198:201], v160 offset:33792
	ds_read_b128 v[202:205], v160 offset:34816
	ds_read_b128 v[206:209], v160 offset:35840
	ds_read_b128 v[218:221], v160 offset:36864
	ds_read_b128 v[222:225], v160 offset:37888
	ds_read_b128 v[226:229], v160 offset:38912
	ds_read_b128 v[230:233], v160 offset:39936
	s_waitcnt vmcnt(8)
	s_waitcnt lgkmcnt(0)
	s_barrier
	s_waitcnt lgkmcnt(0)
	v_mfma_f32_16x16x32_bf16 v[126:129], v[130:133], v[194:197], v[126:129]
	v_mfma_f32_16x16x32_bf16 v[122:125], v[138:141], v[194:197], v[122:125]
	v_mfma_f32_16x16x32_bf16 v[118:121], v[130:133], v[202:205], v[118:121]
	v_mfma_f32_16x16x32_bf16 v[110:113], v[138:141], v[202:205], v[110:113]
	v_mfma_f32_16x16x32_bf16 v[102:105], v[130:133], v[218:221], v[102:105]
	v_mfma_f32_16x16x32_bf16 v[94:97], v[138:141], v[218:221], v[94:97]
	v_mfma_f32_16x16x32_bf16 v[86:89], v[130:133], v[226:229], v[86:89]
	v_mfma_f32_16x16x32_bf16 v[78:81], v[138:141], v[226:229], v[78:81]
	v_mfma_f32_16x16x32_bf16 v[126:129], v[134:137], v[198:201], v[126:129]
	v_mfma_f32_16x16x32_bf16 v[122:125], v[142:145], v[198:201], v[122:125]
	v_mfma_f32_16x16x32_bf16 v[118:121], v[134:137], v[206:209], v[118:121]
	v_mfma_f32_16x16x32_bf16 v[110:113], v[142:145], v[206:209], v[110:113]
	v_mfma_f32_16x16x32_bf16 v[102:105], v[134:137], v[222:225], v[102:105]
	v_mfma_f32_16x16x32_bf16 v[94:97], v[142:145], v[222:225], v[94:97]
	v_mfma_f32_16x16x32_bf16 v[86:89], v[134:137], v[230:233], v[86:89]
	v_mfma_f32_16x16x32_bf16 v[78:81], v[142:145], v[230:233], v[78:81]
	v_mfma_f32_16x16x32_bf16 v[114:117], v[162:165], v[194:197], v[114:117]
	v_mfma_f32_16x16x32_bf16 v[106:109], v[170:173], v[194:197], v[106:109]
	v_mfma_f32_16x16x32_bf16 v[98:101], v[162:165], v[202:205], v[98:101]
	v_mfma_f32_16x16x32_bf16 v[90:93], v[170:173], v[202:205], v[90:93]
	v_mfma_f32_16x16x32_bf16 v[82:85], v[162:165], v[218:221], v[82:85]
	v_mfma_f32_16x16x32_bf16 v[74:77], v[170:173], v[218:221], v[74:77]
	v_mfma_f32_16x16x32_bf16 v[70:73], v[162:165], v[226:229], v[70:73]
	v_mfma_f32_16x16x32_bf16 v[66:69], v[170:173], v[226:229], v[66:69]
	v_mfma_f32_16x16x32_bf16 v[114:117], v[166:169], v[198:201], v[114:117]
	v_mfma_f32_16x16x32_bf16 v[106:109], v[190:193], v[198:201], v[106:109]
	v_mfma_f32_16x16x32_bf16 v[98:101], v[166:169], v[206:209], v[98:101]
	v_mfma_f32_16x16x32_bf16 v[90:93], v[190:193], v[206:209], v[90:93]
	v_mfma_f32_16x16x32_bf16 v[82:85], v[166:169], v[222:225], v[82:85]
	v_mfma_f32_16x16x32_bf16 v[74:77], v[190:193], v[222:225], v[74:77]
	v_mfma_f32_16x16x32_bf16 v[70:73], v[166:169], v[230:233], v[70:73]
	v_mfma_f32_16x16x32_bf16 v[66:69], v[190:193], v[230:233], v[66:69]
	s_barrier
	s_add_i32 s20, s8, 0x18000
	s_add_u32 s80, s76, 0x80
	s_addc_u32 s81, s77, 0
	s_mov_b32 m0, s20
	s_nop 0
	global_load_lds_dwordx4 v148, s[80:81]
	s_add_i32 m0, s20, 0x2000
	s_add_u32 s20, s76, 0x40080
	s_addc_u32 s21, s77, 0
	s_add_i32 s12, s8, 0x1c000
	global_load_lds_dwordx4 v152, s[80:81]
	s_mov_b32 m0, s12
	s_nop 0
	global_load_lds_dwordx4 v148, s[20:21]
	s_add_i32 m0, s12, 0x2000
	s_nop 0
	global_load_lds_dwordx4 v152, s[20:21]
	s_mov_b32 m0, s31
	s_nop 0
	global_load_lds_dwordx4 v146, s[100:101]
	s_mov_b32 m0, s34
	s_nop 0
	global_load_lds_dwordx4 v150, s[100:101]
	ds_read_b128 v[194:197], v160 offset:49152
	ds_read_b128 v[198:201], v160 offset:50176
	ds_read_b128 v[202:205], v160 offset:51200
	ds_read_b128 v[206:209], v160 offset:52224
	ds_read_b128 v[218:221], v160 offset:53248
	ds_read_b128 v[222:225], v160 offset:54272
	ds_read_b128 v[226:229], v160 offset:55296
	ds_read_b128 v[230:233], v160 offset:56320
	s_waitcnt vmcnt(8)
	s_waitcnt lgkmcnt(0)
	s_barrier
	s_waitcnt lgkmcnt(0)
	v_mfma_f32_16x16x32_bf16 v[62:65], v[130:133], v[194:197], v[62:65]
	v_mfma_f32_16x16x32_bf16 v[58:61], v[138:141], v[194:197], v[58:61]
	v_mfma_f32_16x16x32_bf16 v[54:57], v[130:133], v[202:205], v[54:57]
	v_mfma_f32_16x16x32_bf16 v[46:49], v[138:141], v[202:205], v[46:49]
	v_mfma_f32_16x16x32_bf16 v[38:41], v[130:133], v[218:221], v[38:41]
	v_mfma_f32_16x16x32_bf16 v[30:33], v[138:141], v[218:221], v[30:33]
	v_mfma_f32_16x16x32_bf16 v[22:25], v[130:133], v[226:229], v[22:25]
	v_mfma_f32_16x16x32_bf16 v[14:17], v[138:141], v[226:229], v[14:17]
	v_mfma_f32_16x16x32_bf16 v[62:65], v[134:137], v[198:201], v[62:65]
	v_mfma_f32_16x16x32_bf16 v[58:61], v[142:145], v[198:201], v[58:61]
	v_mfma_f32_16x16x32_bf16 v[54:57], v[134:137], v[206:209], v[54:57]
	v_mfma_f32_16x16x32_bf16 v[46:49], v[142:145], v[206:209], v[46:49]
	v_mfma_f32_16x16x32_bf16 v[38:41], v[134:137], v[222:225], v[38:41]
	v_mfma_f32_16x16x32_bf16 v[30:33], v[142:145], v[222:225], v[30:33]
	v_mfma_f32_16x16x32_bf16 v[22:25], v[134:137], v[230:233], v[22:25]
	v_mfma_f32_16x16x32_bf16 v[14:17], v[142:145], v[230:233], v[14:17]
	v_mfma_f32_16x16x32_bf16 v[50:53], v[162:165], v[194:197], v[50:53]
	v_mfma_f32_16x16x32_bf16 v[42:45], v[170:173], v[194:197], v[42:45]
	v_mfma_f32_16x16x32_bf16 v[34:37], v[162:165], v[202:205], v[34:37]
	v_mfma_f32_16x16x32_bf16 v[26:29], v[170:173], v[202:205], v[26:29]
	v_mfma_f32_16x16x32_bf16 v[18:21], v[162:165], v[218:221], v[18:21]
	v_mfma_f32_16x16x32_bf16 v[10:13], v[170:173], v[218:221], v[10:13]
	v_mfma_f32_16x16x32_bf16 v[6:9], v[162:165], v[226:229], v[6:9]
	v_mfma_f32_16x16x32_bf16 v[2:5], v[170:173], v[226:229], v[2:5]
	v_mfma_f32_16x16x32_bf16 v[50:53], v[166:169], v[198:201], v[50:53]
	v_mfma_f32_16x16x32_bf16 v[42:45], v[190:193], v[198:201], v[42:45]
	v_mfma_f32_16x16x32_bf16 v[34:37], v[166:169], v[206:209], v[34:37]
	v_mfma_f32_16x16x32_bf16 v[26:29], v[190:193], v[206:209], v[26:29]
	v_mfma_f32_16x16x32_bf16 v[18:21], v[166:169], v[222:225], v[18:21]
	v_mfma_f32_16x16x32_bf16 v[10:13], v[190:193], v[222:225], v[10:13]
	v_mfma_f32_16x16x32_bf16 v[6:9], v[166:169], v[230:233], v[6:9]
	v_mfma_f32_16x16x32_bf16 v[2:5], v[190:193], v[230:233], v[2:5]
	s_barrier
	s_add_i32 s78, s78, 2
	s_add_u32 s18, s18, 0x100
	s_addc_u32 s19, s19, 0
	s_add_u32 s69, s69, 0x100
	s_addc_u32 s71, s71, 0
	s_cmp_gt_u32 s78, 13
	s_cbranch_scc0 .LBB0_378
	s_and_b64 vcc, exec, s[36:37]
	s_cbranch_vccz .LBB0_381
	s_barrier

; #define PG8_STAGE(bufoff, gbase, voff) do { _Pragma("unroll") for (int _i = 0; _i < 2; ++_i) \
;         __builtin_amdgcn_global_load_lds((const unsigned*)((const char*)(gbase) + (voff)[_i]), (LAS unsigned*)(lds + (bufoff) + ldsw + _i * 8192), 16, 0, 0); } while (0)
; #define PG8_LDA(dst, b, h) do { _Pragma("unroll") for (int m = 0; m < 4; ++m) _Pragma("unroll") for (int k = 0; k < 2; ++k) dst[m][k] = *(const LAS bf16x8*)(lds + PG8_SA(b, h) + aoff + m * 2048 + k * 1024); } while (0)
; #define PG8_LDB(dst, b, h) do { _Pragma("unroll") for (int n = 0; n < 2; ++n) _Pragma("unroll") for (int k = 0; k < 2; ++k) dst[n][k] = *(const LAS bf16x8*)(lds + PG8_SB(b, h) + boff + n * 2048 + k * 1024); } while (0)
; #define PG8_MMA(ai, bj, At, Bt) do { __builtin_amdgcn_s_setprio(1); _Pragma("unroll") for (int m = 0; m < 4; ++m) _Pragma("unroll") for (int n = 0; n < 2; ++n) _Pragma("unroll") for (int k = 0; k < 2; ++k) \
;         acc[ai][bj][m][n] = __builtin_amdgcn_mfma_f32_16x16x32_bf16(Bt[n][k], At[m][k], acc[ai][bj][m][n], 0, 0, 0); __builtin_amdgcn_s_setprio(0); } while (0)
; #define PG8_WAIT_V(n) asm volatile("s_waitcnt vmcnt(" #n ")" ::: "memory")
; #define PG8_WAIT_L(n) asm volatile("s_waitcnt lgkmcnt(" #n ")" ::: "memory")
; #define PG8_BAR __builtin_amdgcn_s_barrier()
; #define PG8_SCHED __builtin_amdgcn_sched_barrier(0)
; template <class Epi, class Sched>
; __device__ __forceinline__ void gemm_phase(LAS unsigned char* lds, const Gemm g, const Sched& S, const Epi& E) {
;     ...
;             const bool last = (t == nt - 2);
;             const char* a1 = cA + (size_t)(t + 1) * kstep;
;             const char* a2 = last ? nA : cA + (size_t)(t + 2) * kstep; const char* b2 = last ? nB : cB + (size_t)(t + 2) * kstep;
;             const char* a3 = a2 + kstep; const char* b3 = b2 + kstep;
;             PG8_LDB(B0, 0, 0); PG8_LDB(B1, 0, 1); PG8_SCHED; PG8_LDA(At, 0, 0); PG8_STAGE(PG8_SA(1, 1), a1 + hstepA, voffA);
;             PG8_WAIT_V(8); PG8_WAIT_L(0); PG8_BAR; PG8_MMA(0, 0, At, B0); PG8_MMA(0, 1, At, B1); PG8_BAR; PG8_SCHED;
;             PG8_LDA(At, 0, 1); PG8_STAGE(PG8_SB(0, 0), b2, voffB); PG8_STAGE(PG8_SB(0, 1), b2 + hstepB, voffB); PG8_STAGE(PG8_SA(0, 0), a2, voffA);
;             PG8_WAIT_V(8); PG8_WAIT_L(0); PG8_BAR; PG8_MMA(1, 0, At, B0); PG8_MMA(1, 1, At, B1); PG8_BAR; PG8_SCHED;
.LBB0_598:
	s_add_i32 vcc_lo, s20, 2
	s_add_u32 s90, s18, 0x80
	s_addc_u32 s21, s19, 0
	s_add_i32 s92, 0, 0x10000
	s_cmp_eq_u32 s43, s20
	s_cselect_b32 s21, s37, s21
	s_cselect_b32 s20, s36, s90
	s_cselect_b32 s91, s71, s87
	s_cselect_b32 s90, s70, s86
	s_add_i32 s93, 0, 0x14000
	s_add_i32 m0, s35, 0xc000
	s_nop 0
	global_load_lds_dwordx4 v138, s[18:19]
	s_add_i32 m0, s35, 0xe000
	s_nop 0
	global_load_lds_dwordx4 v140, s[18:19]
	ds_read_b128 v[142:145], v255
	ds_read_b128 v[150:153], v255 offset:1024
	ds_read_b128 v[154:157], v255 offset:2048
	ds_read_b128 v[158:161], v255 offset:3072
	ds_read_b128 v[162:165], v255 offset:16384
	ds_read_b128 v[166:169], v255 offset:17408
	ds_read_b128 v[170:173], v255 offset:18432
	ds_read_b128 v[190:193], v255 offset:19456
	ds_read_b128 v[194:197], v148
	ds_read_b128 v[198:201], v148 offset:1024
	ds_read_b128 v[202:205], v148 offset:2048
	ds_read_b128 v[206:209], v148 offset:3072
	ds_read_b128 v[218:221], v148 offset:4096
	ds_read_b128 v[222:225], v148 offset:5120
	ds_read_b128 v[226:229], v148 offset:6144
	ds_read_b128 v[230:233], v148 offset:7168
	s_waitcnt vmcnt(8)
	s_waitcnt lgkmcnt(0)
	s_barrier
	s_waitcnt lgkmcnt(0)
	v_mfma_f32_16x16x32_bf16 v[114:117], v[142:145], v[194:197], v[114:117]
	v_mfma_f32_16x16x32_bf16 v[118:121], v[154:157], v[194:197], v[118:121]
	v_mfma_f32_16x16x32_bf16 v[94:97], v[142:145], v[202:205], v[94:97]
	v_mfma_f32_16x16x32_bf16 v[98:101], v[154:157], v[202:205], v[98:101]
	v_mfma_f32_16x16x32_bf16 v[62:65], v[142:145], v[218:221], v[62:65]
	v_mfma_f32_16x16x32_bf16 v[66:69], v[154:157], v[218:221], v[66:69]
	v_mfma_f32_16x16x32_bf16 v[22:25], v[142:145], v[226:229], v[22:25]
	v_mfma_f32_16x16x32_bf16 v[34:37], v[154:157], v[226:229], v[34:37]
	v_mfma_f32_16x16x32_bf16 v[114:117], v[150:153], v[198:201], v[114:117]
	v_mfma_f32_16x16x32_bf16 v[118:121], v[158:161], v[198:201], v[118:121]
	v_mfma_f32_16x16x32_bf16 v[94:97], v[150:153], v[206:209], v[94:97]
	v_mfma_f32_16x16x32_bf16 v[98:101], v[158:161], v[206:209], v[98:101]
	v_mfma_f32_16x16x32_bf16 v[62:65], v[150:153], v[222:225], v[62:65]
	v_mfma_f32_16x16x32_bf16 v[66:69], v[158:161], v[222:225], v[66:69]
	v_mfma_f32_16x16x32_bf16 v[22:25], v[150:153], v[230:233], v[22:25]
	v_mfma_f32_16x16x32_bf16 v[34:37], v[158:161], v[230:233], v[34:37]
	v_mfma_f32_16x16x32_bf16 v[122:125], v[162:165], v[194:197], v[122:125]
	v_mfma_f32_16x16x32_bf16 v[126:129], v[170:173], v[194:197], v[126:129]
	v_mfma_f32_16x16x32_bf16 v[102:105], v[162:165], v[202:205], v[102:105]
	v_mfma_f32_16x16x32_bf16 v[106:109], v[170:173], v[202:205], v[106:109]
	v_mfma_f32_16x16x32_bf16 v[70:73], v[162:165], v[218:221], v[70:73]
	v_mfma_f32_16x16x32_bf16 v[78:81], v[170:173], v[218:221], v[78:81]
	v_mfma_f32_16x16x32_bf16 v[38:41], v[162:165], v[226:229], v[38:41]
	v_mfma_f32_16x16x32_bf16 v[46:49], v[170:173], v[226:229], v[46:49]
	v_mfma_f32_16x16x32_bf16 v[122:125], v[166:169], v[198:201], v[122:125]
	v_mfma_f32_16x16x32_bf16 v[126:129], v[190:193], v[198:201], v[126:129]
	v_mfma_f32_16x16x32_bf16 v[102:105], v[166:169], v[206:209], v[102:105]
	v_mfma_f32_16x16x32_bf16 v[106:109], v[190:193], v[206:209], v[106:109]
	v_mfma_f32_16x16x32_bf16 v[70:73], v[166:169], v[222:225], v[70:73]
	v_mfma_f32_16x16x32_bf16 v[78:81], v[190:193], v[222:225], v[78:81]
	v_mfma_f32_16x16x32_bf16 v[38:41], v[166:169], v[230:233], v[38:41]
	v_mfma_f32_16x16x32_bf16 v[46:49], v[190:193], v[230:233], v[46:49]
	s_barrier
	s_add_i32 s92, s92, s34
	s_add_u32 s98, s90, 0x80
	s_addc_u32 s99, s91, 0
	s_add_u32 s100, s20, 0x80
	s_addc_u32 s101, s21, 0
	s_mov_b32 m0, s92
	s_nop 0
	global_load_lds_dwordx4 v132, s[90:91]
	s_add_i32 m0, s92, 0x2000
	s_add_i32 s92, s93, s34
	global_load_lds_dwordx4 v136, s[90:91]
	s_add_u32 s90, s90, s29
	s_addc_u32 s91, s91, 0
	s_mov_b32 m0, s92
	s_nop 0
	global_load_lds_dwordx4 v132, s[90:91]
	s_add_i32 m0, s92, 0x2000
	s_nop 0
	global_load_lds_dwordx4 v136, s[90:91]
	s_mov_b32 m0, s35
	s_nop 0
	global_load_lds_dwordx4 v130, s[20:21]
	s_mov_b32 m0, s8
	s_nop 0
	global_load_lds_dwordx4 v134, s[20:21]
	ds_read_b128 v[194:197], v148 offset:16384
	ds_read_b128 v[198:201], v148 offset:17408
	ds_read_b128 v[202:205], v148 offset:18432
	ds_read_b128 v[206:209], v148 offset:19456
	ds_read_b128 v[218:221], v148 offset:20480
	ds_read_b128 v[222:225], v148 offset:21504
	ds_read_b128 v[226:229], v148 offset:22528
	ds_read_b128 v[230:233], v148 offset:23552
	s_waitcnt vmcnt(8)
	s_waitcnt lgkmcnt(0)
	s_barrier
	s_waitcnt lgkmcnt(0)
	v_mfma_f32_16x16x32_bf16 v[14:17], v[142:145], v[194:197], v[14:17]
	v_mfma_f32_16x16x32_bf16 v[26:29], v[154:157], v[194:197], v[26:29]
	v_mfma_f32_16x16x32_bf16 v[74:77], v[142:145], v[202:205], v[74:77]
	v_mfma_f32_16x16x32_bf16 v[82:85], v[154:157], v[202:205], v[82:85]
	v_mfma_f32_16x16x32_bf16 v[42:45], v[142:145], v[218:221], v[42:45]
	v_mfma_f32_16x16x32_bf16 v[50:53], v[154:157], v[218:221], v[50:53]
	v_mfma_f32_16x16x32_bf16 v[2:5], v[142:145], v[226:229], v[2:5]
	v_mfma_f32_16x16x32_bf16 v[6:9], v[154:157], v[226:229], v[6:9]
	v_mfma_f32_16x16x32_bf16 v[14:17], v[150:153], v[198:201], v[14:17]
	v_mfma_f32_16x16x32_bf16 v[26:29], v[158:161], v[198:201], v[26:29]
	v_mfma_f32_16x16x32_bf16 v[74:77], v[150:153], v[206:209], v[74:77]
	v_mfma_f32_16x16x32_bf16 v[82:85], v[158:161], v[206:209], v[82:85]
	v_mfma_f32_16x16x32_bf16 v[42:45], v[150:153], v[222:225], v[42:45]
	v_mfma_f32_16x16x32_bf16 v[50:53], v[158:161], v[222:225], v[50:53]
	v_mfma_f32_16x16x32_bf16 v[2:5], v[150:153], v[230:233], v[2:5]
	v_mfma_f32_16x16x32_bf16 v[6:9], v[158:161], v[230:233], v[6:9]
	v_mfma_f32_16x16x32_bf16 v[30:33], v[162:165], v[194:197], v[30:33]
	v_mfma_f32_16x16x32_bf16 v[110:113], v[170:173], v[194:197], v[110:113]
	v_mfma_f32_16x16x32_bf16 v[86:89], v[162:165], v[202:205], v[86:89]
	v_mfma_f32_16x16x32_bf16 v[90:93], v[170:173], v[202:205], v[90:93]
	v_mfma_f32_16x16x32_bf16 v[54:57], v[162:165], v[218:221], v[54:57]
	v_mfma_f32_16x16x32_bf16 v[58:61], v[170:173], v[218:221], v[58:61]
	v_mfma_f32_16x16x32_bf16 v[10:13], v[162:165], v[226:229], v[10:13]
	v_mfma_f32_16x16x32_bf16 v[18:21], v[170:173], v[226:229], v[18:21]
	v_mfma_f32_16x16x32_bf16 v[30:33], v[166:169], v[198:201], v[30:33]
	v_mfma_f32_16x16x32_bf16 v[110:113], v[190:193], v[198:201], v[110:113]
	v_mfma_f32_16x16x32_bf16 v[86:89], v[166:169], v[206:209], v[86:89]
	v_mfma_f32_16x16x32_bf16 v[90:93], v[190:193], v[206:209], v[90:93]
	v_mfma_f32_16x16x32_bf16 v[54:57], v[166:169], v[222:225], v[54:57]
	v_mfma_f32_16x16x32_bf16 v[58:61], v[190:193], v[222:225], v[58:61]
	v_mfma_f32_16x16x32_bf16 v[10:13], v[166:169], v[230:233], v[10:13]
	v_mfma_f32_16x16x32_bf16 v[18:21], v[190:193], v[230:233], v[18:21]
	s_barrier
; #define PG8_STAGE(bufoff, gbase, voff) do { _Pragma("unroll") for (int _i = 0; _i < 2; ++_i) \
;         __builtin_amdgcn_global_load_lds((const unsigned*)((const char*)(gbase) + (voff)[_i]), (LAS unsigned*)(lds + (bufoff) + ldsw + _i * 8192), 16, 0, 0); } while (0)
; #define PG8_LDA(dst, b, h) do { _Pragma("unroll") for (int m = 0; m < 4; ++m) _Pragma("unroll") for (int k = 0; k < 2; ++k) dst[m][k] = *(const LAS bf16x8*)(lds + PG8_SA(b, h) + aoff + m * 2048 + k * 1024); } while (0)
; #define PG8_LDB(dst, b, h) do { _Pragma("unroll") for (int n = 0; n < 2; ++n) _Pragma("unroll") for (int k = 0; k < 2; ++k) dst[n][k] = *(const LAS bf16x8*)(lds + PG8_SB(b, h) + boff + n * 2048 + k * 1024); } while (0)
; #define PG8_MMA(ai, bj, At, Bt) do { __builtin_amdgcn_s_setprio(1); _Pragma("unroll") for (int m = 0; m < 4; ++m) _Pragma("unroll") for (int n = 0; n < 2; ++n) _Pragma("unroll") for (int k = 0; k < 2; ++k) \
;         acc[ai][bj][m][n] = __builtin_amdgcn_mfma_f32_16x16x32_bf16(Bt[n][k], At[m][k], acc[ai][bj][m][n], 0, 0, 0); __builtin_amdgcn_s_setprio(0); } while (0)
; #define PG8_WAIT_V(n) asm volatile("s_waitcnt vmcnt(" #n ")" ::: "memory")
; #define PG8_WAIT_L(n) asm volatile("s_waitcnt lgkmcnt(" #n ")" ::: "memory")
; #define PG8_BAR __builtin_amdgcn_s_barrier()
; #define PG8_SCHED __builtin_amdgcn_sched_barrier(0)
; template <class Epi, class Sched>
; __device__ __forceinline__ void gemm_phase(LAS unsigned char* lds, const Gemm g, const Sched& S, const Epi& E) {
;     ...
;             PG8_LDB(B0, 1, 0); PG8_LDB(B1, 1, 1); PG8_SCHED; PG8_LDA(At, 1, 0); PG8_STAGE(PG8_SA(0, 1), a2 + hstepA, voffA);
;             PG8_WAIT_V(8); PG8_WAIT_L(0); PG8_BAR; PG8_MMA(0, 0, At, B0); PG8_MMA(0, 1, At, B1); PG8_BAR; PG8_SCHED;
;             PG8_LDA(At, 1, 1); PG8_STAGE(PG8_SB(1, 0), b3, voffB); PG8_STAGE(PG8_SB(1, 1), b3 + hstepB, voffB); PG8_STAGE(PG8_SA(1, 0), a3, voffA);
;             PG8_WAIT_V(8); PG8_WAIT_L(0); PG8_BAR; PG8_MMA(1, 0, At, B0); PG8_MMA(1, 1, At, B1); PG8_BAR; PG8_SCHED;
;         }
;         if (wr == 0) PG8_BAR;
	s_add_u32 s20, s20, s80
	s_addc_u32 s21, s21, 0
	s_mov_b32 m0, s9
	s_nop 0
	global_load_lds_dwordx4 v130, s[20:21]
	s_mov_b32 m0, s40
	s_nop 0
	global_load_lds_dwordx4 v134, s[20:21]
	ds_read_b128 v[142:145], v255 offset:32768
	ds_read_b128 v[150:153], v255 offset:33792
	ds_read_b128 v[154:157], v255 offset:34816
	ds_read_b128 v[158:161], v255 offset:35840
	ds_read_b128 v[162:165], v255 offset:49152
	ds_read_b128 v[166:169], v255 offset:50176
	ds_read_b128 v[170:173], v255 offset:51200
	ds_read_b128 v[190:193], v255 offset:52224
	ds_read_b128 v[194:197], v148 offset:32768
	ds_read_b128 v[198:201], v148 offset:33792
	ds_read_b128 v[202:205], v148 offset:34816
	ds_read_b128 v[206:209], v148 offset:35840
	ds_read_b128 v[218:221], v148 offset:36864
	ds_read_b128 v[222:225], v148 offset:37888
	ds_read_b128 v[226:229], v148 offset:38912
	ds_read_b128 v[230:233], v148 offset:39936
	s_waitcnt vmcnt(8)
	s_waitcnt lgkmcnt(0)
	s_barrier
	s_waitcnt lgkmcnt(0)
	v_mfma_f32_16x16x32_bf16 v[114:117], v[142:145], v[194:197], v[114:117]
	v_mfma_f32_16x16x32_bf16 v[118:121], v[154:157], v[194:197], v[118:121]
	v_mfma_f32_16x16x32_bf16 v[94:97], v[142:145], v[202:205], v[94:97]
	v_mfma_f32_16x16x32_bf16 v[98:101], v[154:157], v[202:205], v[98:101]
	v_mfma_f32_16x16x32_bf16 v[62:65], v[142:145], v[218:221], v[62:65]
	v_mfma_f32_16x16x32_bf16 v[66:69], v[154:157], v[218:221], v[66:69]
	v_mfma_f32_16x16x32_bf16 v[22:25], v[142:145], v[226:229], v[22:25]
	v_mfma_f32_16x16x32_bf16 v[34:37], v[154:157], v[226:229], v[34:37]
	v_mfma_f32_16x16x32_bf16 v[114:117], v[150:153], v[198:201], v[114:117]
	v_mfma_f32_16x16x32_bf16 v[118:121], v[158:161], v[198:201], v[118:121]
	v_mfma_f32_16x16x32_bf16 v[94:97], v[150:153], v[206:209], v[94:97]
	v_mfma_f32_16x16x32_bf16 v[98:101], v[158:161], v[206:209], v[98:101]
	v_mfma_f32_16x16x32_bf16 v[62:65], v[150:153], v[222:225], v[62:65]
	v_mfma_f32_16x16x32_bf16 v[66:69], v[158:161], v[222:225], v[66:69]
	v_mfma_f32_16x16x32_bf16 v[22:25], v[150:153], v[230:233], v[22:25]
	v_mfma_f32_16x16x32_bf16 v[34:37], v[158:161], v[230:233], v[34:37]
	v_mfma_f32_16x16x32_bf16 v[122:125], v[162:165], v[194:197], v[122:125]
	v_mfma_f32_16x16x32_bf16 v[126:129], v[170:173], v[194:197], v[126:129]
	v_mfma_f32_16x16x32_bf16 v[102:105], v[162:165], v[202:205], v[102:105]
	v_mfma_f32_16x16x32_bf16 v[106:109], v[170:173], v[202:205], v[106:109]
	v_mfma_f32_16x16x32_bf16 v[70:73], v[162:165], v[218:221], v[70:73]
	v_mfma_f32_16x16x32_bf16 v[78:81], v[170:173], v[218:221], v[78:81]
	v_mfma_f32_16x16x32_bf16 v[38:41], v[162:165], v[226:229], v[38:41]
	v_mfma_f32_16x16x32_bf16 v[46:49], v[170:173], v[226:229], v[46:49]
	v_mfma_f32_16x16x32_bf16 v[122:125], v[166:169], v[198:201], v[122:125]
	v_mfma_f32_16x16x32_bf16 v[126:129], v[190:193], v[198:201], v[126:129]
	v_mfma_f32_16x16x32_bf16 v[102:105], v[166:169], v[206:209], v[102:105]
	v_mfma_f32_16x16x32_bf16 v[106:109], v[190:193], v[206:209], v[106:109]
	v_mfma_f32_16x16x32_bf16 v[70:73], v[166:169], v[222:225], v[70:73]
	v_mfma_f32_16x16x32_bf16 v[78:81], v[190:193], v[222:225], v[78:81]
	v_mfma_f32_16x16x32_bf16 v[38:41], v[166:169], v[230:233], v[38:41]
	v_mfma_f32_16x16x32_bf16 v[46:49], v[190:193], v[230:233], v[46:49]
	s_barrier
	s_add_i32 s20, s34, 0x18000
	s_mov_b32 m0, s20
	s_nop 0
	global_load_lds_dwordx4 v132, s[98:99]
	s_add_i32 m0, s20, 0x2000
	s_add_i32 s20, s34, 0x1c000
	global_load_lds_dwordx4 v136, s[98:99]
	s_add_u32 s98, s98, s29
	s_addc_u32 s99, s99, 0
	s_mov_b32 m0, s20
	s_nop 0
	global_load_lds_dwordx4 v132, s[98:99]
	s_add_i32 m0, s20, 0x2000
	s_nop 0
	global_load_lds_dwordx4 v136, s[98:99]
	s_mov_b32 m0, s41
	s_nop 0
	global_load_lds_dwordx4 v130, s[100:101]
	s_mov_b32 m0, s42
	s_nop 0
	global_load_lds_dwordx4 v134, s[100:101]
	ds_read_b128 v[194:197], v148 offset:49152
	ds_read_b128 v[198:201], v148 offset:50176
	ds_read_b128 v[202:205], v148 offset:51200
	ds_read_b128 v[206:209], v148 offset:52224
	ds_read_b128 v[218:221], v148 offset:53248
	ds_read_b128 v[222:225], v148 offset:54272
	ds_read_b128 v[226:229], v148 offset:55296
	ds_read_b128 v[230:233], v148 offset:56320
	s_waitcnt vmcnt(8)
	s_waitcnt lgkmcnt(0)
	s_barrier
	s_waitcnt lgkmcnt(0)
	v_mfma_f32_16x16x32_bf16 v[14:17], v[142:145], v[194:197], v[14:17]
	v_mfma_f32_16x16x32_bf16 v[26:29], v[154:157], v[194:197], v[26:29]
	v_mfma_f32_16x16x32_bf16 v[74:77], v[142:145], v[202:205], v[74:77]
	v_mfma_f32_16x16x32_bf16 v[82:85], v[154:157], v[202:205], v[82:85]
	v_mfma_f32_16x16x32_bf16 v[42:45], v[142:145], v[218:221], v[42:45]
	v_mfma_f32_16x16x32_bf16 v[50:53], v[154:157], v[218:221], v[50:53]
	v_mfma_f32_16x16x32_bf16 v[2:5], v[142:145], v[226:229], v[2:5]
	v_mfma_f32_16x16x32_bf16 v[6:9], v[154:157], v[226:229], v[6:9]
	v_mfma_f32_16x16x32_bf16 v[14:17], v[150:153], v[198:201], v[14:17]
	v_mfma_f32_16x16x32_bf16 v[26:29], v[158:161], v[198:201], v[26:29]
	v_mfma_f32_16x16x32_bf16 v[74:77], v[150:153], v[206:209], v[74:77]
	v_mfma_f32_16x16x32_bf16 v[82:85], v[158:161], v[206:209], v[82:85]
	v_mfma_f32_16x16x32_bf16 v[42:45], v[150:153], v[222:225], v[42:45]
	v_mfma_f32_16x16x32_bf16 v[50:53], v[158:161], v[222:225], v[50:53]
	v_mfma_f32_16x16x32_bf16 v[2:5], v[150:153], v[230:233], v[2:5]
	v_mfma_f32_16x16x32_bf16 v[6:9], v[158:161], v[230:233], v[6:9]
	v_mfma_f32_16x16x32_bf16 v[30:33], v[162:165], v[194:197], v[30:33]
	v_mfma_f32_16x16x32_bf16 v[110:113], v[170:173], v[194:197], v[110:113]
	v_mfma_f32_16x16x32_bf16 v[86:89], v[162:165], v[202:205], v[86:89]
	v_mfma_f32_16x16x32_bf16 v[90:93], v[170:173], v[202:205], v[90:93]
	v_mfma_f32_16x16x32_bf16 v[54:57], v[162:165], v[218:221], v[54:57]
	v_mfma_f32_16x16x32_bf16 v[58:61], v[170:173], v[218:221], v[58:61]
	v_mfma_f32_16x16x32_bf16 v[10:13], v[162:165], v[226:229], v[10:13]
	v_mfma_f32_16x16x32_bf16 v[18:21], v[170:173], v[226:229], v[18:21]
	v_mfma_f32_16x16x32_bf16 v[30:33], v[166:169], v[198:201], v[30:33]
	v_mfma_f32_16x16x32_bf16 v[110:113], v[190:193], v[198:201], v[110:113]
	v_mfma_f32_16x16x32_bf16 v[86:89], v[166:169], v[206:209], v[86:89]
	v_mfma_f32_16x16x32_bf16 v[90:93], v[190:193], v[206:209], v[90:93]
	v_mfma_f32_16x16x32_bf16 v[54:57], v[166:169], v[222:225], v[54:57]
	v_mfma_f32_16x16x32_bf16 v[58:61], v[190:193], v[222:225], v[58:61]
	v_mfma_f32_16x16x32_bf16 v[10:13], v[166:169], v[230:233], v[10:13]
	v_mfma_f32_16x16x32_bf16 v[18:21], v[190:193], v[230:233], v[18:21]
	s_barrier
	s_add_u32 s18, s18, 0x100
	s_addc_u32 s19, s19, 0
	s_add_u32 s86, s86, 0x100
	s_addc_u32 s87, s87, 0
	s_cmp_ge_u32 vcc_lo, s48
	s_mov_b32 s20, vcc_lo
	s_cbranch_scc0 .LBB0_598
	s_and_b64 vcc, exec, s[84:85]
	s_cbranch_vccz .LBB0_601
	s_barrier

; #define PG8_STAGE(bufoff, gbase, voff) do { _Pragma("unroll") for (int _i = 0; _i < 2; ++_i) \
;         __builtin_amdgcn_global_load_lds((const unsigned*)((const char*)(gbase) + (voff)[_i]), (LAS unsigned*)(lds + (bufoff) + ldsw + _i * 8192), 16, 0, 0); } while (0)
; #define PG8_LDA(dst, b, h) do { _Pragma("unroll") for (int m = 0; m < 4; ++m) _Pragma("unroll") for (int k = 0; k < 2; ++k) dst[m][k] = *(const LAS bf16x8*)(lds + PG8_SA(b, h) + aoff + m * 2048 + k * 1024); } while (0)
; #define PG8_LDB(dst, b, h) do { _Pragma("unroll") for (int n = 0; n < 2; ++n) _Pragma("unroll") for (int k = 0; k < 2; ++k) dst[n][k] = *(const LAS bf16x8*)(lds + PG8_SB(b, h) + boff + n * 2048 + k * 1024); } while (0)
; #define PG8_MMA(ai, bj, At, Bt) do { __builtin_amdgcn_s_setprio(1); _Pragma("unroll") for (int m = 0; m < 4; ++m) _Pragma("unroll") for (int n = 0; n < 2; ++n) _Pragma("unroll") for (int k = 0; k < 2; ++k) \
;         acc[ai][bj][m][n] = __builtin_amdgcn_mfma_f32_16x16x32_bf16(Bt[n][k], At[m][k], acc[ai][bj][m][n], 0, 0, 0); __builtin_amdgcn_s_setprio(0); } while (0)
; #define PG8_WAIT_V(n) asm volatile("s_waitcnt vmcnt(" #n ")" ::: "memory")
; #define PG8_WAIT_L(n) asm volatile("s_waitcnt lgkmcnt(" #n ")" ::: "memory")
; #define PG8_BAR __builtin_amdgcn_s_barrier()
; #define PG8_SCHED __builtin_amdgcn_sched_barrier(0)
; template <class Epi, class Sched>
; __device__ __forceinline__ void gemm_phase(LAS unsigned char* lds, const Gemm g, const Sched& S, const Epi& E) {
;     ...
;         for (int t = 0; t < nt; t += 2) {
;             const bool last = (t == nt - 2);
;             const char* a1 = cA + (size_t)(t + 1) * kstep;
;             const char* a2 = last ? nA : cA + (size_t)(t + 2) * kstep; const char* b2 = last ? nB : cB + (size_t)(t + 2) * kstep;
;             const char* a3 = a2 + kstep; const char* b3 = b2 + kstep;
;             PG8_LDB(B0, 0, 0); PG8_LDB(B1, 0, 1); PG8_SCHED; PG8_LDA(At, 0, 0); PG8_STAGE(PG8_SA(1, 1), a1 + hstepA, voffA);
;             PG8_WAIT_V(8); PG8_WAIT_L(0); PG8_BAR; PG8_MMA(0, 0, At, B0); PG8_MMA(0, 1, At, B1); PG8_BAR; PG8_SCHED;
;             PG8_LDA(At, 0, 1); PG8_STAGE(PG8_SB(0, 0), b2, voffB); PG8_STAGE(PG8_SB(0, 1), b2 + hstepB, voffB); PG8_STAGE(PG8_SA(0, 0), a2, voffA);
;             PG8_WAIT_V(8); PG8_WAIT_L(0); PG8_BAR; PG8_MMA(1, 0, At, B0); PG8_MMA(1, 1, At, B1); PG8_BAR; PG8_SCHED;
.LBB0_640:
	s_add_i32 s87, s20, 2
	s_add_u32 s88, s18, 0x80
	s_addc_u32 s21, s19, 0
	s_add_i32 s90, 0, 0x10000
	s_cmp_eq_u32 s43, s20
	s_cselect_b32 s21, s69, s21
	s_cselect_b32 s20, s68, s88
	s_cselect_b32 s89, s81, s83
	s_cselect_b32 s88, s80, s82
	s_add_i32 s91, 0, 0x14000
	s_add_i32 m0, s30, 0xc000
	s_nop 0
	global_load_lds_dwordx4 v138, s[18:19]
	s_add_i32 m0, s30, 0xe000
	s_nop 0
	global_load_lds_dwordx4 v140, s[18:19]
	ds_read_b128 v[146:149], v255
	ds_read_b128 v[150:153], v255 offset:1024
	ds_read_b128 v[154:157], v255 offset:2048
	ds_read_b128 v[158:161], v255 offset:3072
	ds_read_b128 v[162:165], v255 offset:16384
	ds_read_b128 v[166:169], v255 offset:17408
	ds_read_b128 v[170:173], v255 offset:18432
	ds_read_b128 v[190:193], v255 offset:19456
	ds_read_b128 v[194:197], v144
	ds_read_b128 v[198:201], v144 offset:1024
	ds_read_b128 v[202:205], v144 offset:2048
	ds_read_b128 v[206:209], v144 offset:3072
	ds_read_b128 v[218:221], v144 offset:4096
	ds_read_b128 v[222:225], v144 offset:5120
	ds_read_b128 v[226:229], v144 offset:6144
	ds_read_b128 v[230:233], v144 offset:7168
	s_waitcnt vmcnt(8)
	s_waitcnt lgkmcnt(0)
	s_barrier
	s_waitcnt lgkmcnt(0)
	v_mfma_f32_16x16x32_bf16 v[2:5], v[146:149], v[194:197], v[2:5]
	v_mfma_f32_16x16x32_bf16 v[6:9], v[154:157], v[194:197], v[6:9]
	v_mfma_f32_16x16x32_bf16 v[10:13], v[146:149], v[202:205], v[10:13]
	v_mfma_f32_16x16x32_bf16 v[14:17], v[154:157], v[202:205], v[14:17]
	v_mfma_f32_16x16x32_bf16 v[26:29], v[146:149], v[218:221], v[26:29]
	v_mfma_f32_16x16x32_bf16 v[30:33], v[154:157], v[218:221], v[30:33]
	v_mfma_f32_16x16x32_bf16 v[42:45], v[146:149], v[226:229], v[42:45]
	v_mfma_f32_16x16x32_bf16 v[46:49], v[154:157], v[226:229], v[46:49]
	v_mfma_f32_16x16x32_bf16 v[2:5], v[150:153], v[198:201], v[2:5]
	v_mfma_f32_16x16x32_bf16 v[6:9], v[158:161], v[198:201], v[6:9]
	v_mfma_f32_16x16x32_bf16 v[10:13], v[150:153], v[206:209], v[10:13]
	v_mfma_f32_16x16x32_bf16 v[14:17], v[158:161], v[206:209], v[14:17]
	v_mfma_f32_16x16x32_bf16 v[26:29], v[150:153], v[222:225], v[26:29]
	v_mfma_f32_16x16x32_bf16 v[30:33], v[158:161], v[222:225], v[30:33]
	v_mfma_f32_16x16x32_bf16 v[42:45], v[150:153], v[230:233], v[42:45]
	v_mfma_f32_16x16x32_bf16 v[46:49], v[158:161], v[230:233], v[46:49]
	v_mfma_f32_16x16x32_bf16 v[18:21], v[162:165], v[194:197], v[18:21]
	v_mfma_f32_16x16x32_bf16 v[22:25], v[170:173], v[194:197], v[22:25]
	v_mfma_f32_16x16x32_bf16 v[34:37], v[162:165], v[202:205], v[34:37]
	v_mfma_f32_16x16x32_bf16 v[38:41], v[170:173], v[202:205], v[38:41]
	v_mfma_f32_16x16x32_bf16 v[50:53], v[162:165], v[218:221], v[50:53]
	v_mfma_f32_16x16x32_bf16 v[54:57], v[170:173], v[218:221], v[54:57]
	v_mfma_f32_16x16x32_bf16 v[58:61], v[162:165], v[226:229], v[58:61]
	v_mfma_f32_16x16x32_bf16 v[66:69], v[170:173], v[226:229], v[66:69]
	v_mfma_f32_16x16x32_bf16 v[18:21], v[166:169], v[198:201], v[18:21]
	v_mfma_f32_16x16x32_bf16 v[22:25], v[190:193], v[198:201], v[22:25]
	v_mfma_f32_16x16x32_bf16 v[34:37], v[166:169], v[206:209], v[34:37]
	v_mfma_f32_16x16x32_bf16 v[38:41], v[190:193], v[206:209], v[38:41]
	v_mfma_f32_16x16x32_bf16 v[50:53], v[166:169], v[222:225], v[50:53]
	v_mfma_f32_16x16x32_bf16 v[54:57], v[190:193], v[222:225], v[54:57]
	v_mfma_f32_16x16x32_bf16 v[58:61], v[166:169], v[230:233], v[58:61]
	v_mfma_f32_16x16x32_bf16 v[66:69], v[190:193], v[230:233], v[66:69]
	s_barrier
	s_add_i32 s90, s90, s29
	s_add_u32 s98, s88, 0x80
	s_addc_u32 s99, s89, 0
	s_add_u32 s100, s20, 0x80
	s_addc_u32 s101, s21, 0
	s_mov_b32 m0, s90
	s_nop 0
	global_load_lds_dwordx4 v132, s[88:89]
	s_add_i32 m0, s90, 0x2000
	s_add_i32 s90, s91, s29
	global_load_lds_dwordx4 v136, s[88:89]
	s_add_u32 s88, s88, s8
	s_addc_u32 s89, s89, 0
	s_mov_b32 m0, s90
	s_nop 0
	global_load_lds_dwordx4 v132, s[88:89]
	s_add_i32 m0, s90, 0x2000
	s_nop 0
	global_load_lds_dwordx4 v136, s[88:89]
	s_mov_b32 m0, s30
	s_nop 0
	global_load_lds_dwordx4 v130, s[20:21]
	s_mov_b32 m0, s31
	s_nop 0
	global_load_lds_dwordx4 v134, s[20:21]
	ds_read_b128 v[194:197], v144 offset:16384
	ds_read_b128 v[198:201], v144 offset:17408
	ds_read_b128 v[202:205], v144 offset:18432
	ds_read_b128 v[206:209], v144 offset:19456
	ds_read_b128 v[218:221], v144 offset:20480
	ds_read_b128 v[222:225], v144 offset:21504
	ds_read_b128 v[226:229], v144 offset:22528
	ds_read_b128 v[230:233], v144 offset:23552
	s_waitcnt vmcnt(8)
	s_waitcnt lgkmcnt(0)
	s_barrier
	s_waitcnt lgkmcnt(0)
	v_mfma_f32_16x16x32_bf16 v[62:65], v[146:149], v[194:197], v[62:65]
	v_mfma_f32_16x16x32_bf16 v[70:73], v[154:157], v[194:197], v[70:73]
	v_mfma_f32_16x16x32_bf16 v[78:81], v[146:149], v[202:205], v[78:81]
	v_mfma_f32_16x16x32_bf16 v[82:85], v[154:157], v[202:205], v[82:85]
	v_mfma_f32_16x16x32_bf16 v[90:93], v[146:149], v[218:221], v[90:93]
	v_mfma_f32_16x16x32_bf16 v[94:97], v[154:157], v[218:221], v[94:97]
	v_mfma_f32_16x16x32_bf16 v[106:109], v[146:149], v[226:229], v[106:109]
	v_mfma_f32_16x16x32_bf16 v[110:113], v[154:157], v[226:229], v[110:113]
	v_mfma_f32_16x16x32_bf16 v[62:65], v[150:153], v[198:201], v[62:65]
	v_mfma_f32_16x16x32_bf16 v[70:73], v[158:161], v[198:201], v[70:73]
	v_mfma_f32_16x16x32_bf16 v[78:81], v[150:153], v[206:209], v[78:81]
	v_mfma_f32_16x16x32_bf16 v[82:85], v[158:161], v[206:209], v[82:85]
	v_mfma_f32_16x16x32_bf16 v[90:93], v[150:153], v[222:225], v[90:93]
	v_mfma_f32_16x16x32_bf16 v[94:97], v[158:161], v[222:225], v[94:97]
	v_mfma_f32_16x16x32_bf16 v[106:109], v[150:153], v[230:233], v[106:109]
	v_mfma_f32_16x16x32_bf16 v[110:113], v[158:161], v[230:233], v[110:113]
	v_mfma_f32_16x16x32_bf16 v[74:77], v[162:165], v[194:197], v[74:77]
	v_mfma_f32_16x16x32_bf16 v[86:89], v[170:173], v[194:197], v[86:89]
	v_mfma_f32_16x16x32_bf16 v[98:101], v[162:165], v[202:205], v[98:101]
	v_mfma_f32_16x16x32_bf16 v[102:105], v[170:173], v[202:205], v[102:105]
	v_mfma_f32_16x16x32_bf16 v[114:117], v[162:165], v[218:221], v[114:117]
	v_mfma_f32_16x16x32_bf16 v[118:121], v[170:173], v[218:221], v[118:121]
	v_mfma_f32_16x16x32_bf16 v[122:125], v[162:165], v[226:229], v[122:125]
	v_mfma_f32_16x16x32_bf16 v[126:129], v[170:173], v[226:229], v[126:129]
	v_mfma_f32_16x16x32_bf16 v[74:77], v[166:169], v[198:201], v[74:77]
	v_mfma_f32_16x16x32_bf16 v[86:89], v[190:193], v[198:201], v[86:89]
	v_mfma_f32_16x16x32_bf16 v[98:101], v[166:169], v[206:209], v[98:101]
	v_mfma_f32_16x16x32_bf16 v[102:105], v[190:193], v[206:209], v[102:105]
	v_mfma_f32_16x16x32_bf16 v[114:117], v[166:169], v[222:225], v[114:117]
	v_mfma_f32_16x16x32_bf16 v[118:121], v[190:193], v[222:225], v[118:121]
	v_mfma_f32_16x16x32_bf16 v[122:125], v[166:169], v[230:233], v[122:125]
	v_mfma_f32_16x16x32_bf16 v[126:129], v[190:193], v[230:233], v[126:129]
	s_barrier
; #define PG8_STAGE(bufoff, gbase, voff) do { _Pragma("unroll") for (int _i = 0; _i < 2; ++_i) \
;         __builtin_amdgcn_global_load_lds((const unsigned*)((const char*)(gbase) + (voff)[_i]), (LAS unsigned*)(lds + (bufoff) + ldsw + _i * 8192), 16, 0, 0); } while (0)
; #define PG8_LDA(dst, b, h) do { _Pragma("unroll") for (int m = 0; m < 4; ++m) _Pragma("unroll") for (int k = 0; k < 2; ++k) dst[m][k] = *(const LAS bf16x8*)(lds + PG8_SA(b, h) + aoff + m * 2048 + k * 1024); } while (0)
; #define PG8_LDB(dst, b, h) do { _Pragma("unroll") for (int n = 0; n < 2; ++n) _Pragma("unroll") for (int k = 0; k < 2; ++k) dst[n][k] = *(const LAS bf16x8*)(lds + PG8_SB(b, h) + boff + n * 2048 + k * 1024); } while (0)
; #define PG8_MMA(ai, bj, At, Bt) do { __builtin_amdgcn_s_setprio(1); _Pragma("unroll") for (int m = 0; m < 4; ++m) _Pragma("unroll") for (int n = 0; n < 2; ++n) _Pragma("unroll") for (int k = 0; k < 2; ++k) \
;         acc[ai][bj][m][n] = __builtin_amdgcn_mfma_f32_16x16x32_bf16(Bt[n][k], At[m][k], acc[ai][bj][m][n], 0, 0, 0); __builtin_amdgcn_s_setprio(0); } while (0)
; #define PG8_WAIT_V(n) asm volatile("s_waitcnt vmcnt(" #n ")" ::: "memory")
; #define PG8_WAIT_L(n) asm volatile("s_waitcnt lgkmcnt(" #n ")" ::: "memory")
; #define PG8_BAR __builtin_amdgcn_s_barrier()
; #define PG8_SCHED __builtin_amdgcn_sched_barrier(0)
; template <class Epi, class Sched>
; __device__ __forceinline__ void gemm_phase(LAS unsigned char* lds, const Gemm g, const Sched& S, const Epi& E) {
;     ...
;             PG8_LDB(B0, 1, 0); PG8_LDB(B1, 1, 1); PG8_SCHED; PG8_LDA(At, 1, 0); PG8_STAGE(PG8_SA(0, 1), a2 + hstepA, voffA);
;             PG8_WAIT_V(8); PG8_WAIT_L(0); PG8_BAR; PG8_MMA(0, 0, At, B0); PG8_MMA(0, 1, At, B1); PG8_BAR; PG8_SCHED;
;             PG8_LDA(At, 1, 1); PG8_STAGE(PG8_SB(1, 0), b3, voffB); PG8_STAGE(PG8_SB(1, 1), b3 + hstepB, voffB); PG8_STAGE(PG8_SA(1, 0), a3, voffA);
;             PG8_WAIT_V(8); PG8_WAIT_L(0); PG8_BAR; PG8_MMA(1, 0, At, B0); PG8_MMA(1, 1, At, B1); PG8_BAR; PG8_SCHED;
;         }
;         if (wr == 0) PG8_BAR;
	s_add_u32 s20, s20, s54
	s_addc_u32 s21, s21, 0
	s_mov_b32 m0, s34
	s_nop 0
	global_load_lds_dwordx4 v130, s[20:21]
	s_mov_b32 m0, s35
	s_nop 0
	global_load_lds_dwordx4 v134, s[20:21]
	ds_read_b128 v[146:149], v255 offset:32768
	ds_read_b128 v[150:153], v255 offset:33792
	ds_read_b128 v[154:157], v255 offset:34816
	ds_read_b128 v[158:161], v255 offset:35840
	ds_read_b128 v[162:165], v255 offset:49152
	ds_read_b128 v[166:169], v255 offset:50176
	ds_read_b128 v[170:173], v255 offset:51200
	ds_read_b128 v[190:193], v255 offset:52224
	ds_read_b128 v[194:197], v144 offset:32768
	ds_read_b128 v[198:201], v144 offset:33792
	ds_read_b128 v[202:205], v144 offset:34816
	ds_read_b128 v[206:209], v144 offset:35840
	ds_read_b128 v[218:221], v144 offset:36864
	ds_read_b128 v[222:225], v144 offset:37888
	ds_read_b128 v[226:229], v144 offset:38912
	ds_read_b128 v[230:233], v144 offset:39936
	s_waitcnt vmcnt(8)
	s_waitcnt lgkmcnt(0)
	s_barrier
	s_waitcnt lgkmcnt(0)
	v_mfma_f32_16x16x32_bf16 v[2:5], v[146:149], v[194:197], v[2:5]
	v_mfma_f32_16x16x32_bf16 v[6:9], v[154:157], v[194:197], v[6:9]
	v_mfma_f32_16x16x32_bf16 v[10:13], v[146:149], v[202:205], v[10:13]
	v_mfma_f32_16x16x32_bf16 v[14:17], v[154:157], v[202:205], v[14:17]
	v_mfma_f32_16x16x32_bf16 v[26:29], v[146:149], v[218:221], v[26:29]
	v_mfma_f32_16x16x32_bf16 v[30:33], v[154:157], v[218:221], v[30:33]
	v_mfma_f32_16x16x32_bf16 v[42:45], v[146:149], v[226:229], v[42:45]
	v_mfma_f32_16x16x32_bf16 v[46:49], v[154:157], v[226:229], v[46:49]
	v_mfma_f32_16x16x32_bf16 v[2:5], v[150:153], v[198:201], v[2:5]
	v_mfma_f32_16x16x32_bf16 v[6:9], v[158:161], v[198:201], v[6:9]
	v_mfma_f32_16x16x32_bf16 v[10:13], v[150:153], v[206:209], v[10:13]
	v_mfma_f32_16x16x32_bf16 v[14:17], v[158:161], v[206:209], v[14:17]
	v_mfma_f32_16x16x32_bf16 v[26:29], v[150:153], v[222:225], v[26:29]
	v_mfma_f32_16x16x32_bf16 v[30:33], v[158:161], v[222:225], v[30:33]
	v_mfma_f32_16x16x32_bf16 v[42:45], v[150:153], v[230:233], v[42:45]
	v_mfma_f32_16x16x32_bf16 v[46:49], v[158:161], v[230:233], v[46:49]
	v_mfma_f32_16x16x32_bf16 v[18:21], v[162:165], v[194:197], v[18:21]
	v_mfma_f32_16x16x32_bf16 v[22:25], v[170:173], v[194:197], v[22:25]
	v_mfma_f32_16x16x32_bf16 v[34:37], v[162:165], v[202:205], v[34:37]
	v_mfma_f32_16x16x32_bf16 v[38:41], v[170:173], v[202:205], v[38:41]
	v_mfma_f32_16x16x32_bf16 v[50:53], v[162:165], v[218:221], v[50:53]
	v_mfma_f32_16x16x32_bf16 v[54:57], v[170:173], v[218:221], v[54:57]
	v_mfma_f32_16x16x32_bf16 v[58:61], v[162:165], v[226:229], v[58:61]
	v_mfma_f32_16x16x32_bf16 v[66:69], v[170:173], v[226:229], v[66:69]
	v_mfma_f32_16x16x32_bf16 v[18:21], v[166:169], v[198:201], v[18:21]
	v_mfma_f32_16x16x32_bf16 v[22:25], v[190:193], v[198:201], v[22:25]
	v_mfma_f32_16x16x32_bf16 v[34:37], v[166:169], v[206:209], v[34:37]
	v_mfma_f32_16x16x32_bf16 v[38:41], v[190:193], v[206:209], v[38:41]
	v_mfma_f32_16x16x32_bf16 v[50:53], v[166:169], v[222:225], v[50:53]
	v_mfma_f32_16x16x32_bf16 v[54:57], v[190:193], v[222:225], v[54:57]
	v_mfma_f32_16x16x32_bf16 v[58:61], v[166:169], v[230:233], v[58:61]
	v_mfma_f32_16x16x32_bf16 v[66:69], v[190:193], v[230:233], v[66:69]
	s_barrier
	s_add_i32 s20, s29, 0x18000
	s_mov_b32 m0, s20
	s_nop 0
	global_load_lds_dwordx4 v132, s[98:99]
	s_add_i32 m0, s20, 0x2000
	s_add_i32 s20, s29, 0x1c000
	global_load_lds_dwordx4 v136, s[98:99]
	s_add_u32 s98, s98, s8
	s_addc_u32 s99, s99, 0
	s_mov_b32 m0, s20
	s_nop 0
	global_load_lds_dwordx4 v132, s[98:99]
	s_add_i32 m0, s20, 0x2000
	s_nop 0
	global_load_lds_dwordx4 v136, s[98:99]
	s_mov_b32 m0, s40
	s_nop 0
	global_load_lds_dwordx4 v130, s[100:101]
	s_mov_b32 m0, s41
	s_nop 0
	global_load_lds_dwordx4 v134, s[100:101]
	ds_read_b128 v[194:197], v144 offset:49152
	ds_read_b128 v[198:201], v144 offset:50176
	ds_read_b128 v[202:205], v144 offset:51200
	ds_read_b128 v[206:209], v144 offset:52224
	ds_read_b128 v[218:221], v144 offset:53248
	ds_read_b128 v[222:225], v144 offset:54272
	ds_read_b128 v[226:229], v144 offset:55296
	ds_read_b128 v[230:233], v144 offset:56320
	s_waitcnt vmcnt(8)
	s_waitcnt lgkmcnt(0)
	s_barrier
	s_waitcnt lgkmcnt(0)
	v_mfma_f32_16x16x32_bf16 v[62:65], v[146:149], v[194:197], v[62:65]
	v_mfma_f32_16x16x32_bf16 v[70:73], v[154:157], v[194:197], v[70:73]
	v_mfma_f32_16x16x32_bf16 v[78:81], v[146:149], v[202:205], v[78:81]
	v_mfma_f32_16x16x32_bf16 v[82:85], v[154:157], v[202:205], v[82:85]
	v_mfma_f32_16x16x32_bf16 v[90:93], v[146:149], v[218:221], v[90:93]
	v_mfma_f32_16x16x32_bf16 v[94:97], v[154:157], v[218:221], v[94:97]
	v_mfma_f32_16x16x32_bf16 v[106:109], v[146:149], v[226:229], v[106:109]
	v_mfma_f32_16x16x32_bf16 v[110:113], v[154:157], v[226:229], v[110:113]
	v_mfma_f32_16x16x32_bf16 v[62:65], v[150:153], v[198:201], v[62:65]
	v_mfma_f32_16x16x32_bf16 v[70:73], v[158:161], v[198:201], v[70:73]
	v_mfma_f32_16x16x32_bf16 v[78:81], v[150:153], v[206:209], v[78:81]
	v_mfma_f32_16x16x32_bf16 v[82:85], v[158:161], v[206:209], v[82:85]
	v_mfma_f32_16x16x32_bf16 v[90:93], v[150:153], v[222:225], v[90:93]
	v_mfma_f32_16x16x32_bf16 v[94:97], v[158:161], v[222:225], v[94:97]
	v_mfma_f32_16x16x32_bf16 v[106:109], v[150:153], v[230:233], v[106:109]
	v_mfma_f32_16x16x32_bf16 v[110:113], v[158:161], v[230:233], v[110:113]
	v_mfma_f32_16x16x32_bf16 v[74:77], v[162:165], v[194:197], v[74:77]
	v_mfma_f32_16x16x32_bf16 v[86:89], v[170:173], v[194:197], v[86:89]
	v_mfma_f32_16x16x32_bf16 v[98:101], v[162:165], v[202:205], v[98:101]
	v_mfma_f32_16x16x32_bf16 v[102:105], v[170:173], v[202:205], v[102:105]
	v_mfma_f32_16x16x32_bf16 v[114:117], v[162:165], v[218:221], v[114:117]
	v_mfma_f32_16x16x32_bf16 v[118:121], v[170:173], v[218:221], v[118:121]
	v_mfma_f32_16x16x32_bf16 v[122:125], v[162:165], v[226:229], v[122:125]
	v_mfma_f32_16x16x32_bf16 v[126:129], v[170:173], v[226:229], v[126:129]
	v_mfma_f32_16x16x32_bf16 v[74:77], v[166:169], v[198:201], v[74:77]
	v_mfma_f32_16x16x32_bf16 v[86:89], v[190:193], v[198:201], v[86:89]
	v_mfma_f32_16x16x32_bf16 v[98:101], v[166:169], v[206:209], v[98:101]
	v_mfma_f32_16x16x32_bf16 v[102:105], v[190:193], v[206:209], v[102:105]
	v_mfma_f32_16x16x32_bf16 v[114:117], v[166:169], v[222:225], v[114:117]
	v_mfma_f32_16x16x32_bf16 v[118:121], v[190:193], v[222:225], v[118:121]
	v_mfma_f32_16x16x32_bf16 v[122:125], v[166:169], v[230:233], v[122:125]
	v_mfma_f32_16x16x32_bf16 v[126:129], v[190:193], v[230:233], v[126:129]
	s_barrier
	s_add_u32 s18, s18, 0x100
	s_addc_u32 s19, s19, 0
	s_add_u32 s82, s82, 0x100
	s_addc_u32 s83, s83, 0
	s_cmp_ge_u32 s87, s42
	s_mov_b32 s20, s87
	s_cbranch_scc0 .LBB0_640
	s_and_b64 vcc, exec, s[70:71]
	s_cbranch_vccz .LBB0_643
	s_barrier
